# phase-0 weight conversion: all 32 tile loads issued before the LDS writes (was 4 drained rounds of 8), 16 LDS read-backs batched with counted lgkmcnt
# speedup vs baseline: 1.0043x; 1.0043x over previous
; #define LAS __attribute__((address_space(3)))
; __device__ __forceinline__ unsigned pk2(float lo, float hi) { return pg8::cvt_pk_bf16(lo, hi); }
; __device__ __forceinline__ void gmlp_phase(KA a, LAS unsigned char* lds, int bid, int tid, int wid, int lane) {
;     const int h = bid & 7;
;     LAS bf16_t* Wl = (LAS bf16_t*)lds;
;     LAS bf16_t* Vt = (LAS bf16_t*)(lds + 128 * GW_STR * 2);
;     const bf16_t* Z = (const bf16_t*)(a->ws + WS_U); bf16_t* Y = (bf16_t*)(a->ws + WS_Y);
;     const int r = lane & 15, q = lane >> 4;
;     { const int i = tid >> 2, qd = tid & 3; const float* src = a->in[I_SPW] + ((size_t)h * 128 + i) * 128 + qd * 32;
; #pragma unroll
;       for (int k = 0; k < 4; ++k) { const f32x4 x0 = *(const f32x4*)(src + 8 * k), x1 = *(const f32x4*)(src + 8 * k + 4); const int j0 = qd * 32 + 8 * k;
;           float e[8] = {x0.x, x0.y, x0.z, x0.w, x1.x, x1.y, x1.z, x1.w};
; #pragma unroll
;           for (int t = 0; t < 8; ++t) e[t] = (j0 + t <= i) ? e[t] : 0.f;
;           u32x4 o; o.x = pk2(e[0], e[1]); o.y = pk2(e[2], e[3]); o.z = pk2(e[4], e[5]); o.w = pk2(e[6], e[7]);
;           *(LAS u32x4*)(Wl + i * GW_STR + j0) = o; } }
.LBB0_100:
	s_and_b64 vcc, exec, s[6:7]
	s_cbranch_vccz .LBB0_197
	s_cmp_gt_i32 s67, 6
	s_mov_b64 s[6:7], -1
	s_cbranch_scc0 .LBB0_144
	s_load_dwordx2 s[6:7], s[82:83], 0x50
	s_load_dwordx4 s[8:11], s[82:83], 0x58
	v_ashrrev_i32_e32 v0, 2, v184
	s_lshl_b32 s3, s2, 7
	s_and_b32 s44, s3, 0x380
	v_ashrrev_i32_e32 v1, 31, v0
	v_lshl_add_u64 v[4:5], s[44:45], 0, v[0:1]
	v_lshlrev_b32_e32 v85, 5, v184
	v_lshlrev_b64 v[4:5], 9, v[4:5]
	v_and_b32_e32 v54, 0x60, v85
	s_waitcnt lgkmcnt(0)
	v_lshl_add_u64 v[4:5], s[6:7], 0, v[4:5]
	v_lshlrev_b32_e32 v2, 2, v54
	v_lshl_add_u64 v[8:9], v[4:5], 0, v[2:3]
	global_load_dwordx4 v[4:7], v[8:9], off
	global_load_dwordx4 v[10:13], v[8:9], off offset:16
	v_cmp_le_i32_e32 vcc, v54, v0
	v_or_b32_e32 v2, 2, v54
	v_or_b32_e32 v14, 3, v54
	v_or_b32_e32 v15, 4, v54
	v_or_b32_e32 v16, 5, v54
	v_or_b32_e32 v17, 6, v54
	v_or_b32_e32 v18, 7, v54
	s_movk_i32 s13, 0x110
	v_or_b32_e32 v19, 8, v54
	v_or_b32_e32 v20, 9, v54
	v_or_b32_e32 v21, 10, v54
	v_or_b32_e32 v22, 11, v54
	v_or_b32_e32 v23, 12, v54
	v_or_b32_e32 v24, 13, v54
	v_or_b32_e32 v25, 14, v54
	v_or_b32_e32 v26, 15, v54
	s_ashr_i32 s5, s2, 3
	s_ashr_i32 s6, s2, 9
	s_ashr_i32 s7, s6, 31
	s_lshl_b32 s3, s5, 7
	v_or_b32_e32 v27, 27, v54
	s_lshl_b64 s[6:7], s[6:7], 13
	s_and_b32 s3, s3, 0x1f80
	v_or_b32_e32 v28, 28, v54
	s_or_b32 s6, s6, s3
	v_and_b32_e32 v84, 15, v184
	v_mov_b64_e32 v[52:53], s[92:93]
	v_or_b32_e32 v29, 29, v54
	v_lshl_or_b32 v90, s79, 4, v84
	v_or_b32_e32 v30, 30, v54
	v_or_b32_e32 v31, 31, v54
	v_ashrrev_i32_e32 v91, 31, v90
	s_ashr_i32 s12, s36, 7
	v_mov_b32_e32 v89, v3
	v_and_b32_e32 v115, 48, v246
	v_or_b32_e32 v118, 48, v246
	v_or_b32_e32 v116, 0x70, v246
	v_readlane_b32 s3, v255, 4
	s_mov_b32 s14, 0
	s_waitcnt vmcnt(0)
	v_cndmask_b32_e32 v4, 0, v4, vcc
	v_cmp_lt_i32_e32 vcc, v54, v0
	s_nop 1
	v_cndmask_b32_e32 v5, 0, v5, vcc
	v_cmp_le_i32_e32 vcc, v2, v0
	v_cvt_pk_bf16_f32 v4, v4, v5
	s_nop 1
	v_cndmask_b32_e32 v2, 0, v6, vcc
	v_cmp_le_i32_e32 vcc, v14, v0
	s_nop 1
	v_cndmask_b32_e32 v6, 0, v7, vcc
	v_cmp_le_i32_e32 vcc, v15, v0
	v_cvt_pk_bf16_f32 v5, v2, v6
	v_lshlrev_b32_e32 v2, 1, v54
	s_waitcnt vmcnt(0)
	v_cndmask_b32_e32 v7, 0, v10, vcc
	v_cmp_le_i32_e32 vcc, v16, v0
	s_nop 1
	v_cndmask_b32_e32 v10, 0, v11, vcc
	v_cmp_le_i32_e32 vcc, v17, v0
	v_cvt_pk_bf16_f32 v6, v7, v10
	s_nop 1
	v_cndmask_b32_e32 v11, 0, v12, vcc
	v_cmp_le_i32_e32 vcc, v18, v0
	v_mul_lo_u32 v18, v0, s13
	v_add3_u32 v55, 0, v18, v2
	v_cndmask_b32_e32 v12, 0, v13, vcc
	v_cvt_pk_bf16_f32 v7, v11, v12
	global_load_dwordx4 v[10:13], v[8:9], off offset:32
	global_load_dwordx4 v[14:17], v[8:9], off offset:48
	v_cmp_le_i32_e32 vcc, v19, v0
	ds_write_b128 v55, v[4:7]
	v_or_b32_e32 v18, 16, v54
	v_or_b32_e32 v19, 17, v54
	s_waitcnt vmcnt(1)
	v_cndmask_b32_e32 v4, 0, v10, vcc
	v_cmp_le_i32_e32 vcc, v20, v0
	v_or_b32_e32 v20, 18, v54
	s_nop 0
	v_cndmask_b32_e32 v5, 0, v11, vcc
	v_cmp_le_i32_e32 vcc, v21, v0
	v_cvt_pk_bf16_f32 v4, v4, v5
	v_or_b32_e32 v21, 19, v54
	s_nop 0
	v_cndmask_b32_e32 v6, 0, v12, vcc
	v_cmp_le_i32_e32 vcc, v22, v0
	v_or_b32_e32 v22, 20, v54
	s_nop 0
	v_cndmask_b32_e32 v7, 0, v13, vcc
	v_cmp_le_i32_e32 vcc, v23, v0
	v_cvt_pk_bf16_f32 v5, v6, v7
	v_or_b32_e32 v23, 21, v54
	s_waitcnt vmcnt(0)
	v_cndmask_b32_e32 v10, 0, v14, vcc
	v_cmp_le_i32_e32 vcc, v24, v0
	v_or_b32_e32 v24, 22, v54
	s_nop 0
	v_cndmask_b32_e32 v11, 0, v15, vcc
	v_cmp_le_i32_e32 vcc, v25, v0
	v_cvt_pk_bf16_f32 v6, v10, v11
	v_or_b32_e32 v25, 23, v54
	s_nop 0
	v_cndmask_b32_e32 v12, 0, v16, vcc
	v_cmp_le_i32_e32 vcc, v26, v0
	v_or_b32_e32 v26, 26, v54
	s_nop 0
	v_cndmask_b32_e32 v13, 0, v17, vcc
	v_cvt_pk_bf16_f32 v7, v12, v13
	global_load_dwordx4 v[10:13], v[8:9], off offset:64
	global_load_dwordx4 v[14:17], v[8:9], off offset:80
	v_cmp_le_i32_e32 vcc, v18, v0
	ds_write_b128 v55, v[4:7] offset:16
	v_or_b32_e32 v18, s44, v54
	v_lshlrev_b32_e32 v32, 2, v18
	s_waitcnt vmcnt(1)
; #define LAS __attribute__((address_space(3)))
; __device__ __forceinline__ unsigned pk2(float lo, float hi) { return pg8::cvt_pk_bf16(lo, hi); }
; __device__ __forceinline__ void gmlp_phase(KA a, LAS unsigned char* lds, int bid, int tid, int wid, int lane) {
;     ...
;     { const int i = tid >> 2, qd = tid & 3; const float* src = a->in[I_SPW] + ((size_t)h * 128 + i) * 128 + qd * 32;
; #pragma unroll
;       for (int k = 0; k < 4; ++k) { const f32x4 x0 = *(const f32x4*)(src + 8 * k), x1 = *(const f32x4*)(src + 8 * k + 4); const int j0 = qd * 32 + 8 * k;
;           float e[8] = {x0.x, x0.y, x0.z, x0.w, x1.x, x1.y, x1.z, x1.w};
; #pragma unroll
;           for (int t = 0; t < 8; ++t) e[t] = (j0 + t <= i) ? e[t] : 0.f;
;           u32x4 o; o.x = pk2(e[0], e[1]); o.y = pk2(e[2], e[3]); o.z = pk2(e[4], e[5]); o.w = pk2(e[6], e[7]);
;           *(LAS u32x4*)(Wl + i * GW_STR + j0) = o; } }
;     const int sj = tid >> 2, sqd = tid & 3;
;     const int gi_ = 16 * wid + r; const float sb = a->in[I_SPB][h * 128 + gi_];
;     float gvr[32];
; #pragma unroll
;     for (int e = 0; e < 32; ++e) gvr[e] = a->in[I_GV][h * 128 + sqd * 32 + e];
;     u32x4 raw[4]; u32x2 ur[8];
;     { const int combo = (bid >> 3); const size_t R0 = (size_t)(combo >> 6) * SEQ + (size_t)(combo & 63) * 128;
;       const bf16_t* src = Z + (R0 + sj) * INC + AW + h * 128 + sqd * 32;
; #pragma unroll
;       for (int k = 0; k < 4; ++k) raw[k] = *(const u32x4*)(src + 8 * k);
;       const bf16_t* up = Z + (R0 + gi_) * INC + h * 128 + 4 * q;
; #pragma unroll
;       for (int dt = 0; dt < 8; ++dt) ur[dt] = *(const u32x2*)(up + 16 * dt); }
	v_cndmask_b32_e32 v4, 0, v10, vcc
	v_cmp_le_i32_e32 vcc, v19, v0
	v_lshl_add_u64 v[18:19], s[6:7], 0, v[0:1]
	s_nop 0
	v_cndmask_b32_e32 v5, 0, v11, vcc
	v_cmp_le_i32_e32 vcc, v20, v0
	v_cvt_pk_bf16_f32 v4, v4, v5
	v_mov_b32_e32 v20, s8
	s_nop 0
	v_cndmask_b32_e32 v6, 0, v12, vcc
	v_cmp_le_i32_e32 vcc, v21, v0
	v_mov_b32_e32 v21, s9
	s_nop 0
	v_cndmask_b32_e32 v7, 0, v13, vcc
	v_cmp_le_i32_e32 vcc, v22, v0
	v_cvt_pk_bf16_f32 v5, v6, v7
	s_waitcnt vmcnt(0)
	s_nop 0
	v_cndmask_b32_e32 v10, 0, v14, vcc
	v_cmp_le_i32_e32 vcc, v23, v0
	v_mad_u64_u32 v[22:23], s[8:9], v18, s59, v[52:53]
	s_nop 0
	v_cndmask_b32_e32 v11, 0, v15, vcc
	v_cmp_le_i32_e32 vcc, v24, v0
	v_cvt_pk_bf16_f32 v6, v10, v11
	v_or_b32_e32 v24, 24, v54
	v_mad_i32_i24 v23, v19, s59, v23
	v_cndmask_b32_e32 v12, 0, v16, vcc
	v_cmp_le_i32_e32 vcc, v25, v0
	v_or_b32_e32 v25, 25, v54
	v_add_u32_e32 v16, s44, v90
	v_cndmask_b32_e32 v13, 0, v17, vcc
	v_cvt_pk_bf16_f32 v7, v12, v13
	global_load_dwordx4 v[12:15], v[8:9], off offset:96
	s_nop 0
	global_load_dwordx4 v[8:11], v[8:9], off offset:112
	v_cmp_le_i32_e32 vcc, v24, v0
	ds_write_b128 v55, v[4:7] offset:32
	s_lshl_b32 s44, s44, 1
	v_ashrrev_i32_e32 v17, 31, v16
	v_lshl_add_u64 v[18:19], v[22:23], 0, s[44:45]
	v_lshl_add_u64 v[16:17], v[16:17], 2, v[20:21]
	v_lshl_add_u64 v[48:49], v[18:19], 0, v[2:3]
	s_cmp_gt_i32 s12, -1
	s_cselect_b64 s[8:9], -1, 0
	v_mul_u32_u24_e32 v54, 0x110, v54
	s_waitcnt vmcnt(1)
	v_cndmask_b32_e32 v4, 0, v12, vcc
	v_cmp_le_i32_e32 vcc, v25, v0
	s_nop 1
	v_cndmask_b32_e32 v5, 0, v13, vcc
	v_cmp_le_i32_e32 vcc, v26, v0
	v_cvt_pk_bf16_f32 v56, v4, v5
	s_nop 1
	v_cndmask_b32_e32 v6, 0, v14, vcc
	v_cmp_le_i32_e32 vcc, v27, v0
	s_nop 1
	v_cndmask_b32_e32 v7, 0, v15, vcc
	v_cmp_le_i32_e32 vcc, v28, v0
	v_cvt_pk_bf16_f32 v57, v6, v7
	s_waitcnt vmcnt(0)
	s_nop 0
	v_cndmask_b32_e32 v8, 0, v8, vcc
	v_cmp_le_i32_e32 vcc, v29, v0
	s_nop 1
	v_cndmask_b32_e32 v9, 0, v9, vcc
	v_cmp_le_i32_e32 vcc, v30, v0
	v_cvt_pk_bf16_f32 v58, v8, v9
	s_nop 1
	v_cndmask_b32_e32 v10, 0, v10, vcc
	v_cmp_le_i32_e32 vcc, v31, v0
	s_nop 1
	v_cndmask_b32_e32 v11, 0, v11, vcc
	v_cvt_pk_bf16_f32 v59, v10, v11
	global_load_dword v114, v[16:17], off
	global_load_dwordx4 v[4:7], v32, s[10:11]
	global_load_dwordx4 v[8:11], v32, s[10:11] offset:16
	global_load_dwordx4 v[12:15], v32, s[10:11] offset:32
	s_nop 0
	global_load_dwordx4 v[16:19], v32, s[10:11] offset:48
	global_load_dwordx4 v[20:23], v32, s[10:11] offset:64
	global_load_dwordx4 v[24:27], v32, s[10:11] offset:80
	global_load_dwordx4 v[28:31], v32, s[10:11] offset:96
	s_nop 0
	global_load_dwordx4 v[32:35], v32, s[10:11] offset:112
	s_nop 0
	global_load_dwordx4 v[36:39], v[48:49], off offset:2096
	global_load_dwordx4 v[40:43], v[48:49], off offset:2080
	global_load_dwordx4 v[44:47], v[48:49], off offset:2064
	s_nop 0
	global_load_dwordx4 v[48:51], v[48:49], off offset:2048
	ds_write_b128 v55, v[56:59] offset:48
	v_lshl_add_u64 v[56:57], s[6:7], 0, v[90:91]
	v_lshrrev_b32_e32 v55, 4, v246
	v_mad_u64_u32 v[52:53], s[6:7], v56, s59, v[52:53]
	v_and_b32_e32 v56, 64, v232
	v_lshlrev_b32_e32 v86, 2, v55
	v_lshlrev_b32_e32 v88, 3, v55
	v_xor_b32_e32 v55, 1, v232
	v_add_u32_e32 v117, 64, v56
	v_cmp_lt_i32_e32 vcc, v55, v117
	s_add_u32 s6, s86, s44
	s_addc_u32 s7, s87, 0
	v_cndmask_b32_e32 v55, v232, v55, vcc
	v_mad_i32_i24 v53, v57, s59, v53
	v_lshlrev_b32_e32 v87, 2, v55
	v_xor_b32_e32 v55, 2, v232
	v_lshl_add_u64 v[56:57], s[6:7], 0, v[88:89]
	s_mov_b64 s[6:7], 0x13100000
	v_cmp_lt_i32_e32 vcc, v55, v117
	v_lshl_add_u64 v[92:93], v[56:57], 0, s[6:7]
	s_add_u32 s6, s92, s44
	v_lshl_add_u64 v[52:53], v[52:53], 0, s[44:45]
	v_cndmask_b32_e32 v55, v232, v55, vcc
	s_addc_u32 s7, s93, 0
	v_mul_lo_u32 v56, v90, s13
	v_lshl_add_u64 v[52:53], v[52:53], 0, v[88:89]
	v_lshlrev_b32_e32 v119, 2, v55
	v_lshl_add_u32 v55, v0, 1, 0
	v_lshl_add_u64 v[94:95], s[6:7], 0, v[88:89]
	v_add3_u32 v89, 0, v56, v115
	v_mul_u32_u24_e32 v56, 0x110, v84
	v_mul_u32_u24_e32 v57, 0x110, v118
	v_mul_u32_u24_e32 v58, 0x110, v116
	v_lshl_add_u64 v[96:97], s[6:7], 0, v[2:3]
	s_add_i32 s12, s12, 1
	v_add3_u32 v2, v58, v115, s3
	v_add3_u32 v120, v57, v115, s3
	v_add3_u32 v121, v56, v115, s3
	v_add_u32_e32 v122, v55, v54
	s_branch .LBB0_104

; __device__ __forceinline__ unsigned f2bf(float f) { unsigned u = __builtin_bit_cast(unsigned, f); return (u + 0x7fffu + ((u >> 16) & 1u)) >> 16; }
; __device__ __forceinline__ void gmlp_phase(KA a, LAS unsigned char* lds, int bid, int tid, int wid, int lane) {
;     ...
;     for (int it = 0; it < 8; ++it) {
;         const int combo = (bid >> 3) + 32 * it; const size_t R0 = (size_t)(combo >> 6) * SEQ + (size_t)(combo & 63) * 128;
;         const int combo1 = (bid >> 3) + 32 * (it < 7 ? it + 1 : it); const size_t R1 = (size_t)(combo1 >> 6) * SEQ + (size_t)(combo1 & 63) * 128;
;         __syncthreads();
;         { float v[32]; float ss = 0.f;
; #pragma unroll
;           for (int k = 0; k < 4; ++k) { v[8 * k + 0] = bflo(raw[k].x); v[8 * k + 1] = bfhi(raw[k].x); v[8 * k + 2] = bflo(raw[k].y); v[8 * k + 3] = bfhi(raw[k].y);
;               v[8 * k + 4] = bflo(raw[k].z); v[8 * k + 5] = bfhi(raw[k].z); v[8 * k + 6] = bflo(raw[k].w); v[8 * k + 7] = bfhi(raw[k].w); }
;           { const bf16_t* src = Z + (R1 + sj) * INC + AW + h * 128 + sqd * 32;
; #pragma unroll
;             for (int k = 0; k < 4; ++k) raw[k] = *(const u32x4*)(src + 8 * k); }
; #pragma unroll
;           for (int e = 0; e < 32; ++e) ss += v[e] * v[e];
;           ss += __shfl_xor(ss, 1); ss += __shfl_xor(ss, 2);
;           const float rstd = 1.0f / sqrtf(ss * (1.0f / 128.0f) + EPS);
; #pragma unroll
;           for (int e = 0; e < 32; ++e) Vt[(sqd * 32 + e) * GW_STR + sj] = (bf16_t)f2bf(v[e] * rstd * gvr[e]); }
.LBB0_104:
	global_load_dwordx2 v[98:99], v[52:53], off offset:224
	global_load_dwordx2 v[100:101], v[52:53], off offset:192
	global_load_dwordx2 v[102:103], v[52:53], off offset:160
	global_load_dwordx2 v[104:105], v[52:53], off offset:128
	global_load_dwordx2 v[106:107], v[52:53], off offset:96
	global_load_dwordx2 v[108:109], v[52:53], off offset:64
	global_load_dwordx2 v[110:111], v[52:53], off offset:32
	global_load_dwordx2 v[112:113], v[52:53], off
	s_waitcnt vmcnt(8)
	v_and_b32_e32 v53, 0xffff0000, v48
	v_lshlrev_b32_e32 v52, 16, v48
	v_lshlrev_b32_e32 v77, 16, v36
	v_and_b32_e32 v78, 0xffff0000, v36
	v_mul_f32_e32 v36, v53, v53
	v_lshlrev_b32_e32 v54, 16, v49
	v_fmac_f32_e32 v36, v52, v52
	v_and_b32_e32 v56, 0xffff0000, v49
	v_fmac_f32_e32 v36, v54, v54
	v_lshlrev_b32_e32 v57, 16, v50
	v_fmac_f32_e32 v36, v56, v56
	v_and_b32_e32 v58, 0xffff0000, v50
	v_fmac_f32_e32 v36, v57, v57
	v_lshlrev_b32_e32 v59, 16, v51
	v_fmac_f32_e32 v36, v58, v58
	v_and_b32_e32 v60, 0xffff0000, v51
	v_fmac_f32_e32 v36, v59, v59
	v_lshlrev_b32_e32 v61, 16, v44
	v_fmac_f32_e32 v36, v60, v60
	v_and_b32_e32 v62, 0xffff0000, v44
	v_fmac_f32_e32 v36, v61, v61
	v_lshlrev_b32_e32 v63, 16, v45
	v_fmac_f32_e32 v36, v62, v62
	v_and_b32_e32 v64, 0xffff0000, v45
	v_fmac_f32_e32 v36, v63, v63
	v_lshlrev_b32_e32 v65, 16, v46
	v_fmac_f32_e32 v36, v64, v64
	v_and_b32_e32 v66, 0xffff0000, v46
	v_fmac_f32_e32 v36, v65, v65
	v_lshlrev_b32_e32 v67, 16, v47
	v_fmac_f32_e32 v36, v66, v66
	v_and_b32_e32 v68, 0xffff0000, v47
	v_fmac_f32_e32 v36, v67, v67
	v_lshlrev_b32_e32 v69, 16, v40
	v_fmac_f32_e32 v36, v68, v68
	v_and_b32_e32 v70, 0xffff0000, v40
	v_fmac_f32_e32 v36, v69, v69
	v_lshlrev_b32_e32 v71, 16, v41
	v_fmac_f32_e32 v36, v70, v70
	v_and_b32_e32 v72, 0xffff0000, v41
	v_fmac_f32_e32 v36, v71, v71
	v_lshlrev_b32_e32 v73, 16, v42
	v_fmac_f32_e32 v36, v72, v72
	v_and_b32_e32 v74, 0xffff0000, v42
	v_fmac_f32_e32 v36, v73, v73
	v_lshlrev_b32_e32 v75, 16, v43
	v_fmac_f32_e32 v36, v74, v74
	v_and_b32_e32 v76, 0xffff0000, v43
	v_fmac_f32_e32 v36, v75, v75
	v_fmac_f32_e32 v36, v76, v76
	v_fmac_f32_e32 v36, v77, v77
	v_lshlrev_b32_e32 v79, 16, v37
	v_fmac_f32_e32 v36, v78, v78
	v_and_b32_e32 v80, 0xffff0000, v37
	v_fmac_f32_e32 v36, v79, v79
	v_lshlrev_b32_e32 v81, 16, v38
	v_fmac_f32_e32 v36, v80, v80
	v_and_b32_e32 v82, 0xffff0000, v38
	v_fmac_f32_e32 v36, v81, v81
	v_lshlrev_b32_e32 v83, 16, v39
	v_fmac_f32_e32 v36, v82, v82
	v_and_b32_e32 v123, 0xffff0000, v39
	v_fmac_f32_e32 v36, v83, v83
	v_fmac_f32_e32 v36, v123, v123
	ds_bpermute_b32 v37, v87, v36
	s_add_i32 s13, s14, 1
	s_lshl_b32 s3, s13, 5
	s_cmp_lg_u32 s14, 7
	s_cselect_b32 s3, s3, 0xe0
	s_add_i32 s3, s3, s5
	s_waitcnt lgkmcnt(0)
	v_add_f32_e32 v38, v36, v37
	s_ashr_i32 s6, s3, 6
	ds_bpermute_b32 v39, v119, v38
	s_ashr_i32 s7, s6, 31
	s_lshl_b32 s3, s3, 7
	s_and_b32 s3, s3, 0x1f80
	s_lshl_b64 s[10:11], s[6:7], 13
	s_or_b32 s10, s10, s3
	v_lshl_add_u64 v[36:37], s[10:11], 0, v[0:1]
	v_mad_u64_u32 v[48:49], s[6:7], v36, s59, v[96:97]
	s_waitcnt lgkmcnt(0)
	v_add_f32_e32 v36, v38, v39
	v_fmamk_f32 v36, v36, 0x3c000000, v233
	v_mul_f32_e32 v38, 0x4f800000, v36
	v_cmp_gt_f32_e32 vcc, s33, v36
	v_mad_i32_i24 v49, v37, s59, v49
	s_nop 0
	v_cndmask_b32_e32 v44, v36, v38, vcc
	v_sqrt_f32_e32 v45, v44
	s_barrier
	global_load_dwordx4 v[36:39], v[48:49], off offset:2096
	global_load_dwordx4 v[40:43], v[48:49], off offset:2080
	v_add_u32_e32 v46, -1, v45
	v_fma_f32 v47, -v46, v45, v44
	v_cmp_ge_f32_e64 s[6:7], 0, v47
	v_add_u32_e32 v47, 1, v45
	v_mov_b32_e32 v55, 0
	v_cndmask_b32_e64 v46, v45, v46, s[6:7]
	v_fma_f32 v45, -v47, v45, v44
	v_cmp_lt_f32_e64 s[6:7], 0, v45
	s_nop 1
	v_cndmask_b32_e64 v45, v46, v47, s[6:7]
	v_mul_f32_e32 v46, 0x37800000, v45
	v_cndmask_b32_e32 v45, v45, v46, vcc
	v_cmp_class_f32_e32 vcc, v44, v234
	s_nop 1
	v_cndmask_b32_e32 v124, v45, v44, vcc
	v_div_scale_f32 v125, s[6:7], v124, v124, 1.0
	v_rcp_f32_e32 v126, v125
	global_load_dwordx4 v[44:47], v[48:49], off offset:2064
	s_nop 0
	global_load_dwordx4 v[48:51], v[48:49], off offset:2048
	v_fma_f32 v127, -v125, v126, 1.0
	v_fmac_f32_e32 v126, v127, v126
	v_div_scale_f32 v127, vcc, 1.0, v124, 1.0
	v_mul_f32_e32 v128, v127, v126
	v_fma_f32 v129, -v125, v128, v127
	v_fmac_f32_e32 v128, v129, v126
	v_fma_f32 v125, -v125, v128, v127
	v_div_fmas_f32 v125, v125, v126, v128
	v_div_fixup_f32 v124, v125, v124, 1.0
	v_mul_f32_e32 v52, v124, v52
	v_mul_f32_e32 v52, v4, v52
	v_bfe_u32 v125, v52, 16, 1
	v_add3_u32 v52, v52, v125, s61
	ds_write_b16_d16_hi v122, v52 offset:34816
	v_mul_f32_e32 v52, v124, v53
	v_mul_f32_e32 v52, v5, v52
	v_bfe_u32 v53, v52, 16, 1
	v_add3_u32 v52, v52, v53, s61
	ds_write_b16_d16_hi v122, v52 offset:35088
	v_mul_f32_e32 v52, v124, v54
	v_mul_f32_e32 v52, v6, v52
	v_bfe_u32 v53, v52, 16, 1
	v_add3_u32 v52, v52, v53, s61
	ds_write_b16_d16_hi v122, v52 offset:35360
	v_mul_f32_e32 v52, v124, v56
	v_mul_f32_e32 v52, v7, v52
	v_bfe_u32 v53, v52, 16, 1
	v_add3_u32 v52, v52, v53, s61
	ds_write_b16_d16_hi v122, v52 offset:35632
	v_mul_f32_e32 v52, v124, v57
	v_mul_f32_e32 v52, v8, v52
	v_bfe_u32 v53, v52, 16, 1
	v_add3_u32 v52, v52, v53, s61
	ds_write_b16_d16_hi v122, v52 offset:35904
	v_mul_f32_e32 v52, v124, v58
	v_mul_f32_e32 v52, v9, v52
	v_bfe_u32 v53, v52, 16, 1
	v_add3_u32 v52, v52, v53, s61
	ds_write_b16_d16_hi v122, v52 offset:36176
	v_mul_f32_e32 v52, v124, v59
	v_mul_f32_e32 v52, v10, v52
	v_bfe_u32 v53, v52, 16, 1
	v_add3_u32 v52, v52, v53, s61
	ds_write_b16_d16_hi v122, v52 offset:36448
	v_mul_f32_e32 v52, v124, v60
	v_mul_f32_e32 v52, v11, v52
	v_bfe_u32 v53, v52, 16, 1
	v_add3_u32 v52, v52, v53, s61
; __device__ __forceinline__ unsigned f2bf(float f) { unsigned u = __builtin_bit_cast(unsigned, f); return (u + 0x7fffu + ((u >> 16) & 1u)) >> 16; }
; __device__ __forceinline__ void gmlp_phase(KA a, LAS unsigned char* lds, int bid, int tid, int wid, int lane) {
;     ...
;           for (int e = 0; e < 32; ++e) Vt[(sqd * 32 + e) * GW_STR + sj] = (bf16_t)f2bf(v[e] * rstd * gvr[e]); }
;         __syncthreads();
;         f32x4 acc[8];
; #pragma unroll
;         for (int dt = 0; dt < 8; ++dt) acc[dt] = (f32x4){0.f, 0.f, 0.f, 0.f};
;         const int nks = (wid >> 1) + 1;
;         for (int ks = 0; ks < nks; ++ks) {
	ds_write_b16_d16_hi v122, v52 offset:36720
	v_mul_f32_e32 v52, v124, v61
	v_mul_f32_e32 v52, v12, v52
	v_bfe_u32 v53, v52, 16, 1
	v_add3_u32 v52, v52, v53, s61
	ds_write_b16_d16_hi v122, v52 offset:36992
	v_mul_f32_e32 v52, v124, v62
	v_mul_f32_e32 v52, v13, v52
	v_bfe_u32 v53, v52, 16, 1
	v_add3_u32 v52, v52, v53, s61
	ds_write_b16_d16_hi v122, v52 offset:37264
	v_mul_f32_e32 v52, v124, v63
	v_mul_f32_e32 v52, v14, v52
	v_bfe_u32 v53, v52, 16, 1
	v_add3_u32 v52, v52, v53, s61
	ds_write_b16_d16_hi v122, v52 offset:37536
	v_mul_f32_e32 v52, v124, v64
	v_mul_f32_e32 v52, v15, v52
	v_bfe_u32 v53, v52, 16, 1
	v_add3_u32 v52, v52, v53, s61
	ds_write_b16_d16_hi v122, v52 offset:37808
	v_mul_f32_e32 v52, v124, v65
	v_mul_f32_e32 v52, v16, v52
	v_bfe_u32 v53, v52, 16, 1
	v_add3_u32 v52, v52, v53, s61
	ds_write_b16_d16_hi v122, v52 offset:38080
	v_mul_f32_e32 v52, v124, v66
	v_mul_f32_e32 v52, v17, v52
	v_bfe_u32 v53, v52, 16, 1
	v_add3_u32 v52, v52, v53, s61
	ds_write_b16_d16_hi v122, v52 offset:38352
	v_mul_f32_e32 v52, v124, v67
	v_mul_f32_e32 v52, v18, v52
	v_bfe_u32 v53, v52, 16, 1
	v_add3_u32 v52, v52, v53, s61
	ds_write_b16_d16_hi v122, v52 offset:38624
	v_mul_f32_e32 v52, v124, v68
	v_mul_f32_e32 v52, v19, v52
	v_bfe_u32 v53, v52, 16, 1
	v_add3_u32 v52, v52, v53, s61
	ds_write_b16_d16_hi v122, v52 offset:38896
	v_mul_f32_e32 v52, v124, v69
	v_mul_f32_e32 v52, v20, v52
	v_bfe_u32 v53, v52, 16, 1
	v_add3_u32 v52, v52, v53, s61
	ds_write_b16_d16_hi v122, v52 offset:39168
	v_mul_f32_e32 v52, v124, v70
	v_mul_f32_e32 v52, v21, v52
	v_bfe_u32 v53, v52, 16, 1
	v_add3_u32 v52, v52, v53, s61
	ds_write_b16_d16_hi v122, v52 offset:39440
	v_mul_f32_e32 v52, v124, v71
	v_mul_f32_e32 v52, v22, v52
	v_bfe_u32 v53, v52, 16, 1
	v_add3_u32 v52, v52, v53, s61
	ds_write_b16_d16_hi v122, v52 offset:39712
	v_mul_f32_e32 v52, v124, v72
	v_mul_f32_e32 v52, v23, v52
	v_bfe_u32 v53, v52, 16, 1
	v_add3_u32 v52, v52, v53, s61
	ds_write_b16_d16_hi v122, v52 offset:39984
	v_mul_f32_e32 v52, v124, v73
	v_mul_f32_e32 v52, v24, v52
	v_bfe_u32 v53, v52, 16, 1
	v_add3_u32 v52, v52, v53, s61
	ds_write_b16_d16_hi v122, v52 offset:40256
	v_mul_f32_e32 v52, v124, v74
	v_mul_f32_e32 v52, v25, v52
	v_bfe_u32 v53, v52, 16, 1
	v_add3_u32 v52, v52, v53, s61
	ds_write_b16_d16_hi v122, v52 offset:40528
	v_mul_f32_e32 v52, v124, v75
	v_mul_f32_e32 v52, v26, v52
	v_bfe_u32 v53, v52, 16, 1
	v_add3_u32 v52, v52, v53, s61
	ds_write_b16_d16_hi v122, v52 offset:40800
	v_mul_f32_e32 v52, v124, v76
	v_mul_f32_e32 v52, v27, v52
	v_bfe_u32 v53, v52, 16, 1
	v_add3_u32 v52, v52, v53, s61
	ds_write_b16_d16_hi v122, v52 offset:41072
	v_mul_f32_e32 v52, v124, v77
	v_mul_f32_e32 v52, v28, v52
	v_bfe_u32 v53, v52, 16, 1
	v_add3_u32 v52, v52, v53, s61
	ds_write_b16_d16_hi v122, v52 offset:41344
	v_mul_f32_e32 v52, v124, v78
	v_mul_f32_e32 v52, v29, v52
	v_bfe_u32 v53, v52, 16, 1
	v_add3_u32 v52, v52, v53, s61
	ds_write_b16_d16_hi v122, v52 offset:41616
	v_mul_f32_e32 v52, v124, v79
	v_mul_f32_e32 v52, v30, v52
	v_bfe_u32 v53, v52, 16, 1
	v_add3_u32 v52, v52, v53, s61
	ds_write_b16_d16_hi v122, v52 offset:41888
	v_mul_f32_e32 v52, v124, v80
	v_mul_f32_e32 v52, v31, v52
	v_bfe_u32 v53, v52, 16, 1
	v_add3_u32 v52, v52, v53, s61
	ds_write_b16_d16_hi v122, v52 offset:42160
	v_mul_f32_e32 v52, v124, v81
	v_mul_f32_e32 v52, v32, v52
	v_bfe_u32 v53, v52, 16, 1
	v_add3_u32 v52, v52, v53, s61
	ds_write_b16_d16_hi v122, v52 offset:42432
	v_mul_f32_e32 v52, v124, v82
	v_mul_f32_e32 v52, v33, v52
	v_bfe_u32 v53, v52, 16, 1
	v_add3_u32 v52, v52, v53, s61
	ds_write_b16_d16_hi v122, v52 offset:42704
	v_mul_f32_e32 v52, v124, v83
	v_mul_f32_e32 v52, v34, v52
	v_bfe_u32 v53, v52, 16, 1
	v_add3_u32 v52, v52, v53, s61
	ds_write_b16_d16_hi v122, v52 offset:42976
	v_mul_f32_e32 v52, v124, v123
	v_mul_f32_e32 v52, v35, v52
	v_bfe_u32 v53, v52, 16, 1
	v_add3_u32 v52, v52, v53, s61
	ds_write_b16_d16_hi v122, v52 offset:43248
	s_andn2_b64 vcc, exec, s[8:9]
	v_mov_b32_e32 v54, v55
	v_mov_b32_e32 v53, v55
	v_mov_b32_e32 v52, v55
	v_mov_b32_e32 v83, v55
	v_mov_b32_e32 v82, v55
	v_mov_b32_e32 v81, v55
	v_mov_b32_e32 v80, v55
	v_mov_b32_e32 v79, v55
	v_mov_b32_e32 v78, v55
	v_mov_b32_e32 v77, v55
	v_mov_b32_e32 v76, v55
	v_mov_b32_e32 v75, v55
	v_mov_b32_e32 v74, v55
	v_mov_b32_e32 v73, v55
	v_mov_b32_e32 v72, v55
	v_mov_b32_e32 v71, v55
	v_mov_b32_e32 v70, v55
	v_mov_b32_e32 v69, v55
	v_mov_b32_e32 v68, v55
	v_mov_b32_e32 v67, v55
	v_mov_b32_e32 v66, v55
	v_mov_b32_e32 v65, v55
	v_mov_b32_e32 v64, v55
	v_mov_b32_e32 v63, v55
	v_mov_b32_e32 v62, v55
	v_mov_b32_e32 v61, v55
	v_mov_b32_e32 v60, v55
	v_mov_b32_e32 v59, v55
	v_mov_b32_e32 v58, v55
	v_mov_b32_e32 v57, v55
	v_mov_b32_e32 v56, v55
	s_waitcnt lgkmcnt(0)
	s_barrier
	s_cbranch_vccnz .LBB0_103
	v_mov_b32_e32 v56, 0
	v_mov_b32_e32 v123, v89
	v_mov_b32_e32 v124, v121
	v_mov_b32_e32 v125, v120
	v_mov_b32_e32 v126, v2
	s_mov_b32 s6, s12
	v_mov_b32_e32 v57, v56
	v_mov_b32_e32 v58, v56
	v_mov_b32_e32 v59, v56
	v_mov_b32_e32 v60, v56
	v_mov_b32_e32 v61, v56
	v_mov_b32_e32 v62, v56
	v_mov_b32_e32 v63, v56
	v_mov_b32_e32 v64, v56
	v_mov_b32_e32 v65, v56
	v_mov_b32_e32 v66, v56
	v_mov_b32_e32 v67, v56
	v_mov_b32_e32 v68, v56
	v_mov_b32_e32 v69, v56
	v_mov_b32_e32 v70, v56
	v_mov_b32_e32 v71, v56
	v_mov_b32_e32 v72, v56
	v_mov_b32_e32 v73, v56
	v_mov_b32_e32 v74, v56
	v_mov_b32_e32 v75, v56
	v_mov_b32_e32 v76, v56
	v_mov_b32_e32 v77, v56
	v_mov_b32_e32 v78, v56
	v_mov_b32_e32 v79, v56
	v_mov_b32_e32 v80, v56
	v_mov_b32_e32 v81, v56
	v_mov_b32_e32 v82, v56
	v_mov_b32_e32 v83, v56
	v_mov_b32_e32 v52, v56
	v_mov_b32_e32 v53, v56
	v_mov_b32_e32 v54, v56
	v_mov_b32_e32 v55, v56

; #define LAS __attribute__((address_space(3)))
; __device__ __forceinline__ unsigned pk2(float lo, float hi) { return pg8::cvt_pk_bf16(lo, hi); }
; __device__ __forceinline__ void attn_phase(KA a, LAS unsigned char* lds, int bid, int nblk, int tid, int wid, int lane) {
;     ...
;         for (int c = 0; c < 8; ++c) {
;             const u32x4 q0 = qn0, q1 = qn1;
;             { const bf16_t* qp = Z + (R0 + 16 * (c < 7 ? c + 1 : c) + r) * INC + 2 * AW + hq * 64 + 8 * q; qn0 = *(const u32x4*)qp; qn1 = *(const u32x4*)(qp + 32); }
;             float qv[2][8] = {{bflo(q0.x), bfhi(q0.x), bflo(q0.y), bfhi(q0.y), bflo(q0.z), bfhi(q0.z), bflo(q0.w), bfhi(q0.w)},
;                               {bflo(q1.x), bfhi(q1.x), bflo(q1.y), bfhi(q1.y), bflo(q1.z), bfhi(q1.z), bflo(q1.w), bfhi(q1.w)}};
;             float ss = 0.f;
; #pragma unroll
;             for (int ks = 0; ks < 2; ++ks)
; #pragma unroll
;                 for (int e = 0; e < 8; ++e) ss += qv[ks][e] * qv[ks][e];
;             ss += __shfl_xor(ss, 16); ss += __shfl_xor(ss, 32);
;             const float rstd = 1.0f / sqrtf(ss * (1.0f / 64.0f) + EPS);
;             bf16x8 qf[2];
; #pragma unroll
;             for (int ks = 0; ks < 2; ++ks) { u32x4 o; o.x = pk2(qv[ks][0] * rstd * gq[ks][0], qv[ks][1] * rstd * gq[ks][1]); o.y = pk2(qv[ks][2] * rstd * gq[ks][2], qv[ks][3] * rstd * gq[ks][3]);
;                 o.z = pk2(qv[ks][4] * rstd * gq[ks][4], qv[ks][5] * rstd * gq[ks][5]); o.w = pk2(qv[ks][6] * rstd * gq[ks][6], qv[ks][7] * rstd * gq[ks][7]); qf[ks] = __builtin_bit_cast(bf16x8, o); }
;             f32x4 sacc[9];
; #pragma unroll
;             for (int t = 0; t < 9; ++t) { sacc[t] = (f32x4){0.f, 0.f, 0.f, 0.f};
; #pragma unroll
;                 for (int ks = 0; ks < 2; ++ks) { const bf16x8 kf = *(const LAS bf16x8*)(Kl + (16 * (c + t) + r) * KL_STR + 32 * ks + 8 * q);
;                     sacc[t] = __builtin_amdgcn_mfma_f32_16x16x32_bf16(kf, qf[ks], sacc[t], 0, 0, 0); } }
.LBB0_141:
	s_waitcnt vmcnt(1)
	v_and_b32_e32 v2, 0xffff0000, v32
	v_lshlrev_b32_e32 v1, 16, v32
	s_waitcnt vmcnt(0)
	v_lshlrev_b32_e32 v129, 16, v30
	v_and_b32_e32 v130, 0xffff0000, v30
	v_mul_f32_e32 v30, v2, v2
	v_lshlrev_b32_e32 v32, 16, v33
	v_fmac_f32_e32 v30, v1, v1
	v_and_b32_e32 v33, 0xffff0000, v33
	v_fmac_f32_e32 v30, v32, v32
	v_lshlrev_b32_e32 v38, 16, v34
	v_fmac_f32_e32 v30, v33, v33
	v_and_b32_e32 v34, 0xffff0000, v34
	v_fmac_f32_e32 v30, v38, v38
	v_lshlrev_b32_e32 v39, 16, v35
	v_fmac_f32_e32 v30, v34, v34
	v_and_b32_e32 v35, 0xffff0000, v35
	v_fmac_f32_e32 v30, v39, v39
	v_lshlrev_b32_e32 v40, 16, v28
	v_fmac_f32_e32 v30, v35, v35
	v_and_b32_e32 v41, 0xffff0000, v28
	v_fmac_f32_e32 v30, v40, v40
	v_lshlrev_b32_e32 v42, 16, v29
	v_fmac_f32_e32 v30, v41, v41
	v_and_b32_e32 v43, 0xffff0000, v29
	v_fmac_f32_e32 v30, v42, v42
	v_fmac_f32_e32 v30, v43, v43
	v_fmac_f32_e32 v30, v129, v129
	v_and_b32_e32 v36, 0xffff0000, v31
	v_lshlrev_b32_e32 v37, 16, v31
	v_fmac_f32_e32 v30, v130, v130
	v_pk_mul_f32 v[28:29], v[36:37], v[36:37]
	global_load_dwordx4 v[24:27], v[90:91], off offset:-64
	global_load_dwordx4 v[20:23], v[90:91], off
	v_add_f32_e32 v29, v29, v30
	v_add_f32_e32 v28, v28, v29
	ds_bpermute_b32 v29, v94, v28
	s_add_i32 s52, s53, 1
	s_cmp_lt_u32 s53, 6
	v_add_u32_e32 v164, s44, v114
	v_add_u32_e32 v165, 0x2000, v164
	s_waitcnt lgkmcnt(0)
	v_add_f32_e32 v28, v28, v29
	ds_bpermute_b32 v29, v95, v28
	v_add_u32_e32 v166, 0x4000, v164
	v_add_u32_e32 v167, s44, v113
	s_waitcnt lgkmcnt(0)
	v_add_f32_e32 v28, v28, v29
	v_fmamk_f32 v28, v28, 0x3c800000, v233
	v_cmp_gt_f32_e32 vcc, s33, v28
	v_mul_f32_e32 v29, 0x4f800000, v28
	s_nop 0
	v_cndmask_b32_e32 v28, v28, v29, vcc
	v_sqrt_f32_e32 v29, v28
	s_nop 0
	v_add_u32_e32 v30, -1, v29
	v_fma_f32 v31, -v30, v29, v28
	v_cmp_ge_f32_e64 s[36:37], 0, v31
	v_add_u32_e32 v31, 1, v29
	s_nop 0
	v_cndmask_b32_e64 v30, v29, v30, s[36:37]
	v_fma_f32 v29, -v31, v29, v28
	v_cmp_lt_f32_e64 s[36:37], 0, v29
	s_nop 1
	v_cndmask_b32_e64 v29, v30, v31, s[36:37]
	v_mul_f32_e32 v30, 0x37800000, v29
	v_cndmask_b32_e32 v29, v29, v30, vcc
	v_cmp_class_f32_e32 vcc, v28, v234
	s_nop 1
	v_cndmask_b32_e32 v28, v29, v28, vcc
	v_div_scale_f32 v29, s[36:37], v28, v28, 1.0
	v_rcp_f32_e32 v30, v29
	s_cselect_b64 s[36:37], -1, 0
	v_fma_f32 v31, -v29, v30, 1.0
	v_fmac_f32_e32 v30, v31, v30
	v_div_scale_f32 v31, vcc, 1.0, v28, 1.0
	v_mul_f32_e32 v131, v31, v30
	v_fma_f32 v132, -v29, v131, v31
	v_fmac_f32_e32 v131, v132, v30
	v_fma_f32 v29, -v29, v131, v31
	v_div_fmas_f32 v29, v29, v30, v131
	v_div_fixup_f32 v131, v29, v28, 1.0
	v_mul_f32_e32 v1, v131, v1
	v_mul_f32_e32 v2, v131, v2
	v_mul_f32_e32 v1, v16, v1
	v_mul_f32_e32 v2, v17, v2
	v_cvt_pk_bf16_f32 v28, v1, v2
	v_mul_f32_e32 v1, v131, v32
	v_mul_f32_e32 v2, v131, v33
	v_mul_f32_e32 v1, v18, v1
	v_mul_f32_e32 v2, v19, v2
	v_cvt_pk_bf16_f32 v29, v1, v2
	v_mul_f32_e32 v1, v131, v38
	v_mul_f32_e32 v2, v131, v34
	v_mul_f32_e32 v1, v12, v1
	v_mul_f32_e32 v2, v13, v2
	v_cvt_pk_bf16_f32 v30, v1, v2
	v_mul_f32_e32 v1, v131, v39
	v_mul_f32_e32 v2, v131, v35
	v_mul_f32_e32 v1, v14, v1
	v_mul_f32_e32 v2, v15, v2
	v_cvt_pk_bf16_f32 v31, v1, v2
	v_mul_f32_e32 v1, v131, v40
	v_mul_f32_e32 v2, v131, v41
	v_mul_f32_e32 v1, v8, v1
	v_mul_f32_e32 v2, v9, v2
	v_cvt_pk_bf16_f32 v32, v1, v2
	v_mul_f32_e32 v1, v131, v42
	v_mul_f32_e32 v2, v131, v43
	v_mul_f32_e32 v1, v10, v1
	v_mul_f32_e32 v2, v11, v2
	v_cvt_pk_bf16_f32 v33, v1, v2
	v_mul_f32_e32 v1, v131, v129
	v_mul_f32_e32 v2, v131, v130
	v_mul_f32_e32 v1, v4, v1
	v_mul_f32_e32 v2, v5, v2
	v_cvt_pk_bf16_f32 v34, v1, v2
	v_mul_f32_e32 v1, v131, v37
	v_mul_f32_e32 v2, v131, v36
	v_mul_f32_e32 v1, v6, v1
	v_mul_f32_e32 v2, v7, v2
	v_cvt_pk_bf16_f32 v35, v1, v2
	ds_read_b128 v[36:39], v0
	ds_read_b128 v[40:43], v0 offset:64
	s_waitcnt lgkmcnt(1)
	v_mfma_f32_16x16x32_bf16 v[36:39], v[36:39], v[28:31], 0
	ds_read_b128 v[130:133], v0 offset:2368
	ds_read_b128 v[134:137], v0 offset:4672
	ds_read_b128 v[138:141], v0 offset:6976
	s_waitcnt lgkmcnt(3)
	v_mfma_f32_16x16x32_bf16 v[36:39], v[40:43], v[32:35], v[36:39]
	ds_read_b128 v[40:43], v0 offset:2304
	ds_read_b128 v[142:145], v0 offset:9280
	ds_read_b128 v[146:149], v0 offset:11584
	s_waitcnt lgkmcnt(2)
	v_mfma_f32_16x16x32_bf16 v[40:43], v[40:43], v[28:31], 0
	ds_read_b128 v[150:153], v0 offset:13888
	v_add_u32_e32 v129, 0x900, v0
	s_nop 0
	v_fmamk_f32 v1, v37, 0x3e38aa3b, v125
	v_mfma_f32_16x16x32_bf16 v[40:43], v[130:133], v[32:35], v[40:43]
	ds_read_b128 v[130:133], v0 offset:4608
	s_and_b64 vcc, s[30:31], s[36:37]
	v_cndmask_b32_e64 v1, v1, v243, s[30:31]
	s_waitcnt lgkmcnt(0)
	v_mfma_f32_16x16x32_bf16 v[130:133], v[130:133], v[28:31], 0
	ds_read_b128 v[154:157], v0 offset:16192
	s_cmp_lt_u32 s53, 5
	s_cselect_b64 s[36:37], -1, 0
	v_mfma_f32_16x16x32_bf16 v[130:133], v[134:137], v[32:35], v[130:133]
	ds_read_b128 v[134:137], v0 offset:6912
	v_fmamk_f32 v37, v43, 0x3e38aa3b, v80
	v_cndmask_b32_e64 v37, v37, v243, s[30:31]
	s_waitcnt lgkmcnt(0)
	v_mfma_f32_16x16x32_bf16 v[134:137], v[134:137], v[28:31], 0
	v_mfma_f32_16x16x32_bf16 v[134:137], v[138:141], v[32:35], v[134:137]
	ds_read_b128 v[138:141], v0 offset:9216
	s_waitcnt lgkmcnt(0)
	v_mfma_f32_16x16x32_bf16 v[138:141], v[138:141], v[28:31], 0
	s_nop 4
	v_fmamk_f32 v43, v135, 0x3e38aa3b, v74
	v_mfma_f32_16x16x32_bf16 v[138:141], v[142:145], v[32:35], v[138:141]
	ds_read_b128 v[142:145], v0 offset:11520
	s_waitcnt lgkmcnt(0)
	v_mfma_f32_16x16x32_bf16 v[142:145], v[142:145], v[28:31], 0
	s_nop 4
	v_fmamk_f32 v135, v141, 0x3e38aa3b, v68
	v_mfma_f32_16x16x32_bf16 v[142:145], v[146:149], v[32:35], v[142:145]
	ds_read_b128 v[146:149], v0 offset:13824
	s_waitcnt lgkmcnt(0)
; #define LAS __attribute__((address_space(3)))
; __device__ __forceinline__ void attn_phase(KA a, LAS unsigned char* lds, int bid, int nblk, int tid, int wid, int lane) {
;     ...
;             f32x4 sacc[9];
; #pragma unroll
;             for (int t = 0; t < 9; ++t) { sacc[t] = (f32x4){0.f, 0.f, 0.f, 0.f};
; #pragma unroll
;                 for (int ks = 0; ks < 2; ++ks) { const bf16x8 kf = *(const LAS bf16x8*)(Kl + (16 * (c + t) + r) * KL_STR + 32 * ks + 8 * q);
;                     sacc[t] = __builtin_amdgcn_mfma_f32_16x16x32_bf16(kf, qf[ks], sacc[t], 0, 0, 0); } }
;             float mx = sink2;
; #pragma unroll
;             for (int t = 0; t < 9; ++t) { const bool dead = (nb == 0) && (c + t < 8);
; #pragma unroll
;                 for (int e = 0; e < 4; ++e) { float s = sacc[t][e] * SC + breg[t][e]; s = dead ? NEG : s; sacc[t][e] = s; mx = fmaxf(mx, s); } }
;             mx = fmaxf(mx, __shfl_xor(mx, 16)); mx = fmaxf(mx, __shfl_xor(mx, 32));
	v_mfma_f32_16x16x32_bf16 v[146:149], v[146:149], v[28:31], 0
	v_mfma_f32_16x16x32_bf16 v[146:149], v[150:153], v[32:35], v[146:149]
	ds_read_b128 v[150:153], v0 offset:16128
	s_waitcnt lgkmcnt(0)
	v_mfma_f32_16x16x32_bf16 v[150:153], v[150:153], v[28:31], 0
	s_nop 4
	v_fmamk_f32 v141, v147, 0x3e38aa3b, v62
	v_mfma_f32_16x16x32_bf16 v[150:153], v[154:157], v[32:35], v[150:153]
	ds_read_b128 v[154:157], v0 offset:18432
	s_waitcnt lgkmcnt(0)
	v_mfma_f32_16x16x32_bf16 v[28:31], v[154:157], v[28:31], 0
	ds_read_b128 v[154:157], v0 offset:18496
	v_fmamk_f32 v0, v36, 0x3e38aa3b, v126
	v_cndmask_b32_e64 v0, v0, v243, s[30:31]
	s_waitcnt lgkmcnt(0)
	v_mfma_f32_16x16x32_bf16 v[28:31], v[154:157], v[32:35], v[28:31]
	v_fmamk_f32 v32, v38, 0x3e38aa3b, v128
	v_fmamk_f32 v33, v39, 0x3e38aa3b, v127
	v_max3_f32 v2, v124, v0, v1
	v_cndmask_b32_e64 v32, v32, v243, s[30:31]
	v_cndmask_b32_e64 v33, v33, v243, s[30:31]
	v_fmamk_f32 v34, v40, 0x3e38aa3b, v83
	v_fmamk_f32 v35, v41, 0x3e38aa3b, v82
	v_fmamk_f32 v38, v130, 0x3e38aa3b, v79
	v_fmamk_f32 v39, v131, 0x3e38aa3b, v78
	v_fmamk_f32 v40, v132, 0x3e38aa3b, v77
	v_fmamk_f32 v41, v133, 0x3e38aa3b, v76
	v_max3_f32 v2, v2, v32, v33
	v_cndmask_b32_e64 v34, v34, v243, s[30:31]
	v_cndmask_b32_e64 v35, v35, v243, s[30:31]
	v_fmamk_f32 v36, v42, 0x3e38aa3b, v81
	v_cndmask_b32_e32 v38, v38, v243, vcc
	v_cndmask_b32_e32 v39, v39, v243, vcc
	v_cndmask_b32_e32 v40, v40, v243, vcc
	v_cndmask_b32_e32 v41, v41, v243, vcc
	s_and_b64 vcc, s[30:31], s[36:37]
	v_max3_f32 v2, v2, v34, v35
	v_cndmask_b32_e64 v36, v36, v243, s[30:31]
	s_cmp_lt_u32 s53, 4
	v_max3_f32 v2, v2, v36, v37
	v_fmamk_f32 v42, v134, 0x3e38aa3b, v75
	v_fmamk_f32 v130, v136, 0x3e38aa3b, v73
	v_fmamk_f32 v131, v137, 0x3e38aa3b, v72
	s_cselect_b64 s[36:37], -1, 0
	v_max3_f32 v2, v2, v38, v39
	v_cndmask_b32_e32 v42, v42, v243, vcc
	v_cndmask_b32_e32 v43, v43, v243, vcc
	v_cndmask_b32_e32 v130, v130, v243, vcc
	v_cndmask_b32_e32 v131, v131, v243, vcc
	s_and_b64 vcc, s[30:31], s[36:37]
	v_max3_f32 v2, v2, v40, v41
	s_cmp_lt_u32 s53, 3
	v_max3_f32 v2, v2, v42, v43
	v_fmamk_f32 v132, v138, 0x3e38aa3b, v71
	v_fmamk_f32 v133, v139, 0x3e38aa3b, v70
	v_fmamk_f32 v134, v140, 0x3e38aa3b, v69
	s_cselect_b64 s[36:37], -1, 0
	v_max3_f32 v2, v2, v130, v131
	v_cndmask_b32_e32 v132, v132, v243, vcc
	v_cndmask_b32_e32 v133, v133, v243, vcc
	v_cndmask_b32_e32 v134, v134, v243, vcc
	v_cndmask_b32_e32 v135, v135, v243, vcc
	s_and_b64 vcc, s[30:31], s[36:37]
	v_max3_f32 v2, v2, v132, v133
	v_fmamk_f32 v136, v142, 0x3e38aa3b, v67
	v_fmamk_f32 v137, v143, 0x3e38aa3b, v66
	s_cmp_lt_u32 s53, 2
	v_max3_f32 v2, v2, v134, v135
	v_cndmask_b32_e32 v136, v136, v243, vcc
	v_cndmask_b32_e32 v137, v137, v243, vcc
	v_fmamk_f32 v138, v144, 0x3e38aa3b, v65
	v_fmamk_f32 v139, v145, 0x3e38aa3b, v64
	s_cselect_b64 s[36:37], -1, 0
	v_max3_f32 v2, v2, v136, v137
	v_cndmask_b32_e32 v138, v138, v243, vcc
	v_cndmask_b32_e32 v139, v139, v243, vcc
	s_and_b64 vcc, s[30:31], s[36:37]
	v_fmamk_f32 v140, v146, 0x3e38aa3b, v63
	s_or_b32 s3, s53, s39
	v_max3_f32 v2, v2, v138, v139
	v_cndmask_b32_e32 v140, v140, v243, vcc
	v_cndmask_b32_e32 v141, v141, v243, vcc
	v_fmamk_f32 v142, v148, 0x3e38aa3b, v61
	v_fmamk_f32 v143, v149, 0x3e38aa3b, v60
	s_cmp_eq_u32 s3, 0
	v_max3_f32 v2, v2, v140, v141
	v_cndmask_b32_e32 v142, v142, v243, vcc
	v_cndmask_b32_e32 v143, v143, v243, vcc
	s_cselect_b64 vcc, -1, 0
	v_fmamk_f32 v144, v150, 0x3e38aa3b, v59
	v_fmamk_f32 v145, v151, 0x3e38aa3b, v58
	v_max3_f32 v2, v2, v142, v143
	v_cndmask_b32_e32 v144, v144, v243, vcc
	v_cndmask_b32_e32 v145, v145, v243, vcc
	v_fmamk_f32 v146, v152, 0x3e38aa3b, v57
	v_fmamk_f32 v147, v153, 0x3e38aa3b, v56
	v_max3_f32 v2, v2, v144, v145
	v_cndmask_b32_e32 v146, v146, v243, vcc
	v_cndmask_b32_e32 v147, v147, v243, vcc
	v_max3_f32 v2, v2, v146, v147
	v_fmamk_f32 v28, v28, 0x3e38aa3b, v121
	v_fmamk_f32 v29, v29, 0x3e38aa3b, v51
	v_max3_f32 v2, v2, v28, v29
	v_fmamk_f32 v30, v30, 0x3e38aa3b, v123
	v_fmamk_f32 v31, v31, 0x3e38aa3b, v122
	v_max3_f32 v2, v2, v30, v31
	ds_bpermute_b32 v148, v94, v2
	s_mov_b32 s3, 0x13100000
	s_add_i32 s44, s44, 32
	s_cmp_eq_u32 s44, 0
	s_mov_b32 s53, s52
	s_waitcnt lgkmcnt(0)
	v_max_f32_e32 v148, v148, v148
	v_max_f32_e32 v2, v2, v148
	ds_bpermute_b32 v148, v95, v2
	s_waitcnt lgkmcnt(0)
; #define LAS __attribute__((address_space(3)))
; __device__ __forceinline__ unsigned pk2(float lo, float hi) { return pg8::cvt_pk_bf16(lo, hi); }
; __device__ __forceinline__ void attn_phase(KA a, LAS unsigned char* lds, int bid, int nblk, int tid, int wid, int lane) {
;     ...
;             mx = fmaxf(mx, __shfl_xor(mx, 16)); mx = fmaxf(mx, __shfl_xor(mx, 32));
;             float l = 0.f;
; #pragma unroll
;             for (int t = 0; t < 9; ++t)
; #pragma unroll
;                 for (int e = 0; e < 4; ++e) { const float p = __builtin_amdgcn_exp2f(sacc[t][e] - mx); sacc[t][e] = p; l += p; }
;             l += __shfl_xor(l, 16); l += __shfl_xor(l, 32);
;             l += __builtin_amdgcn_exp2f(sink2 - mx);
;             const float inv = 1.0f / l;
;             f32x4 o[4];
; #pragma unroll
;             for (int dt = 0; dt < 4; ++dt) o[dt] = (f32x4){0.f, 0.f, 0.f, 0.f};
; #pragma unroll
;             for (int kk = 0; kk < 5; ++kk) {
;                 u32x4 pw; pw.x = pk2(sacc[2 * kk][0], sacc[2 * kk][1]); pw.y = pk2(sacc[2 * kk][2], sacc[2 * kk][3]);
;                 if (kk < 4) { pw.z = pk2(sacc[(2 * kk + 1) % 9][0], sacc[(2 * kk + 1) % 9][1]); pw.w = pk2(sacc[(2 * kk + 1) % 9][2], sacc[(2 * kk + 1) % 9][3]); } else { pw.z = 0u; pw.w = 0u; }
;                 const bf16x8 pf = __builtin_bit_cast(bf16x8, pw);
; #pragma unroll
;                 for (int dt = 0; dt < 4; ++dt) { const LAS bf16_t* vp = Vt + (16 * dt + r) * VT_STR + 16 * (c + 2 * kk) + 4 * q;
;                     u32x4 av; const u32x2 lo = *(const LAS u32x2*)vp; av.x = lo.x; av.y = lo.y;
;                     if (kk < 4) { const u32x2 hi = *(const LAS u32x2*)(vp + 16); av.z = hi.x; av.w = hi.y; } else { av.z = 0u; av.w = 0u; }
;                     o[dt] = __builtin_amdgcn_mfma_f32_16x16x32_bf16(__builtin_bit_cast(bf16x8, av), pf, o[dt], 0, 0, 0); }
;             }
	v_max_f32_e32 v148, v148, v148
	v_max_f32_e32 v148, v2, v148
	v_sub_f32_e32 v0, v0, v148
	v_exp_f32_e32 v149, v0
	v_sub_f32_e32 v1, v1, v148
	v_exp_f32_e32 v150, v1
	v_sub_f32_e32 v1, v32, v148
	v_exp_f32_e32 v151, v1
	v_sub_f32_e32 v1, v33, v148
	v_exp_f32_e32 v152, v1
	v_sub_f32_e32 v1, v34, v148
	v_add_f32_e32 v0, 0, v149
	v_exp_f32_e32 v153, v1
	v_sub_f32_e32 v1, v35, v148
	v_add_f32_e32 v0, v150, v0
	v_exp_f32_e32 v154, v1
	v_sub_f32_e32 v1, v36, v148
	v_add_f32_e32 v0, v151, v0
	v_exp_f32_e32 v155, v1
	v_sub_f32_e32 v1, v37, v148
	v_add_f32_e32 v0, v152, v0
	v_exp_f32_e32 v156, v1
	v_add_f32_e32 v0, v153, v0
	v_add_f32_e32 v0, v154, v0
	v_add_f32_e32 v0, v155, v0
	v_add_f32_e32 v1, v156, v0
	v_sub_f32_e32 v0, v38, v148
	v_exp_f32_e32 v0, v0
	v_sub_f32_e32 v35, v43, v148
	v_exp_f32_e32 v35, v35
	v_sub_f32_e32 v36, v130, v148
	v_add_f32_e32 v2, v0, v1
	v_sub_f32_e32 v1, v39, v148
	v_exp_f32_e32 v1, v1
	v_exp_f32_e32 v36, v36
	v_sub_f32_e32 v37, v131, v148
	v_exp_f32_e32 v39, v37
	v_add_f32_e32 v32, v1, v2
	v_sub_f32_e32 v2, v40, v148
	v_exp_f32_e32 v2, v2
	v_sub_f32_e32 v43, v137, v148
	v_exp_f32_e32 v43, v43
	v_sub_f32_e32 v130, v138, v148
	v_add_f32_e32 v33, v2, v32
	v_sub_f32_e32 v32, v41, v148
	v_exp_f32_e32 v32, v32
	v_exp_f32_e32 v131, v130
	v_sub_f32_e32 v130, v139, v148
	v_sub_f32_e32 v137, v145, v148
	v_add_f32_e32 v34, v32, v33
	v_sub_f32_e32 v33, v42, v148
	v_exp_f32_e32 v33, v33
	v_exp_f32_e32 v138, v137
	v_sub_f32_e32 v137, v146, v148
	v_exp_f32_e32 v139, v137
	v_add_f32_e32 v34, v33, v34
	v_add_f32_e32 v34, v35, v34
	v_add_f32_e32 v34, v36, v34
	v_add_f32_e32 v37, v39, v34
	v_sub_f32_e32 v34, v132, v148
	v_exp_f32_e32 v34, v34
	v_sub_f32_e32 v132, v141, v148
	v_exp_f32_e32 v132, v132
	v_sub_f32_e32 v137, v147, v148
	v_add_f32_e32 v38, v34, v37
	v_sub_f32_e32 v37, v133, v148
	v_exp_f32_e32 v37, v37
	v_sub_f32_e32 v133, v142, v148
	v_exp_f32_e32 v133, v133
	v_exp_f32_e32 v142, v137
	v_add_f32_e32 v40, v37, v38
	v_sub_f32_e32 v38, v134, v148
	v_exp_f32_e32 v38, v38
	v_exp_f32_e32 v134, v130
	v_sub_f32_e32 v28, v28, v148
	v_exp_f32_e32 v137, v28
	v_add_f32_e32 v41, v38, v40
	v_sub_f32_e32 v40, v135, v148
	v_exp_f32_e32 v40, v40
	v_sub_f32_e32 v135, v143, v148
	v_exp_f32_e32 v135, v135
	v_sub_f32_e32 v29, v29, v148
	v_add_f32_e32 v42, v40, v41
	v_sub_f32_e32 v41, v136, v148
	v_exp_f32_e32 v41, v41
	v_sub_f32_e32 v136, v144, v148
	v_exp_f32_e32 v136, v136
	v_add_f32_e32 v42, v41, v42
	v_add_f32_e32 v42, v43, v42
	v_add_f32_e32 v42, v131, v42
	v_add_f32_e32 v130, v134, v42
	v_sub_f32_e32 v42, v140, v148
	v_exp_f32_e32 v42, v42
	v_exp_f32_e32 v140, v29
	v_sub_f32_e32 v29, v30, v148
	v_exp_f32_e32 v141, v29
	v_add_f32_e32 v130, v42, v130
	v_add_f32_e32 v130, v132, v130
	v_add_f32_e32 v130, v133, v130
	v_add_f32_e32 v130, v135, v130
	v_add_f32_e32 v130, v136, v130
	v_add_f32_e32 v130, v138, v130
	v_add_f32_e32 v130, v139, v130
	v_sub_f32_e32 v29, v31, v148
	v_add_f32_e32 v130, v142, v130
	v_exp_f32_e32 v143, v29
	v_add_f32_e32 v28, v137, v130
	v_add_f32_e32 v28, v140, v28
	v_add_f32_e32 v28, v141, v28
	v_add_f32_e32 v28, v143, v28
	ds_bpermute_b32 v29, v94, v28
	s_waitcnt lgkmcnt(0)
	v_add_f32_e32 v28, v28, v29
	ds_bpermute_b32 v29, v95, v28
	s_waitcnt lgkmcnt(0)
	v_add_f32_e32 v28, v28, v29
	v_sub_f32_e32 v29, v124, v148
	v_exp_f32_e32 v29, v29
	s_nop 0
	v_add_f32_e32 v130, v29, v28
	v_cvt_pk_bf16_f32 v28, v149, v150
	v_cvt_pk_bf16_f32 v29, v151, v152
	v_cvt_pk_bf16_f32 v30, v153, v154
	v_cvt_pk_bf16_f32 v31, v155, v156
	ds_read2_b64 v[144:147], v164 offset0:28 offset1:32
	ds_read2_b64 v[148:151], v165 offset0:60 offset1:64
	ds_read2_b64 v[152:155], v166 offset0:92 offset1:96
	ds_read2_b64 v[156:159], v167 offset0:28 offset1:32
	s_waitcnt lgkmcnt(3)
	v_mfma_f32_16x16x32_bf16 v[144:147], v[144:147], v[28:31], 0
	s_waitcnt lgkmcnt(2)
	v_mfma_f32_16x16x32_bf16 v[148:151], v[148:151], v[28:31], 0
	s_waitcnt lgkmcnt(1)
	v_mfma_f32_16x16x32_bf16 v[152:155], v[152:155], v[28:31], 0
	s_waitcnt lgkmcnt(0)
	v_mfma_f32_16x16x32_bf16 v[28:31], v[156:159], v[28:31], 0
	v_cvt_pk_bf16_f32 v156, v0, v1
	v_cvt_pk_bf16_f32 v157, v2, v32
	v_cvt_pk_bf16_f32 v158, v33, v35
	v_cvt_pk_bf16_f32 v159, v36, v39
	ds_read2_b64 v[160:163], v164 offset0:36 offset1:40
	s_waitcnt lgkmcnt(0)
	v_mfma_f32_16x16x32_bf16 v[144:147], v[160:163], v[156:159], v[144:147]
	ds_read2_b64 v[160:163], v165 offset0:68 offset1:72
	v_mov_b32_e32 v2, v3
	s_waitcnt lgkmcnt(0)
	v_mfma_f32_16x16x32_bf16 v[148:151], v[160:163], v[156:159], v[148:151]
	ds_read2_b64 v[160:163], v166 offset0:100 offset1:104
	s_waitcnt lgkmcnt(0)
	v_mfma_f32_16x16x32_bf16 v[152:155], v[160:163], v[156:159], v[152:155]
	ds_read2_b64 v[160:163], v167 offset0:36 offset1:40
	v_cvt_pk_bf16_f32 v32, v34, v37
	v_cvt_pk_bf16_f32 v33, v38, v40
	v_cvt_pk_bf16_f32 v34, v41, v43
	v_cvt_pk_bf16_f32 v35, v131, v134
	ds_read2_b64 v[36:39], v164 offset0:44 offset1:48
	s_waitcnt lgkmcnt(0)
	v_mfma_f32_16x16x32_bf16 v[36:39], v[36:39], v[32:35], v[144:147]
	s_nop 2
	ds_read2_b64 v[144:147], v165 offset0:76 offset1:80
	s_waitcnt lgkmcnt(0)
	v_mfma_f32_16x16x32_bf16 v[144:147], v[144:147], v[32:35], v[148:151]
	s_nop 2
	ds_read2_b64 v[148:151], v166 offset0:108 offset1:112
	s_waitcnt lgkmcnt(0)
	v_mfma_f32_16x16x32_bf16 v[148:151], v[148:151], v[32:35], v[152:155]
	s_nop 2
	ds_read2_b64 v[152:155], v167 offset0:44 offset1:48
	v_cvt_pk_bf16_f32 v132, v42, v132
	v_cvt_pk_bf16_f32 v133, v133, v135
	v_mfma_f32_16x16x32_bf16 v[28:31], v[160:163], v[156:159], v[28:31]
	v_cvt_pk_bf16_f32 v134, v136, v138
	v_cvt_pk_bf16_f32 v135, v139, v142
	s_waitcnt lgkmcnt(0)
; #define LAS __attribute__((address_space(3)))
; __device__ __forceinline__ unsigned pk2(float lo, float hi) { return pg8::cvt_pk_bf16(lo, hi); }
; __device__ __forceinline__ void attn_phase(KA a, LAS unsigned char* lds, int bid, int nblk, int tid, int wid, int lane) {
;     ...
;             float qv[2][8] = {{bflo(q0.x), bfhi(q0.x), bflo(q0.y), bfhi(q0.y), bflo(q0.z), bfhi(q0.z), bflo(q0.w), bfhi(q0.w)},
;                               {bflo(q1.x), bfhi(q1.x), bflo(q1.y), bfhi(q1.y), bflo(q1.z), bfhi(q1.z), bflo(q1.w), bfhi(q1.w)}};
;             float ss = 0.f;
; #pragma unroll
;             for (int ks = 0; ks < 2; ++ks)
; #pragma unroll
;                 for (int e = 0; e < 8; ++e) ss += qv[ks][e] * qv[ks][e];
;             ss += __shfl_xor(ss, 16); ss += __shfl_xor(ss, 32);
;             const float rstd = 1.0f / sqrtf(ss * (1.0f / 64.0f) + EPS);
;     ...
; #pragma unroll
;             for (int kk = 0; kk < 5; ++kk) {
;                 u32x4 pw; pw.x = pk2(sacc[2 * kk][0], sacc[2 * kk][1]); pw.y = pk2(sacc[2 * kk][2], sacc[2 * kk][3]);
;                 if (kk < 4) { pw.z = pk2(sacc[(2 * kk + 1) % 9][0], sacc[(2 * kk + 1) % 9][1]); pw.w = pk2(sacc[(2 * kk + 1) % 9][2], sacc[(2 * kk + 1) % 9][3]); } else { pw.z = 0u; pw.w = 0u; }
;                 const bf16x8 pf = __builtin_bit_cast(bf16x8, pw);
; #pragma unroll
;                 for (int dt = 0; dt < 4; ++dt) { const LAS bf16_t* vp = Vt + (16 * dt + r) * VT_STR + 16 * (c + 2 * kk) + 4 * q;
;                     u32x4 av; const u32x2 lo = *(const LAS u32x2*)vp; av.x = lo.x; av.y = lo.y;
;                     if (kk < 4) { const u32x2 hi = *(const LAS u32x2*)(vp + 16); av.z = hi.x; av.w = hi.y; } else { av.z = 0u; av.w = 0u; }
;                     o[dt] = __builtin_amdgcn_mfma_f32_16x16x32_bf16(__builtin_bit_cast(bf16x8, av), pf, o[dt], 0, 0, 0); }
;             }
;             bf16_t* yp = Y + (R0 + 16 * c + r) * DM + AW + hq * 64 + 4 * q;
; #pragma unroll
;             for (int dt = 0; dt < 4; ++dt) { u32x2 w; w.x = pk2(o[dt][0] * inv, o[dt][1] * inv); w.y = pk2(o[dt][2] * inv, o[dt][3] * inv); *(u32x2*)(yp + 16 * dt) = w; }
;         }
	v_mfma_f32_16x16x32_bf16 v[28:31], v[152:155], v[32:35], v[28:31]
	ds_read2_b64 v[32:35], v164 offset0:52 offset1:56
	s_waitcnt lgkmcnt(0)
	v_mfma_f32_16x16x32_bf16 v[40:43], v[32:35], v[132:135], v[36:39]
	ds_read2_b64 v[32:35], v165 offset0:84 offset1:88
	s_waitcnt lgkmcnt(0)
	v_mfma_f32_16x16x32_bf16 v[36:39], v[32:35], v[132:135], v[144:147]
	ds_read2_b64 v[32:35], v166 offset0:116 offset1:120
	s_nop 1
	ds_read2_b64 v[144:147], v167 offset0:52 offset1:56
	v_cvt_pk_bf16_f32 v0, v137, v140
	s_waitcnt lgkmcnt(1)
	v_mfma_f32_16x16x32_bf16 v[32:35], v[32:35], v[132:135], v[148:151]
	v_cvt_pk_bf16_f32 v1, v141, v143
	s_waitcnt lgkmcnt(0)
	v_mfma_f32_16x16x32_bf16 v[28:31], v[144:147], v[132:135], v[28:31]
	ds_read_b64 v[132:133], v164 offset:480
	v_mov_b32_e32 v134, v3
	v_mov_b32_e32 v135, v3
	s_waitcnt lgkmcnt(0)
	s_nop 0
	v_mfma_f32_16x16x32_bf16 v[40:43], v[132:135], v[0:3], v[40:43]
	ds_read_b64 v[132:133], v164 offset:8928
	s_waitcnt lgkmcnt(0)
	v_mfma_f32_16x16x32_bf16 v[36:39], v[132:135], v[0:3], v[36:39]
	ds_read_b64 v[132:133], v164 offset:17376
	s_waitcnt lgkmcnt(0)
	v_mfma_f32_16x16x32_bf16 v[32:35], v[132:135], v[0:3], v[32:35]
	ds_read_b64 v[132:133], v167 offset:480
	s_waitcnt lgkmcnt(0)
	v_mfma_f32_16x16x32_bf16 v[28:31], v[132:135], v[0:3], v[28:31]
	v_div_scale_f32 v0, s[36:37], v130, v130, 1.0
	v_rcp_f32_e32 v1, v0
	s_mov_b64 s[36:37], 0x13100800
	v_fma_f32 v2, -v0, v1, 1.0
	v_fmac_f32_e32 v1, v2, v1
	v_div_scale_f32 v2, vcc, 1.0, v130, 1.0
	v_mul_f32_e32 v131, v2, v1
	v_fma_f32 v132, -v0, v131, v2
	v_fmac_f32_e32 v131, v132, v1
	v_fma_f32 v0, -v0, v131, v2
	v_div_fmas_f32 v0, v0, v1, v131
	v_div_fixup_f32 v132, v0, v130, 1.0
	v_or_b32_e32 v1, s49, v93
	v_or_b32_e32 v0, s48, v92
	v_lshlrev_b64 v[0:1], 12, v[0:1]
	v_lshl_add_u64 v[0:1], s[86:87], 0, v[0:1]
	v_lshl_add_u64 v[0:1], v[54:55], 1, v[0:1]
	v_lshlrev_b32_e32 v2, 1, v86
	v_lshl_add_u64 v[0:1], v[0:1], 0, v[2:3]
	v_lshl_add_u64 v[130:131], v[0:1], 0, s[36:37]
	v_mul_f32_e32 v40, v132, v40
	v_mul_f32_e32 v41, v132, v41
	v_add_co_u32_e32 v0, vcc, s3, v0
	v_cvt_pk_bf16_f32 v40, v40, v41
	v_mul_f32_e32 v41, v132, v42
	s_nop 0
	v_addc_co_u32_e32 v1, vcc, 0, v1, vcc
	v_mul_f32_e32 v42, v132, v43
	v_cvt_pk_bf16_f32 v41, v41, v42
	global_store_dwordx2 v[0:1], v[40:41], off offset:2048
	v_mul_f32_e32 v0, v132, v36
	v_mul_f32_e32 v1, v132, v37
	v_cvt_pk_bf16_f32 v0, v0, v1
	v_mul_f32_e32 v1, v132, v38
	v_mul_f32_e32 v36, v132, v39
	v_cvt_pk_bf16_f32 v1, v1, v36
	global_store_dwordx2 v[130:131], v[0:1], off offset:32
	v_mul_f32_e32 v0, v132, v32
	v_mul_f32_e32 v1, v132, v33
	v_cvt_pk_bf16_f32 v0, v0, v1
	v_mul_f32_e32 v1, v132, v34
	v_mul_f32_e32 v32, v132, v35
	v_cvt_pk_bf16_f32 v1, v1, v32
	global_store_dwordx2 v[130:131], v[0:1], off offset:64
	v_mul_f32_e32 v0, v132, v28
	v_mul_f32_e32 v1, v132, v29
	v_cvt_pk_bf16_f32 v0, v0, v1
	v_mul_f32_e32 v1, v132, v30
	v_mul_f32_e32 v28, v132, v31
	v_cvt_pk_bf16_f32 v1, v1, v28
	s_mov_b64 s[36:37], 0x1a000
	s_waitcnt vmcnt(4)
	v_mov_b64_e32 v[34:35], v[26:27]
	s_waitcnt vmcnt(3)
	v_mov_b64_e32 v[30:31], v[22:23]
	global_store_dwordx2 v[130:131], v[0:1], off offset:96
	v_lshl_add_u64 v[92:93], v[92:93], 0, 16
	v_lshl_add_u64 v[90:91], v[90:91], 0, s[36:37]
	v_mov_b32_e32 v0, v129
	v_mov_b64_e32 v[32:33], v[24:25]
	v_mov_b64_e32 v[28:29], v[20:21]
	s_cbranch_scc0 .LBB0_141
	v_lshlrev_b32_e32 v28, 16, v24
	v_and_b32_e32 v24, 0xffff0000, v24
	v_mul_f32_e32 v37, v24, v24
	v_lshlrev_b32_e32 v29, 16, v25
	v_fmac_f32_e32 v37, v28, v28
	v_and_b32_e32 v25, 0xffff0000, v25
	v_fmac_f32_e32 v37, v29, v29
	v_lshlrev_b32_e32 v30, 16, v26
	v_fmac_f32_e32 v37, v25, v25
	v_and_b32_e32 v26, 0xffff0000, v26
	v_fmac_f32_e32 v37, v30, v30
	v_lshlrev_b32_e32 v31, 16, v27
	v_fmac_f32_e32 v37, v26, v26
	v_and_b32_e32 v27, 0xffff0000, v27
	v_fmac_f32_e32 v37, v31, v31
	v_lshlrev_b32_e32 v32, 16, v20
	v_fmac_f32_e32 v37, v27, v27
	v_and_b32_e32 v33, 0xffff0000, v20
	v_fmac_f32_e32 v37, v32, v32
	v_lshlrev_b32_e32 v34, 16, v21
	v_fmac_f32_e32 v37, v33, v33
	v_and_b32_e32 v35, 0xffff0000, v21
	v_fmac_f32_e32 v37, v34, v34
	v_lshlrev_b32_e32 v36, 16, v22
	v_fmac_f32_e32 v37, v35, v35
	v_and_b32_e32 v22, 0xffff0000, v22
	v_fmac_f32_e32 v37, v36, v36
	v_and_b32_e32 v0, 0xffff0000, v23
	v_lshlrev_b32_e32 v1, 16, v23
	v_fmac_f32_e32 v37, v22, v22
	v_pk_mul_f32 v[20:21], v[0:1], v[0:1]
	s_mov_b32 s3, 0x13170000
	v_add_f32_e32 v21, v21, v37
	v_add_f32_e32 v20, v20, v21
	ds_bpermute_b32 v21, v94, v20
	s_add_i32 s5, s5, s38
	s_xor_b64 s[96:97], s[96:97], s[98:99]
	s_cmpk_gt_i32 s5, 0x1ff
	s_waitcnt lgkmcnt(0)
	v_add_f32_e32 v20, v20, v21
	ds_bpermute_b32 v21, v95, v20
	s_waitcnt lgkmcnt(0)
; #define LAS __attribute__((address_space(3)))
; __device__ __forceinline__ unsigned pk2(float lo, float hi) { return pg8::cvt_pk_bf16(lo, hi); }
; __device__ __forceinline__ void attn_phase(KA a, LAS unsigned char* lds, int bid, int nblk, int tid, int wid, int lane) {
;     ...
;             const float rstd = 1.0f / sqrtf(ss * (1.0f / 64.0f) + EPS);
;             bf16x8 qf[2];
; #pragma unroll
;             for (int ks = 0; ks < 2; ++ks) { u32x4 o; o.x = pk2(qv[ks][0] * rstd * gq[ks][0], qv[ks][1] * rstd * gq[ks][1]); o.y = pk2(qv[ks][2] * rstd * gq[ks][2], qv[ks][3] * rstd * gq[ks][3]);
;                 o.z = pk2(qv[ks][4] * rstd * gq[ks][4], qv[ks][5] * rstd * gq[ks][5]); o.w = pk2(qv[ks][6] * rstd * gq[ks][6], qv[ks][7] * rstd * gq[ks][7]); qf[ks] = __builtin_bit_cast(bf16x8, o); }
;             f32x4 sacc[9];
; #pragma unroll
;             for (int t = 0; t < 9; ++t) { sacc[t] = (f32x4){0.f, 0.f, 0.f, 0.f};
; #pragma unroll
;                 for (int ks = 0; ks < 2; ++ks) { const bf16x8 kf = *(const LAS bf16x8*)(Kl + (16 * (c + t) + r) * KL_STR + 32 * ks + 8 * q);
;                     sacc[t] = __builtin_amdgcn_mfma_f32_16x16x32_bf16(kf, qf[ks], sacc[t], 0, 0, 0); } }
;             float mx = sink2;
; #pragma unroll
;             for (int t = 0; t < 9; ++t) { const bool dead = (nb == 0) && (c + t < 8);
; #pragma unroll
;                 for (int e = 0; e < 4; ++e) { float s = sacc[t][e] * SC + breg[t][e]; s = dead ? NEG : s; sacc[t][e] = s; mx = fmaxf(mx, s); } }
	v_add_f32_e32 v20, v20, v21
	v_fmamk_f32 v20, v20, 0x3c800000, v233
	v_cmp_gt_f32_e32 vcc, s33, v20
	v_mul_f32_e32 v21, 0x4f800000, v20
	s_nop 0
	v_cndmask_b32_e32 v20, v20, v21, vcc
	v_sqrt_f32_e32 v21, v20
	s_nop 0
	v_add_u32_e32 v23, -1, v21
	v_fma_f32 v37, -v23, v21, v20
	v_cmp_ge_f32_e64 s[36:37], 0, v37
	v_add_u32_e32 v37, 1, v21
	s_nop 0
	v_cndmask_b32_e64 v23, v21, v23, s[36:37]
	v_fma_f32 v21, -v37, v21, v20
	v_cmp_lt_f32_e64 s[36:37], 0, v21
	s_nop 1
	v_cndmask_b32_e64 v21, v23, v37, s[36:37]
	v_mul_f32_e32 v23, 0x37800000, v21
	v_cndmask_b32_e32 v21, v21, v23, vcc
	v_cmp_class_f32_e32 vcc, v20, v234
	s_nop 1
	v_cndmask_b32_e32 v20, v21, v20, vcc
	v_div_scale_f32 v21, s[36:37], v20, v20, 1.0
	v_rcp_f32_e32 v23, v21
	s_nop 0
	v_fma_f32 v37, -v21, v23, 1.0
	v_fmac_f32_e32 v23, v37, v23
	v_div_scale_f32 v37, vcc, 1.0, v20, 1.0
	v_mul_f32_e32 v38, v37, v23
	v_fma_f32 v39, -v21, v38, v37
	v_fmac_f32_e32 v38, v39, v23
	v_fma_f32 v21, -v21, v38, v37
	v_div_fmas_f32 v21, v21, v23, v38
	v_div_fixup_f32 v20, v21, v20, 1.0
	v_mul_f32_e32 v21, v20, v28
	v_mul_f32_e32 v16, v16, v21
	v_mul_f32_e32 v21, v20, v24
	v_mul_f32_e32 v17, v17, v21
	v_cvt_pk_bf16_f32 v16, v16, v17
	v_mul_f32_e32 v17, v20, v29
	v_mul_f32_e32 v17, v18, v17
	v_mul_f32_e32 v18, v20, v25
	v_mul_f32_e32 v18, v19, v18
	v_cvt_pk_bf16_f32 v17, v17, v18
	v_mul_f32_e32 v18, v20, v30
	v_mul_f32_e32 v12, v12, v18
	v_mul_f32_e32 v18, v20, v26
	v_mul_f32_e32 v13, v13, v18
	v_cvt_pk_bf16_f32 v18, v12, v13
	v_mul_f32_e32 v12, v20, v31
	v_mul_f32_e32 v12, v14, v12
	v_mul_f32_e32 v13, v20, v27
	v_mul_f32_e32 v13, v15, v13
	v_cvt_pk_bf16_f32 v19, v12, v13
	v_mul_f32_e32 v12, v20, v32
	v_mul_f32_e32 v8, v8, v12
	v_mul_f32_e32 v12, v20, v33
	v_mul_f32_e32 v9, v9, v12
	v_cvt_pk_bf16_f32 v8, v8, v9
	v_mul_f32_e32 v9, v20, v34
	v_mul_f32_e32 v9, v10, v9
	v_mul_f32_e32 v10, v20, v35
	v_mul_f32_e32 v10, v11, v10
	v_cvt_pk_bf16_f32 v9, v9, v10
	v_mul_f32_e32 v10, v20, v36
	v_mul_f32_e32 v4, v4, v10
	v_mul_f32_e32 v10, v20, v22
	v_mul_f32_e32 v5, v5, v10
	v_mul_f32_e32 v1, v20, v1
	v_mul_f32_e32 v0, v20, v0
	v_cvt_pk_bf16_f32 v10, v4, v5
	v_mul_f32_e32 v1, v6, v1
	v_mul_f32_e32 v0, v7, v0
	v_cvt_pk_bf16_f32 v11, v1, v0
	ds_read_b128 v[4:7], v117
	ds_read_b128 v[12:15], v117 offset:64
	s_waitcnt lgkmcnt(1)
	v_mfma_f32_16x16x32_bf16 v[4:7], v[4:7], v[16:19], 0
	ds_read_b128 v[20:23], v118 offset:64
	v_add_u32_e32 v0, v89, v107
	ds_read_b128 v[24:27], v0 offset:20800
	s_waitcnt lgkmcnt(2)
	v_mfma_f32_16x16x32_bf16 v[4:7], v[12:15], v[8:11], v[4:7]
	ds_read_b128 v[12:15], v118
	ds_read_b128 v[28:31], v0 offset:23104
	ds_read_b128 v[32:35], v119 offset:64
	s_waitcnt lgkmcnt(2)
	v_mfma_f32_16x16x32_bf16 v[12:15], v[12:15], v[16:19], 0
	ds_read_b128 v[36:39], v0 offset:27712
	s_nop 1
	v_fmac_f32_e32 v126, 0x3e38aa3b, v4
	v_fmac_f32_e32 v125, 0x3e38aa3b, v5
	v_mfma_f32_16x16x32_bf16 v[12:15], v[20:23], v[8:11], v[12:15]
	ds_read_b128 v[20:23], v0 offset:20736
	ds_read_b128 v[40:43], v0 offset:30016
	v_cndmask_b32_e64 v1, v125, v243, s[30:31]
	s_waitcnt lgkmcnt(1)
	v_mfma_f32_16x16x32_bf16 v[20:23], v[20:23], v[16:19], 0
	v_fmac_f32_e32 v128, 0x3e38aa3b, v6
	v_fmac_f32_e32 v127, 0x3e38aa3b, v7
	ds_read_b128 v[90:93], v0 offset:32320
	v_mfma_f32_16x16x32_bf16 v[20:23], v[24:27], v[8:11], v[20:23]
	ds_read_b128 v[24:27], v0 offset:23040
	v_cndmask_b32_e64 v5, v128, v243, s[30:31]
	v_cndmask_b32_e64 v6, v127, v243, s[30:31]
	s_waitcnt lgkmcnt(0)
	v_mfma_f32_16x16x32_bf16 v[24:27], v[24:27], v[16:19], 0
	v_fmamk_f32 v7, v12, 0x3e38aa3b, v83
	v_fmac_f32_e32 v82, 0x3e38aa3b, v13
	v_fmamk_f32 v12, v14, 0x3e38aa3b, v81
	v_mfma_f32_16x16x32_bf16 v[24:27], v[28:31], v[8:11], v[24:27]
	ds_read_b128 v[28:31], v119
	v_fmac_f32_e32 v80, 0x3e38aa3b, v15
	v_fmamk_f32 v13, v20, 0x3e38aa3b, v79
	s_waitcnt lgkmcnt(0)
	v_mfma_f32_16x16x32_bf16 v[28:31], v[28:31], v[16:19], 0
	v_fmac_f32_e32 v78, 0x3e38aa3b, v21
	v_fmamk_f32 v14, v22, 0x3e38aa3b, v77
	v_fmac_f32_e32 v76, 0x3e38aa3b, v23
	v_mfma_f32_16x16x32_bf16 v[28:31], v[32:35], v[8:11], v[28:31]
	ds_read_b128 v[32:35], v0 offset:27648
	v_fmamk_f32 v15, v24, 0x3e38aa3b, v75
	v_fmac_f32_e32 v74, 0x3e38aa3b, v25
	s_waitcnt lgkmcnt(0)
	v_mfma_f32_16x16x32_bf16 v[32:35], v[32:35], v[16:19], 0
	v_fmac_f32_e32 v72, 0x3e38aa3b, v27
	s_nop 1
	v_fmac_f32_e32 v70, 0x3e38aa3b, v29
	v_fmac_f32_e32 v68, 0x3e38aa3b, v31
	v_mfma_f32_16x16x32_bf16 v[32:35], v[36:39], v[8:11], v[32:35]
	ds_read_b128 v[36:39], v0 offset:29952
	s_waitcnt lgkmcnt(0)
	v_mfma_f32_16x16x32_bf16 v[36:39], v[36:39], v[16:19], 0
	s_nop 4
	v_fmac_f32_e32 v66, 0x3e38aa3b, v33
	v_fmamk_f32 v20, v34, 0x3e38aa3b, v65
	v_fmac_f32_e32 v64, 0x3e38aa3b, v35
	v_mfma_f32_16x16x32_bf16 v[36:39], v[40:43], v[8:11], v[36:39]
	ds_read_b128 v[40:43], v0 offset:32256
	v_cndmask_b32_e64 v0, v126, v243, s[30:31]
	v_max3_f32 v4, v124, v0, v1
	s_waitcnt lgkmcnt(0)
	v_mfma_f32_16x16x32_bf16 v[40:43], v[40:43], v[16:19], 0
	v_max3_f32 v4, v4, v5, v6
	v_max3_f32 v4, v4, v7, v82
	v_max3_f32 v4, v4, v12, v80
	v_mfma_f32_16x16x32_bf16 v[40:43], v[90:93], v[8:11], v[40:43]
	ds_read_b128 v[90:93], v120
	v_max3_f32 v4, v4, v13, v78
	v_max3_f32 v4, v4, v14, v76
	s_waitcnt lgkmcnt(0)
	v_mfma_f32_16x16x32_bf16 v[16:19], v[90:93], v[16:19], 0
	ds_read_b128 v[90:93], v120 offset:64
	v_max3_f32 v4, v4, v15, v74
	v_fmamk_f32 v21, v36, 0x3e38aa3b, v63
	s_waitcnt lgkmcnt(0)
; __device__ __forceinline__ void attn_phase(KA a, LAS unsigned char* lds, int bid, int nblk, int tid, int wid, int lane) {
;     ...
;             float mx = sink2;
; #pragma unroll
;             for (int t = 0; t < 9; ++t) { const bool dead = (nb == 0) && (c + t < 8);
; #pragma unroll
;                 for (int e = 0; e < 4; ++e) { float s = sacc[t][e] * SC + breg[t][e]; s = dead ? NEG : s; sacc[t][e] = s; mx = fmaxf(mx, s); } }
;             mx = fmaxf(mx, __shfl_xor(mx, 16)); mx = fmaxf(mx, __shfl_xor(mx, 32));
;             float l = 0.f;
; #pragma unroll
;             for (int t = 0; t < 9; ++t)
; #pragma unroll
;                 for (int e = 0; e < 4; ++e) { const float p = __builtin_amdgcn_exp2f(sacc[t][e] - mx); sacc[t][e] = p; l += p; }
;             l += __shfl_xor(l, 16); l += __shfl_xor(l, 32);
;             l += __builtin_amdgcn_exp2f(sink2 - mx);
;             const float inv = 1.0f / l;
;             f32x4 o[4];
; #pragma unroll
;             for (int dt = 0; dt < 4; ++dt) o[dt] = (f32x4){0.f, 0.f, 0.f, 0.f};
; #pragma unroll
	v_mfma_f32_16x16x32_bf16 v[8:11], v[90:93], v[8:11], v[16:19]
	s_nop 2
	v_fmamk_f32 v16, v26, 0x3e38aa3b, v73
	v_max3_f32 v4, v4, v16, v72
	v_fmamk_f32 v17, v28, 0x3e38aa3b, v71
	v_max3_f32 v4, v4, v17, v70
	v_fmamk_f32 v18, v30, 0x3e38aa3b, v69
	v_max3_f32 v4, v4, v18, v68
	v_fmamk_f32 v19, v32, 0x3e38aa3b, v67
	v_max3_f32 v4, v4, v19, v66
	v_max3_f32 v4, v4, v20, v64
	v_fmac_f32_e32 v62, 0x3e38aa3b, v37
	v_max3_f32 v4, v4, v21, v62
	v_fmamk_f32 v22, v38, 0x3e38aa3b, v61
	v_fmac_f32_e32 v60, 0x3e38aa3b, v39
	v_max3_f32 v4, v4, v22, v60
	v_fmamk_f32 v23, v40, 0x3e38aa3b, v59
	v_fmac_f32_e32 v58, 0x3e38aa3b, v41
	v_max3_f32 v4, v4, v23, v58
	v_fmamk_f32 v24, v42, 0x3e38aa3b, v57
	v_fmac_f32_e32 v56, 0x3e38aa3b, v43
	v_max3_f32 v4, v4, v24, v56
	v_fmac_f32_e32 v121, 0x3e38aa3b, v8
	v_fmac_f32_e32 v51, 0x3e38aa3b, v9
	v_max3_f32 v4, v4, v121, v51
	v_fmac_f32_e32 v123, 0x3e38aa3b, v10
	v_fmac_f32_e32 v122, 0x3e38aa3b, v11
	v_max3_f32 v4, v4, v123, v122
	ds_bpermute_b32 v8, v94, v4
	s_waitcnt lgkmcnt(0)
	v_max_f32_e32 v8, v8, v8
	v_max_f32_e32 v4, v4, v8
	ds_bpermute_b32 v8, v95, v4
	s_waitcnt lgkmcnt(0)
	v_max_f32_e32 v8, v8, v8
	v_max_f32_e32 v8, v4, v8
	v_sub_f32_e32 v0, v0, v8
	v_exp_f32_e32 v9, v0
	v_sub_f32_e32 v1, v1, v8
	v_exp_f32_e32 v10, v1
	v_sub_f32_e32 v1, v5, v8
	v_exp_f32_e32 v11, v1
	v_sub_f32_e32 v1, v6, v8
	v_exp_f32_e32 v25, v1
	v_sub_f32_e32 v1, v7, v8
	v_add_f32_e32 v0, 0, v9
	v_exp_f32_e32 v7, v1
	v_sub_f32_e32 v1, v82, v8
	v_add_f32_e32 v0, v10, v0
	v_exp_f32_e32 v26, v1
	v_sub_f32_e32 v1, v12, v8
	v_add_f32_e32 v0, v11, v0
	v_exp_f32_e32 v12, v1
	v_sub_f32_e32 v1, v80, v8
	v_add_f32_e32 v0, v25, v0
	v_exp_f32_e32 v27, v1
	v_sub_f32_e32 v1, v13, v8
	v_add_f32_e32 v0, v7, v0
	v_exp_f32_e32 v28, v1
	v_sub_f32_e32 v1, v78, v8
	v_add_f32_e32 v0, v26, v0
	v_exp_f32_e32 v29, v1
	v_sub_f32_e32 v1, v14, v8
	v_add_f32_e32 v0, v12, v0
	v_exp_f32_e32 v30, v1
	v_sub_f32_e32 v1, v76, v8
	v_add_f32_e32 v0, v27, v0
	v_exp_f32_e32 v31, v1
	v_sub_f32_e32 v1, v15, v8
	v_add_f32_e32 v0, v28, v0
	v_exp_f32_e32 v32, v1
	v_sub_f32_e32 v1, v74, v8
	v_add_f32_e32 v0, v29, v0
	v_exp_f32_e32 v33, v1
	v_sub_f32_e32 v1, v16, v8
	v_add_f32_e32 v0, v30, v0
	v_exp_f32_e32 v34, v1
	v_sub_f32_e32 v1, v72, v8
	v_add_f32_e32 v0, v31, v0
	v_exp_f32_e32 v35, v1
	v_sub_f32_e32 v1, v17, v8
	v_add_f32_e32 v0, v32, v0
	v_exp_f32_e32 v36, v1
	v_sub_f32_e32 v1, v70, v8
	v_add_f32_e32 v0, v33, v0
	v_exp_f32_e32 v37, v1
	v_sub_f32_e32 v1, v18, v8
	v_add_f32_e32 v0, v34, v0
	v_exp_f32_e32 v38, v1
	v_sub_f32_e32 v1, v68, v8
	v_add_f32_e32 v0, v35, v0
	v_exp_f32_e32 v39, v1
	v_sub_f32_e32 v1, v19, v8
	v_add_f32_e32 v0, v36, v0
	v_exp_f32_e32 v40, v1
	v_sub_f32_e32 v1, v66, v8
	v_add_f32_e32 v0, v37, v0
	v_exp_f32_e32 v41, v1
	v_sub_f32_e32 v1, v20, v8
	v_add_f32_e32 v0, v38, v0
	v_exp_f32_e32 v42, v1
	v_sub_f32_e32 v1, v64, v8
	v_add_f32_e32 v0, v39, v0
	v_exp_f32_e32 v43, v1
	v_sub_f32_e32 v1, v21, v8
	v_add_f32_e32 v0, v40, v0
	v_exp_f32_e32 v57, v1
	v_sub_f32_e32 v1, v62, v8
	v_add_f32_e32 v0, v41, v0
	v_exp_f32_e32 v59, v1
	v_sub_f32_e32 v1, v22, v8
	v_add_f32_e32 v0, v42, v0
	v_exp_f32_e32 v61, v1
	v_sub_f32_e32 v1, v60, v8
	v_add_f32_e32 v0, v43, v0
	v_exp_f32_e32 v60, v1
	v_sub_f32_e32 v1, v23, v8
	v_add_f32_e32 v0, v57, v0
	v_exp_f32_e32 v62, v1
	v_sub_f32_e32 v1, v58, v8
	v_add_f32_e32 v0, v59, v0
	v_exp_f32_e32 v58, v1
	v_sub_f32_e32 v1, v24, v8
	v_add_f32_e32 v0, v61, v0
	v_exp_f32_e32 v63, v1
	v_sub_f32_e32 v1, v56, v8
	v_add_f32_e32 v0, v60, v0
	v_exp_f32_e32 v56, v1
	v_sub_f32_e32 v1, v121, v8
	v_add_f32_e32 v0, v62, v0
	v_exp_f32_e32 v1, v1
	v_sub_f32_e32 v4, v51, v8
	v_add_f32_e32 v0, v58, v0
	v_exp_f32_e32 v4, v4
	v_sub_f32_e32 v5, v123, v8
	v_add_f32_e32 v0, v63, v0
	v_exp_f32_e32 v5, v5
	v_sub_f32_e32 v6, v122, v8
	v_add_f32_e32 v0, v56, v0
	v_exp_f32_e32 v6, v6
	v_add_f32_e32 v0, v1, v0
	v_add_f32_e32 v0, v4, v0
	v_add_f32_e32 v0, v5, v0
	v_add_f32_e32 v0, v6, v0
	ds_bpermute_b32 v13, v94, v0
	v_sub_f32_e32 v8, v124, v8
	v_exp_f32_e32 v8, v8
	v_add_u32_e32 v51, v96, v106
	v_add_u32_e32 v66, v96, v97
	s_waitcnt lgkmcnt(0)
	v_add_f32_e32 v0, v0, v13
	ds_bpermute_b32 v13, v95, v0
	v_add_u32_e32 v64, 0xb000, v51
	v_add_u32_e32 v65, 0xd000, v51
	v_add_u32_e32 v67, 0x9000, v66
	s_waitcnt lgkmcnt(0)
	v_add_f32_e32 v0, v0, v13
	v_add_f32_e32 v0, v8, v0
	v_cvt_pk_bf16_f32 v8, v9, v10
	v_cvt_pk_bf16_f32 v9, v11, v25
	v_cvt_pk_bf16_f32 v10, v7, v26
	v_add_u32_e32 v7, 0x9000, v51
	v_cvt_pk_bf16_f32 v11, v12, v27
	ds_read2_b64 v[12:15], v7 offset0:28 offset1:32
	ds_read2_b64 v[16:19], v64 offset0:60 offset1:64
	ds_read2_b64 v[20:23], v65 offset0:92 offset1:96
	ds_read2_b64 v[24:27], v67 offset0:28 offset1:32
	s_waitcnt lgkmcnt(3)
; #define LAS __attribute__((address_space(3)))
; __device__ __forceinline__ unsigned pk2(float lo, float hi) { return pg8::cvt_pk_bf16(lo, hi); }
; __device__ __forceinline__ void attn_phase(KA a, LAS unsigned char* lds, int bid, int nblk, int tid, int wid, int lane) {
;     ...
; #pragma unroll
;             for (int kk = 0; kk < 5; ++kk) {
;                 u32x4 pw; pw.x = pk2(sacc[2 * kk][0], sacc[2 * kk][1]); pw.y = pk2(sacc[2 * kk][2], sacc[2 * kk][3]);
;                 if (kk < 4) { pw.z = pk2(sacc[(2 * kk + 1) % 9][0], sacc[(2 * kk + 1) % 9][1]); pw.w = pk2(sacc[(2 * kk + 1) % 9][2], sacc[(2 * kk + 1) % 9][3]); } else { pw.z = 0u; pw.w = 0u; }
;                 const bf16x8 pf = __builtin_bit_cast(bf16x8, pw);
; #pragma unroll
;                 for (int dt = 0; dt < 4; ++dt) { const LAS bf16_t* vp = Vt + (16 * dt + r) * VT_STR + 16 * (c + 2 * kk) + 4 * q;
;                     u32x4 av; const u32x2 lo = *(const LAS u32x2*)vp; av.x = lo.x; av.y = lo.y;
;                     if (kk < 4) { const u32x2 hi = *(const LAS u32x2*)(vp + 16); av.z = hi.x; av.w = hi.y; } else { av.z = 0u; av.w = 0u; }
;                     o[dt] = __builtin_amdgcn_mfma_f32_16x16x32_bf16(__builtin_bit_cast(bf16x8, av), pf, o[dt], 0, 0, 0); }
;             }
;             bf16_t* yp = Y + (R0 + 16 * c + r) * DM + AW + hq * 64 + 4 * q;
; #pragma unroll
;             for (int dt = 0; dt < 4; ++dt) { u32x2 w; w.x = pk2(o[dt][0] * inv, o[dt][1] * inv); w.y = pk2(o[dt][2] * inv, o[dt][3] * inv); *(u32x2*)(yp + 16 * dt) = w; }
;         }
	v_mfma_f32_16x16x32_bf16 v[12:15], v[12:15], v[8:11], 0
	s_waitcnt lgkmcnt(2)
	v_mfma_f32_16x16x32_bf16 v[16:19], v[16:19], v[8:11], 0
	s_waitcnt lgkmcnt(1)
	v_mfma_f32_16x16x32_bf16 v[20:23], v[20:23], v[8:11], 0
	s_waitcnt lgkmcnt(0)
	v_mfma_f32_16x16x32_bf16 v[8:11], v[24:27], v[8:11], 0
	v_cvt_pk_bf16_f32 v24, v28, v29
	v_cvt_pk_bf16_f32 v25, v30, v31
	v_cvt_pk_bf16_f32 v26, v32, v33
	v_cvt_pk_bf16_f32 v27, v34, v35
	ds_read2_b64 v[28:31], v7 offset0:36 offset1:40
	s_waitcnt lgkmcnt(0)
	v_mfma_f32_16x16x32_bf16 v[12:15], v[28:31], v[24:27], v[12:15]
	ds_read2_b64 v[28:31], v64 offset0:68 offset1:72
	s_waitcnt lgkmcnt(0)
	v_mfma_f32_16x16x32_bf16 v[16:19], v[28:31], v[24:27], v[16:19]
	ds_read2_b64 v[28:31], v65 offset0:100 offset1:104
	s_waitcnt lgkmcnt(0)
	v_mfma_f32_16x16x32_bf16 v[20:23], v[28:31], v[24:27], v[20:23]
	ds_read2_b64 v[28:31], v67 offset0:36 offset1:40
	s_waitcnt lgkmcnt(0)
	v_mfma_f32_16x16x32_bf16 v[8:11], v[28:31], v[24:27], v[8:11]
	v_cvt_pk_bf16_f32 v24, v36, v37
	v_cvt_pk_bf16_f32 v25, v38, v39
	v_cvt_pk_bf16_f32 v26, v40, v41
	v_cvt_pk_bf16_f32 v27, v42, v43
	ds_read2_b64 v[28:31], v7 offset0:44 offset1:48
	s_waitcnt lgkmcnt(0)
	v_mfma_f32_16x16x32_bf16 v[12:15], v[28:31], v[24:27], v[12:15]
	ds_read2_b64 v[28:31], v64 offset0:76 offset1:80
	s_waitcnt lgkmcnt(0)
	v_mfma_f32_16x16x32_bf16 v[16:19], v[28:31], v[24:27], v[16:19]
	ds_read2_b64 v[28:31], v65 offset0:108 offset1:112
	s_waitcnt lgkmcnt(0)
	v_mfma_f32_16x16x32_bf16 v[20:23], v[28:31], v[24:27], v[20:23]
	ds_read2_b64 v[28:31], v67 offset0:44 offset1:48
	s_waitcnt lgkmcnt(0)
	v_mfma_f32_16x16x32_bf16 v[8:11], v[28:31], v[24:27], v[8:11]
	v_cvt_pk_bf16_f32 v24, v57, v59
	v_cvt_pk_bf16_f32 v25, v61, v60
	v_cvt_pk_bf16_f32 v26, v62, v58
	v_cvt_pk_bf16_f32 v27, v63, v56
	ds_read2_b64 v[28:31], v7 offset0:52 offset1:56
	s_waitcnt lgkmcnt(0)
	v_mfma_f32_16x16x32_bf16 v[12:15], v[28:31], v[24:27], v[12:15]
	ds_read2_b64 v[28:31], v64 offset0:84 offset1:88
	v_mov_b32_e32 v7, v3
	s_waitcnt lgkmcnt(0)
	v_mfma_f32_16x16x32_bf16 v[16:19], v[28:31], v[24:27], v[16:19]
	ds_read2_b64 v[28:31], v65 offset0:116 offset1:120
	s_waitcnt lgkmcnt(0)
	v_mfma_f32_16x16x32_bf16 v[20:23], v[28:31], v[24:27], v[20:23]
	ds_read2_b64 v[28:31], v67 offset0:52 offset1:56
	v_cvt_pk_bf16_f32 v4, v1, v4
	v_cvt_pk_bf16_f32 v5, v5, v6
	s_waitcnt lgkmcnt(0)
	v_mfma_f32_16x16x32_bf16 v[8:11], v[28:31], v[24:27], v[8:11]
	ds_read_b64 v[24:25], v51 offset:37344
	v_mov_b32_e32 v26, v3
	v_mov_b32_e32 v27, v3
	v_mov_b32_e32 v6, v3
	v_div_scale_f32 v1, s[30:31], v0, v0, 1.0
	s_waitcnt lgkmcnt(0)
	v_mfma_f32_16x16x32_bf16 v[12:15], v[24:27], v[4:7], v[12:15]
	ds_read_b64 v[24:25], v51 offset:45792
	s_mov_b64 s[30:31], 0x13170800
	s_waitcnt lgkmcnt(0)
	v_mfma_f32_16x16x32_bf16 v[16:19], v[24:27], v[4:7], v[16:19]
	ds_read_b64 v[24:25], v51 offset:54240
	s_waitcnt lgkmcnt(0)
	v_mfma_f32_16x16x32_bf16 v[20:23], v[24:27], v[4:7], v[20:23]
	ds_read_b64 v[24:25], v66 offset:37344
	s_waitcnt lgkmcnt(0)
	v_mfma_f32_16x16x32_bf16 v[4:7], v[24:27], v[4:7], v[8:11]
	s_nop 2
	v_rcp_f32_e32 v8, v1
	s_nop 0
	v_fma_f32 v9, -v1, v8, 1.0
	v_fmac_f32_e32 v8, v9, v8
	v_div_scale_f32 v9, vcc, 1.0, v0, 1.0
	v_mul_f32_e32 v10, v9, v8
	v_fma_f32 v11, -v1, v10, v9
	v_fmac_f32_e32 v10, v11, v8
	v_fma_f32 v1, -v1, v10, v9
	v_div_fmas_f32 v1, v1, v8, v10
	v_div_fixup_f32 v24, v1, v0, 1.0
	v_lshlrev_b64 v[0:1], 12, v[52:53]
	v_lshl_add_u64 v[0:1], s[86:87], 0, v[0:1]
	v_lshl_add_u64 v[0:1], v[54:55], 1, v[0:1]
	v_lshl_add_u64 v[0:1], v[0:1], 0, v[2:3]
	v_lshl_add_u64 v[8:9], v[0:1], 0, s[30:31]
	v_add_co_u32_e32 v0, vcc, s3, v0
	v_mul_f32_e32 v2, v24, v12
	v_mul_f32_e32 v10, v24, v13
	v_mul_f32_e32 v11, v24, v15
	v_addc_co_u32_e32 v1, vcc, 0, v1, vcc
	v_cvt_pk_bf16_f32 v10, v2, v10
	v_mul_f32_e32 v2, v24, v14
	v_cvt_pk_bf16_f32 v11, v2, v11
	global_store_dwordx2 v[0:1], v[10:11], off offset:2048
	v_mul_f32_e32 v0, v24, v16
	v_mul_f32_e32 v1, v24, v17
	v_cvt_pk_bf16_f32 v0, v0, v1
	v_mul_f32_e32 v1, v24, v18
	v_mul_f32_e32 v2, v24, v19
	v_cvt_pk_bf16_f32 v1, v1, v2
	global_store_dwordx2 v[8:9], v[0:1], off offset:32
	v_mul_f32_e32 v0, v24, v20
	v_mul_f32_e32 v1, v24, v21
	v_cvt_pk_bf16_f32 v0, v0, v1
	v_mul_f32_e32 v1, v24, v22
	v_mul_f32_e32 v2, v24, v23
	v_cvt_pk_bf16_f32 v1, v1, v2
	global_store_dwordx2 v[8:9], v[0:1], off offset:64
	v_mul_f32_e32 v0, v24, v4
	v_mul_f32_e32 v1, v24, v5
	v_cvt_pk_bf16_f32 v0, v0, v1
	v_mul_f32_e32 v1, v24, v6
	v_mul_f32_e32 v2, v24, v7
	v_cvt_pk_bf16_f32 v1, v1, v2
	global_store_dwordx2 v[8:9], v[0:1], off offset:96
	s_cbranch_scc0 .LBB0_109

; #define LAS __attribute__((address_space(3)))
; #define LDS_WAIT() asm volatile("s_waitcnt lgkmcnt(0)" ::: "memory")
; __device__ __forceinline__ void conv_item(const float* W, int K, int N, bf16_t* WT, int kb, int n0, int dst_row0, LAS float* scr, int lane) {
;     const int k0 = 64 * kb;
; #pragma unroll 8
;     for (int i = 0; i < 32; ++i) { const int kk = 2 * i + (lane >> 5); scr[kk * 33 + (lane & 31)] = __builtin_nontemporal_load(W + (size_t)(k0 + kk) * N + n0 + (lane & 31)); }
;     LDS_WAIT(); asm volatile("" ::: "memory");
.LBB0_369:
	v_add_u32_e32 v7, s7, v16
	v_add_u32_e32 v2, 0xfb780000, v7
	v_lshl_add_u64 v[8:9], v[2:3], 2, v[4:5]
	v_add_u32_e32 v2, 0xfb781000, v7
	v_lshl_add_u64 v[10:11], v[2:3], 2, v[4:5]
	v_add_u32_e32 v2, 0xfb782000, v7
	global_load_dword v138, v[8:9], off nt
	global_load_dword v139, v[10:11], off nt
	v_lshl_add_u64 v[8:9], v[2:3], 2, v[4:5]
	v_add_u32_e32 v2, 0xfb783000, v7
	v_lshl_add_u64 v[10:11], v[2:3], 2, v[4:5]
	v_add_u32_e32 v2, 0xfb784000, v7
	global_load_dword v140, v[8:9], off nt
	global_load_dword v141, v[10:11], off nt
	v_lshl_add_u64 v[8:9], v[2:3], 2, v[4:5]
	v_add_u32_e32 v2, 0xfb785000, v7
	v_lshl_add_u64 v[10:11], v[2:3], 2, v[4:5]
	v_add_u32_e32 v2, 0xfb786000, v7
	global_load_dword v142, v[8:9], off nt
	global_load_dword v143, v[10:11], off nt
	v_lshl_add_u64 v[8:9], v[2:3], 2, v[4:5]
	v_add_u32_e32 v2, 0xfb787000, v7
	v_lshl_add_u64 v[10:11], v[2:3], 2, v[4:5]
	global_load_dword v144, v[8:9], off nt
	global_load_dword v145, v[10:11], off nt
	s_add_i32 s7, s7, 0x8000
	v_add_u32_e32 v7, s7, v16
	v_add_u32_e32 v2, 0xfb780000, v7
	v_lshl_add_u64 v[8:9], v[2:3], 2, v[4:5]
	v_add_u32_e32 v2, 0xfb781000, v7
	v_lshl_add_u64 v[10:11], v[2:3], 2, v[4:5]
	v_add_u32_e32 v2, 0xfb782000, v7
	global_load_dword v146, v[8:9], off nt
	global_load_dword v147, v[10:11], off nt
	v_lshl_add_u64 v[8:9], v[2:3], 2, v[4:5]
	v_add_u32_e32 v2, 0xfb783000, v7
	v_lshl_add_u64 v[10:11], v[2:3], 2, v[4:5]
	v_add_u32_e32 v2, 0xfb784000, v7
	global_load_dword v148, v[8:9], off nt
	global_load_dword v149, v[10:11], off nt
	v_lshl_add_u64 v[8:9], v[2:3], 2, v[4:5]
	v_add_u32_e32 v2, 0xfb785000, v7
	v_lshl_add_u64 v[10:11], v[2:3], 2, v[4:5]
	v_add_u32_e32 v2, 0xfb786000, v7
	global_load_dword v150, v[8:9], off nt
	global_load_dword v151, v[10:11], off nt
	v_lshl_add_u64 v[8:9], v[2:3], 2, v[4:5]
	v_add_u32_e32 v2, 0xfb787000, v7
	v_lshl_add_u64 v[10:11], v[2:3], 2, v[4:5]
	global_load_dword v152, v[8:9], off nt
	global_load_dword v153, v[10:11], off nt
	s_add_i32 s7, s7, 0x8000
	v_add_u32_e32 v7, s7, v16
	v_add_u32_e32 v2, 0xfb780000, v7
	v_lshl_add_u64 v[8:9], v[2:3], 2, v[4:5]
	v_add_u32_e32 v2, 0xfb781000, v7
	v_lshl_add_u64 v[10:11], v[2:3], 2, v[4:5]
	v_add_u32_e32 v2, 0xfb782000, v7
	global_load_dword v154, v[8:9], off nt
	global_load_dword v155, v[10:11], off nt
	v_lshl_add_u64 v[8:9], v[2:3], 2, v[4:5]
	v_add_u32_e32 v2, 0xfb783000, v7
	v_lshl_add_u64 v[10:11], v[2:3], 2, v[4:5]
	v_add_u32_e32 v2, 0xfb784000, v7
	global_load_dword v156, v[8:9], off nt
	global_load_dword v157, v[10:11], off nt
	v_lshl_add_u64 v[8:9], v[2:3], 2, v[4:5]
	v_add_u32_e32 v2, 0xfb785000, v7
	v_lshl_add_u64 v[10:11], v[2:3], 2, v[4:5]
	v_add_u32_e32 v2, 0xfb786000, v7
	global_load_dword v158, v[8:9], off nt
	global_load_dword v159, v[10:11], off nt
	v_lshl_add_u64 v[8:9], v[2:3], 2, v[4:5]
	v_add_u32_e32 v2, 0xfb787000, v7
	v_lshl_add_u64 v[10:11], v[2:3], 2, v[4:5]
	global_load_dword v160, v[8:9], off nt
	global_load_dword v161, v[10:11], off nt
	s_add_i32 s7, s7, 0x8000
	v_add_u32_e32 v7, s7, v16
	v_add_u32_e32 v2, 0xfb780000, v7
	v_lshl_add_u64 v[8:9], v[2:3], 2, v[4:5]
	v_add_u32_e32 v2, 0xfb781000, v7
	v_lshl_add_u64 v[10:11], v[2:3], 2, v[4:5]
	v_add_u32_e32 v2, 0xfb782000, v7
	global_load_dword v162, v[8:9], off nt
	global_load_dword v163, v[10:11], off nt
	v_lshl_add_u64 v[8:9], v[2:3], 2, v[4:5]
	v_add_u32_e32 v2, 0xfb783000, v7
	v_lshl_add_u64 v[10:11], v[2:3], 2, v[4:5]
	v_add_u32_e32 v2, 0xfb784000, v7
	global_load_dword v164, v[8:9], off nt
	global_load_dword v165, v[10:11], off nt
	v_lshl_add_u64 v[8:9], v[2:3], 2, v[4:5]
	v_add_u32_e32 v2, 0xfb785000, v7
	v_lshl_add_u64 v[10:11], v[2:3], 2, v[4:5]
	v_add_u32_e32 v2, 0xfb786000, v7
	global_load_dword v166, v[8:9], off nt
	global_load_dword v167, v[10:11], off nt
	v_lshl_add_u64 v[8:9], v[2:3], 2, v[4:5]
	v_add_u32_e32 v2, 0xfb787000, v7
	v_lshl_add_u64 v[10:11], v[2:3], 2, v[4:5]
	global_load_dword v168, v[8:9], off nt
	global_load_dword v169, v[10:11], off nt
	s_add_i32 s7, s7, 0x8000
	v_add_u32_e32 v8, 0x400, v6
	s_waitcnt vmcnt(30)
; #define LAS __attribute__((address_space(3)))
; #define LDS_WAIT() asm volatile("s_waitcnt lgkmcnt(0)" ::: "memory")
; __device__ __forceinline__ unsigned pk2(float lo, float hi) { return pg8::cvt_pk_bf16(lo, hi); }
; __device__ __forceinline__ void conv_item(const float* W, int K, int N, bf16_t* WT, int kb, int n0, int dst_row0, LAS float* scr, int lane) {
;     ...
;     for (int i = 0; i < 32; ++i) { const int kk = 2 * i + (lane >> 5); scr[kk * 33 + (lane & 31)] = __builtin_nontemporal_load(W + (size_t)(k0 + kk) * N + n0 + (lane & 31)); }
;     LDS_WAIT(); asm volatile("" ::: "memory");
;     const int c = lane & 7;
; #pragma unroll
;     for (int j = 0; j < 4; ++j) { const int n = (lane >> 3) + 8 * j; const LAS float* s = scr + (8 * c) * 33 + n;
;         u32x4 o; o.x = pk2(s[0 * 33], s[1 * 33]); o.y = pk2(s[2 * 33], s[3 * 33]); o.z = pk2(s[4 * 33], s[5 * 33]); o.w = pk2(s[6 * 33], s[7 * 33]);
;         *(u32x4*)(WT + (size_t)(dst_row0 + n) * K + k0 + 8 * c) = o; }
;     LDS_WAIT(); asm volatile("" ::: "memory");
	ds_write2_b32 v6, v138, v139 offset1:66
	s_waitcnt vmcnt(28)
	ds_write2_b32 v6, v140, v141 offset0:132 offset1:198
	v_add_u32_e32 v6, 0x840, v6
	s_waitcnt vmcnt(26)
	ds_write2_b32 v8, v142, v143 offset0:8 offset1:74
	s_waitcnt vmcnt(24)
	ds_write2_b32 v8, v144, v145 offset0:140 offset1:206
	v_add_u32_e32 v8, 0x400, v6
	s_waitcnt vmcnt(22)
	ds_write2_b32 v6, v146, v147 offset1:66
	s_waitcnt vmcnt(20)
	ds_write2_b32 v6, v148, v149 offset0:132 offset1:198
	v_add_u32_e32 v6, 0x840, v6
	s_waitcnt vmcnt(18)
	ds_write2_b32 v8, v150, v151 offset0:8 offset1:74
	s_waitcnt vmcnt(16)
	ds_write2_b32 v8, v152, v153 offset0:140 offset1:206
	v_add_u32_e32 v8, 0x400, v6
	s_waitcnt vmcnt(14)
	ds_write2_b32 v6, v154, v155 offset1:66
	s_waitcnt vmcnt(12)
	ds_write2_b32 v6, v156, v157 offset0:132 offset1:198
	v_add_u32_e32 v6, 0x840, v6
	s_waitcnt vmcnt(10)
	ds_write2_b32 v8, v158, v159 offset0:8 offset1:74
	s_waitcnt vmcnt(8)
	ds_write2_b32 v8, v160, v161 offset0:140 offset1:206
	v_add_u32_e32 v8, 0x400, v6
	s_waitcnt vmcnt(6)
	ds_write2_b32 v6, v162, v163 offset1:66
	s_waitcnt vmcnt(4)
	ds_write2_b32 v6, v164, v165 offset0:132 offset1:198
	v_add_u32_e32 v6, 0x840, v6
	s_waitcnt vmcnt(2)
	ds_write2_b32 v8, v166, v167 offset0:8 offset1:74
	s_waitcnt vmcnt(0)
	ds_write2_b32 v8, v168, v169 offset0:140 offset1:206
	s_waitcnt lgkmcnt(0)
	ds_read2_b32 v[170:171], v46 offset1:33
	ds_read2_b32 v[172:173], v46 offset0:66 offset1:99
	ds_read2_b32 v[174:175], v46 offset0:132 offset1:165
	ds_read2_b32 v[176:177], v46 offset0:198 offset1:231
	ds_read2_b32 v[178:179], v46 offset0:8 offset1:41
	ds_read2_b32 v[180:181], v46 offset0:74 offset1:107
	ds_read2_b32 v[182:183], v46 offset0:140 offset1:173
	ds_read2_b32 v[192:193], v46 offset0:206 offset1:239
	ds_read2_b32 v[194:195], v46 offset0:16 offset1:49
	ds_read2_b32 v[196:197], v46 offset0:82 offset1:115
	ds_read2_b32 v[198:199], v46 offset0:148 offset1:181
	ds_read2_b32 v[200:201], v46 offset0:214 offset1:247
	ds_read2_b32 v[202:203], v46 offset0:24 offset1:57
	ds_read2_b32 v[204:205], v46 offset0:90 offset1:123
	ds_read2_b32 v[206:207], v46 offset0:156 offset1:189
	ds_read2_b32 v[208:209], v46 offset0:222 offset1:255
	s_and_b32 s7, s10, 0xffc0
	s_waitcnt lgkmcnt(15)
	v_cvt_pk_bf16_f32 v4, v170, v171
	v_or_b32_e32 v2, s6, v1
	s_add_i32 s44, s7, 0xffff6f00
	s_waitcnt lgkmcnt(14)
	v_cvt_pk_bf16_f32 v5, v172, v173
	v_lshlrev_b32_e32 v2, 12, v2
	v_lshl_add_u64 v[10:11], s[44:45], 1, v[22:23]
	s_waitcnt lgkmcnt(13)
	v_cvt_pk_bf16_f32 v6, v174, v175
	s_waitcnt lgkmcnt(12)
	v_cvt_pk_bf16_f32 v7, v176, v177
	v_lshl_add_u64 v[12:13], v[10:11], 0, v[2:3]
	global_store_dwordx4 v[12:13], v[4:7], off
	v_or_b32_e32 v2, s6, v47
	v_lshlrev_b32_e32 v2, 12, v2
	s_waitcnt lgkmcnt(11)
	v_cvt_pk_bf16_f32 v4, v178, v179
	s_waitcnt lgkmcnt(10)
	v_cvt_pk_bf16_f32 v5, v180, v181
	s_waitcnt lgkmcnt(9)
	v_cvt_pk_bf16_f32 v6, v182, v183
	s_waitcnt lgkmcnt(8)
	v_cvt_pk_bf16_f32 v7, v192, v193
	v_lshl_add_u64 v[12:13], v[10:11], 0, v[2:3]
	global_store_dwordx4 v[12:13], v[4:7], off
	v_or_b32_e32 v2, s6, v48
	v_lshlrev_b32_e32 v2, 12, v2
	s_waitcnt lgkmcnt(7)
	v_cvt_pk_bf16_f32 v4, v194, v195
	s_waitcnt lgkmcnt(6)
	v_cvt_pk_bf16_f32 v5, v196, v197
	s_waitcnt lgkmcnt(5)
	v_cvt_pk_bf16_f32 v6, v198, v199
	s_waitcnt lgkmcnt(4)
	v_cvt_pk_bf16_f32 v7, v200, v201
	v_lshl_add_u64 v[12:13], v[10:11], 0, v[2:3]
	global_store_dwordx4 v[12:13], v[4:7], off
	v_or_b32_e32 v2, s6, v49
	v_lshlrev_b32_e32 v2, 12, v2
	s_waitcnt lgkmcnt(3)
	v_cvt_pk_bf16_f32 v4, v202, v203
	s_waitcnt lgkmcnt(2)
	v_cvt_pk_bf16_f32 v5, v204, v205
	s_waitcnt lgkmcnt(1)
	v_cvt_pk_bf16_f32 v6, v206, v207
	s_waitcnt lgkmcnt(0)
	v_cvt_pk_bf16_f32 v7, v208, v209
	v_lshl_add_u64 v[8:9], v[10:11], 0, v[2:3]
	global_store_dwordx4 v[8:9], v[4:7], off
	s_waitcnt lgkmcnt(0)
	s_mov_b64 s[6:7], 0

; #define LAS __attribute__((address_space(3)))
; #define LDS_WAIT() asm volatile("s_waitcnt lgkmcnt(0)" ::: "memory")
; __device__ __forceinline__ void conv_item(const float* W, int K, int N, bf16_t* WT, int kb, int n0, int dst_row0, LAS float* scr, int lane) {
;     const int k0 = 64 * kb;
; #pragma unroll 8
;     for (int i = 0; i < 32; ++i) { const int kk = 2 * i + (lane >> 5); scr[kk * 33 + (lane & 31)] = __builtin_nontemporal_load(W + (size_t)(k0 + kk) * N + n0 + (lane & 31)); }
;     LDS_WAIT(); asm volatile("" ::: "memory");
.LBB0_373:
	v_lshl_add_u64 v[18:19], v[14:15], 0, s[6:7]
	v_lshl_add_u64 v[42:43], v[12:13], 0, s[6:7]
	global_load_dword v138, v[18:19], off nt
	v_add_co_u32_e32 v18, vcc, 0x6000, v42
	v_lshl_add_u64 v[44:45], v[10:11], 0, s[6:7]
	s_nop 0
	v_addc_co_u32_e32 v19, vcc, 0, v43, vcc
	v_add_co_u32_e32 v68, vcc, 0xd000, v42
	global_load_dword v139, v[18:19], off offset:2048 nt
	s_nop 0
	v_addc_co_u32_e32 v69, vcc, 0, v43, vcc
	v_add_co_u32_e32 v18, vcc, 0x13000, v42
	v_lshl_add_u64 v[62:63], v[8:9], 0, s[6:7]
	s_nop 0
	v_addc_co_u32_e32 v19, vcc, 0, v43, vcc
	v_lshl_add_u64 v[64:65], v[6:7], 0, s[6:7]
	v_lshl_add_u64 v[66:67], v[4:5], 0, s[6:7]
	global_load_dword v140, v[68:69], off nt
	s_nop 0
	global_load_dword v141, v[18:19], off offset:2048 nt
	s_nop 0
	global_load_dword v142, v[44:45], off nt
	global_load_dword v143, v[62:63], off nt
	s_nop 0
	global_load_dword v144, v[64:65], off nt
	global_load_dword v145, v[66:67], off nt
	s_add_u32 s6, s6, 0x34000
	s_addc_u32 s7, s7, 0
	v_lshl_add_u64 v[18:19], v[14:15], 0, s[6:7]
	v_lshl_add_u64 v[42:43], v[12:13], 0, s[6:7]
	global_load_dword v146, v[18:19], off nt
	v_add_co_u32_e32 v18, vcc, 0x6000, v42
	v_lshl_add_u64 v[44:45], v[10:11], 0, s[6:7]
	s_nop 0
	v_addc_co_u32_e32 v19, vcc, 0, v43, vcc
	v_add_co_u32_e32 v68, vcc, 0xd000, v42
	global_load_dword v147, v[18:19], off offset:2048 nt
	s_nop 0
	v_addc_co_u32_e32 v69, vcc, 0, v43, vcc
	v_add_co_u32_e32 v18, vcc, 0x13000, v42
	v_lshl_add_u64 v[62:63], v[8:9], 0, s[6:7]
	s_nop 0
	v_addc_co_u32_e32 v19, vcc, 0, v43, vcc
	v_lshl_add_u64 v[64:65], v[6:7], 0, s[6:7]
	v_lshl_add_u64 v[66:67], v[4:5], 0, s[6:7]
	global_load_dword v148, v[68:69], off nt
	s_nop 0
	global_load_dword v149, v[18:19], off offset:2048 nt
	s_nop 0
	global_load_dword v150, v[44:45], off nt
	global_load_dword v151, v[62:63], off nt
	s_nop 0
	global_load_dword v152, v[64:65], off nt
	global_load_dword v153, v[66:67], off nt
	s_add_u32 s6, s6, 0x34000
	s_addc_u32 s7, s7, 0
	v_lshl_add_u64 v[18:19], v[14:15], 0, s[6:7]
	v_lshl_add_u64 v[42:43], v[12:13], 0, s[6:7]
	global_load_dword v154, v[18:19], off nt
	v_add_co_u32_e32 v18, vcc, 0x6000, v42
	v_lshl_add_u64 v[44:45], v[10:11], 0, s[6:7]
	s_nop 0
	v_addc_co_u32_e32 v19, vcc, 0, v43, vcc
	v_add_co_u32_e32 v68, vcc, 0xd000, v42
	global_load_dword v155, v[18:19], off offset:2048 nt
	s_nop 0
	v_addc_co_u32_e32 v69, vcc, 0, v43, vcc
	v_add_co_u32_e32 v18, vcc, 0x13000, v42
	v_lshl_add_u64 v[62:63], v[8:9], 0, s[6:7]
	s_nop 0
	v_addc_co_u32_e32 v19, vcc, 0, v43, vcc
	v_lshl_add_u64 v[64:65], v[6:7], 0, s[6:7]
	v_lshl_add_u64 v[66:67], v[4:5], 0, s[6:7]
	global_load_dword v156, v[68:69], off nt
	s_nop 0
	global_load_dword v157, v[18:19], off offset:2048 nt
	s_nop 0
	global_load_dword v158, v[44:45], off nt
	global_load_dword v159, v[62:63], off nt
	s_nop 0
	global_load_dword v160, v[64:65], off nt
	global_load_dword v161, v[66:67], off nt
	s_add_u32 s6, s6, 0x34000
	s_addc_u32 s7, s7, 0
	v_lshl_add_u64 v[18:19], v[14:15], 0, s[6:7]
	v_lshl_add_u64 v[42:43], v[12:13], 0, s[6:7]
	global_load_dword v162, v[18:19], off nt
	v_add_co_u32_e32 v18, vcc, 0x6000, v42
	v_lshl_add_u64 v[44:45], v[10:11], 0, s[6:7]
	s_nop 0
	v_addc_co_u32_e32 v19, vcc, 0, v43, vcc
	v_add_co_u32_e32 v68, vcc, 0xd000, v42
	global_load_dword v163, v[18:19], off offset:2048 nt
	s_nop 0
	v_addc_co_u32_e32 v69, vcc, 0, v43, vcc
	v_add_co_u32_e32 v18, vcc, 0x13000, v42
	v_lshl_add_u64 v[62:63], v[8:9], 0, s[6:7]
	s_nop 0
	v_addc_co_u32_e32 v19, vcc, 0, v43, vcc
	v_lshl_add_u64 v[64:65], v[6:7], 0, s[6:7]
	v_lshl_add_u64 v[66:67], v[4:5], 0, s[6:7]
	global_load_dword v164, v[68:69], off nt
	s_nop 0
	global_load_dword v165, v[18:19], off offset:2048 nt
	s_nop 0
	global_load_dword v166, v[44:45], off nt
	global_load_dword v167, v[62:63], off nt
	s_nop 0
	global_load_dword v168, v[64:65], off nt
	global_load_dword v169, v[66:67], off nt
	s_add_u32 s6, s6, 0x34000
	s_addc_u32 s7, s7, 0
	v_add_u32_e32 v62, 0x400, v2
	s_waitcnt vmcnt(30)
; #define LAS __attribute__((address_space(3)))
; #define LDS_WAIT() asm volatile("s_waitcnt lgkmcnt(0)" ::: "memory")
; __device__ __forceinline__ unsigned pk2(float lo, float hi) { return pg8::cvt_pk_bf16(lo, hi); }
; __device__ __forceinline__ void conv_item(const float* W, int K, int N, bf16_t* WT, int kb, int n0, int dst_row0, LAS float* scr, int lane) {
;     ...
;     for (int i = 0; i < 32; ++i) { const int kk = 2 * i + (lane >> 5); scr[kk * 33 + (lane & 31)] = __builtin_nontemporal_load(W + (size_t)(k0 + kk) * N + n0 + (lane & 31)); }
;     LDS_WAIT(); asm volatile("" ::: "memory");
;     const int c = lane & 7;
; #pragma unroll
;     for (int j = 0; j < 4; ++j) { const int n = (lane >> 3) + 8 * j; const LAS float* s = scr + (8 * c) * 33 + n;
;         u32x4 o; o.x = pk2(s[0 * 33], s[1 * 33]); o.y = pk2(s[2 * 33], s[3 * 33]); o.z = pk2(s[4 * 33], s[5 * 33]); o.w = pk2(s[6 * 33], s[7 * 33]);
;         *(u32x4*)(WT + (size_t)(dst_row0 + n) * K + k0 + 8 * c) = o; }
;     LDS_WAIT(); asm volatile("" ::: "memory");
	ds_write2_b32 v2, v138, v139 offset1:66
	s_waitcnt vmcnt(28)
	ds_write2_b32 v2, v140, v141 offset0:132 offset1:198
	s_waitcnt vmcnt(26)
	ds_write2_b32 v62, v142, v143 offset0:8 offset1:74
	s_waitcnt vmcnt(24)
	ds_write2_b32 v62, v144, v145 offset0:140 offset1:206
	v_add_u32_e32 v2, 0x840, v2
	v_add_u32_e32 v62, 0x400, v2
	s_waitcnt vmcnt(22)
	ds_write2_b32 v2, v146, v147 offset1:66
	s_waitcnt vmcnt(20)
	ds_write2_b32 v2, v148, v149 offset0:132 offset1:198
	s_waitcnt vmcnt(18)
	ds_write2_b32 v62, v150, v151 offset0:8 offset1:74
	s_waitcnt vmcnt(16)
	ds_write2_b32 v62, v152, v153 offset0:140 offset1:206
	v_add_u32_e32 v2, 0x840, v2
	v_add_u32_e32 v62, 0x400, v2
	s_waitcnt vmcnt(14)
	ds_write2_b32 v2, v154, v155 offset1:66
	s_waitcnt vmcnt(12)
	ds_write2_b32 v2, v156, v157 offset0:132 offset1:198
	s_waitcnt vmcnt(10)
	ds_write2_b32 v62, v158, v159 offset0:8 offset1:74
	s_waitcnt vmcnt(8)
	ds_write2_b32 v62, v160, v161 offset0:140 offset1:206
	v_add_u32_e32 v2, 0x840, v2
	v_add_u32_e32 v62, 0x400, v2
	s_waitcnt vmcnt(6)
	ds_write2_b32 v2, v162, v163 offset1:66
	s_waitcnt vmcnt(4)
	ds_write2_b32 v2, v164, v165 offset0:132 offset1:198
	s_waitcnt vmcnt(2)
	ds_write2_b32 v62, v166, v167 offset0:8 offset1:74
	s_waitcnt vmcnt(0)
	ds_write2_b32 v62, v168, v169 offset0:140 offset1:206
	v_add_u32_e32 v2, 0x840, v2
	s_waitcnt lgkmcnt(0)
	ds_read2_b32 v[170:171], v46 offset1:33
	ds_read2_b32 v[172:173], v46 offset0:66 offset1:99
	ds_read2_b32 v[174:175], v46 offset0:132 offset1:165
	ds_read2_b32 v[176:177], v46 offset0:198 offset1:231
	ds_read2_b32 v[178:179], v46 offset0:8 offset1:41
	ds_read2_b32 v[180:181], v46 offset0:74 offset1:107
	ds_read2_b32 v[182:183], v46 offset0:140 offset1:173
	ds_read2_b32 v[192:193], v46 offset0:206 offset1:239
	ds_read2_b32 v[194:195], v46 offset0:16 offset1:49
	ds_read2_b32 v[196:197], v46 offset0:82 offset1:115
	ds_read2_b32 v[198:199], v46 offset0:148 offset1:181
	ds_read2_b32 v[200:201], v46 offset0:214 offset1:247
	ds_read2_b32 v[202:203], v46 offset0:24 offset1:57
	ds_read2_b32 v[204:205], v46 offset0:90 offset1:123
	ds_read2_b32 v[206:207], v46 offset0:156 offset1:189
	ds_read2_b32 v[208:209], v46 offset0:222 offset1:255
	s_and_b32 s6, 0xffff, s8
	s_and_b32 s7, 0xffff, s9
	s_waitcnt lgkmcnt(15)
	v_cvt_pk_bf16_f32 v4, v170, v171
	s_lshl_b32 s44, s7, 1
	v_or_b32_e32 v2, s6, v1
	s_waitcnt lgkmcnt(14)
	v_cvt_pk_bf16_f32 v5, v172, v173
	v_lshl_add_u64 v[10:11], v[24:25], 0, s[44:45]
	v_lshlrev_b32_e32 v2, 12, v2
	s_waitcnt lgkmcnt(13)
	v_cvt_pk_bf16_f32 v6, v174, v175
	s_waitcnt lgkmcnt(12)
	v_cvt_pk_bf16_f32 v7, v176, v177
	v_lshl_add_u64 v[12:13], v[10:11], 0, v[2:3]
	global_store_dwordx4 v[12:13], v[4:7], off
	v_or_b32_e32 v2, s6, v47
	v_lshlrev_b32_e32 v2, 12, v2
	s_waitcnt lgkmcnt(11)
	v_cvt_pk_bf16_f32 v4, v178, v179
	s_waitcnt lgkmcnt(10)
	v_cvt_pk_bf16_f32 v5, v180, v181
	s_waitcnt lgkmcnt(9)
	v_cvt_pk_bf16_f32 v6, v182, v183
	s_waitcnt lgkmcnt(8)
	v_cvt_pk_bf16_f32 v7, v192, v193
	v_lshl_add_u64 v[12:13], v[10:11], 0, v[2:3]
	global_store_dwordx4 v[12:13], v[4:7], off
	v_or_b32_e32 v2, s6, v48
	v_lshlrev_b32_e32 v2, 12, v2
	s_waitcnt lgkmcnt(7)
	v_cvt_pk_bf16_f32 v4, v194, v195
	s_waitcnt lgkmcnt(6)
	v_cvt_pk_bf16_f32 v5, v196, v197
	s_waitcnt lgkmcnt(5)
	v_cvt_pk_bf16_f32 v6, v198, v199
	s_waitcnt lgkmcnt(4)
	v_cvt_pk_bf16_f32 v7, v200, v201
	v_lshl_add_u64 v[12:13], v[10:11], 0, v[2:3]
	global_store_dwordx4 v[12:13], v[4:7], off
	v_or_b32_e32 v2, s6, v49
	v_lshlrev_b32_e32 v2, 12, v2
	s_waitcnt lgkmcnt(3)
	v_cvt_pk_bf16_f32 v4, v202, v203
	s_waitcnt lgkmcnt(2)
	v_cvt_pk_bf16_f32 v5, v204, v205
	s_waitcnt lgkmcnt(1)
	v_cvt_pk_bf16_f32 v6, v206, v207
	s_waitcnt lgkmcnt(0)
	v_cvt_pk_bf16_f32 v7, v208, v209
	v_lshl_add_u64 v[8:9], v[10:11], 0, v[2:3]
	global_store_dwordx4 v[8:9], v[4:7], off
	s_waitcnt lgkmcnt(0)

; #define LAS __attribute__((address_space(3)))
; #define LDS_WAIT() asm volatile("s_waitcnt lgkmcnt(0)" ::: "memory")
; __device__ __forceinline__ void conv_item(const float* W, int K, int N, bf16_t* WT, int kb, int n0, int dst_row0, LAS float* scr, int lane) {
;     const int k0 = 64 * kb;
; #pragma unroll 8
;     for (int i = 0; i < 32; ++i) { const int kk = 2 * i + (lane >> 5); scr[kk * 33 + (lane & 31)] = __builtin_nontemporal_load(W + (size_t)(k0 + kk) * N + n0 + (lane & 31)); }
;     LDS_WAIT(); asm volatile("" ::: "memory");
.LBB0_378:
	v_add_u32_e32 v7, s7, v16
	v_add_u32_e32 v2, 0xfc900000, v7
	v_lshl_add_u64 v[8:9], v[2:3], 2, v[4:5]
	v_add_u32_e32 v2, 0xfc901000, v7
	v_lshl_add_u64 v[10:11], v[2:3], 2, v[4:5]
	v_add_u32_e32 v2, 0xfc902000, v7
	global_load_dword v138, v[8:9], off nt
	global_load_dword v139, v[10:11], off nt
	v_lshl_add_u64 v[8:9], v[2:3], 2, v[4:5]
	v_add_u32_e32 v2, 0xfc903000, v7
	v_lshl_add_u64 v[10:11], v[2:3], 2, v[4:5]
	v_add_u32_e32 v2, 0xfc904000, v7
	global_load_dword v140, v[8:9], off nt
	global_load_dword v141, v[10:11], off nt
	v_lshl_add_u64 v[8:9], v[2:3], 2, v[4:5]
	v_add_u32_e32 v2, 0xfc905000, v7
	v_lshl_add_u64 v[10:11], v[2:3], 2, v[4:5]
	v_add_u32_e32 v2, 0xfc906000, v7
	global_load_dword v142, v[8:9], off nt
	global_load_dword v143, v[10:11], off nt
	v_lshl_add_u64 v[8:9], v[2:3], 2, v[4:5]
	v_add_u32_e32 v2, 0xfc907000, v7
	v_lshl_add_u64 v[10:11], v[2:3], 2, v[4:5]
	global_load_dword v144, v[8:9], off nt
	global_load_dword v145, v[10:11], off nt
	s_add_i32 s7, s7, 0x8000
	v_add_u32_e32 v7, s7, v16
	v_add_u32_e32 v2, 0xfc900000, v7
	v_lshl_add_u64 v[8:9], v[2:3], 2, v[4:5]
	v_add_u32_e32 v2, 0xfc901000, v7
	v_lshl_add_u64 v[10:11], v[2:3], 2, v[4:5]
	v_add_u32_e32 v2, 0xfc902000, v7
	global_load_dword v146, v[8:9], off nt
	global_load_dword v147, v[10:11], off nt
	v_lshl_add_u64 v[8:9], v[2:3], 2, v[4:5]
	v_add_u32_e32 v2, 0xfc903000, v7
	v_lshl_add_u64 v[10:11], v[2:3], 2, v[4:5]
	v_add_u32_e32 v2, 0xfc904000, v7
	global_load_dword v148, v[8:9], off nt
	global_load_dword v149, v[10:11], off nt
	v_lshl_add_u64 v[8:9], v[2:3], 2, v[4:5]
	v_add_u32_e32 v2, 0xfc905000, v7
	v_lshl_add_u64 v[10:11], v[2:3], 2, v[4:5]
	v_add_u32_e32 v2, 0xfc906000, v7
	global_load_dword v150, v[8:9], off nt
	global_load_dword v151, v[10:11], off nt
	v_lshl_add_u64 v[8:9], v[2:3], 2, v[4:5]
	v_add_u32_e32 v2, 0xfc907000, v7
	v_lshl_add_u64 v[10:11], v[2:3], 2, v[4:5]
	global_load_dword v152, v[8:9], off nt
	global_load_dword v153, v[10:11], off nt
	s_add_i32 s7, s7, 0x8000
	v_add_u32_e32 v7, s7, v16
	v_add_u32_e32 v2, 0xfc900000, v7
	v_lshl_add_u64 v[8:9], v[2:3], 2, v[4:5]
	v_add_u32_e32 v2, 0xfc901000, v7
	v_lshl_add_u64 v[10:11], v[2:3], 2, v[4:5]
	v_add_u32_e32 v2, 0xfc902000, v7
	global_load_dword v154, v[8:9], off nt
	global_load_dword v155, v[10:11], off nt
	v_lshl_add_u64 v[8:9], v[2:3], 2, v[4:5]
	v_add_u32_e32 v2, 0xfc903000, v7
	v_lshl_add_u64 v[10:11], v[2:3], 2, v[4:5]
	v_add_u32_e32 v2, 0xfc904000, v7
	global_load_dword v156, v[8:9], off nt
	global_load_dword v157, v[10:11], off nt
	v_lshl_add_u64 v[8:9], v[2:3], 2, v[4:5]
	v_add_u32_e32 v2, 0xfc905000, v7
	v_lshl_add_u64 v[10:11], v[2:3], 2, v[4:5]
	v_add_u32_e32 v2, 0xfc906000, v7
	global_load_dword v158, v[8:9], off nt
	global_load_dword v159, v[10:11], off nt
	v_lshl_add_u64 v[8:9], v[2:3], 2, v[4:5]
	v_add_u32_e32 v2, 0xfc907000, v7
	v_lshl_add_u64 v[10:11], v[2:3], 2, v[4:5]
	global_load_dword v160, v[8:9], off nt
	global_load_dword v161, v[10:11], off nt
	s_add_i32 s7, s7, 0x8000
	v_add_u32_e32 v7, s7, v16
	v_add_u32_e32 v2, 0xfc900000, v7
	v_lshl_add_u64 v[8:9], v[2:3], 2, v[4:5]
	v_add_u32_e32 v2, 0xfc901000, v7
	v_lshl_add_u64 v[10:11], v[2:3], 2, v[4:5]
	v_add_u32_e32 v2, 0xfc902000, v7
	global_load_dword v162, v[8:9], off nt
	global_load_dword v163, v[10:11], off nt
	v_lshl_add_u64 v[8:9], v[2:3], 2, v[4:5]
	v_add_u32_e32 v2, 0xfc903000, v7
	v_lshl_add_u64 v[10:11], v[2:3], 2, v[4:5]
	v_add_u32_e32 v2, 0xfc904000, v7
	global_load_dword v164, v[8:9], off nt
	global_load_dword v165, v[10:11], off nt
	v_lshl_add_u64 v[8:9], v[2:3], 2, v[4:5]
	v_add_u32_e32 v2, 0xfc905000, v7
	v_lshl_add_u64 v[10:11], v[2:3], 2, v[4:5]
	v_add_u32_e32 v2, 0xfc906000, v7
	global_load_dword v166, v[8:9], off nt
	global_load_dword v167, v[10:11], off nt
	v_lshl_add_u64 v[8:9], v[2:3], 2, v[4:5]
	v_add_u32_e32 v2, 0xfc907000, v7
	v_lshl_add_u64 v[10:11], v[2:3], 2, v[4:5]
	global_load_dword v168, v[8:9], off nt
	global_load_dword v169, v[10:11], off nt
	s_add_i32 s7, s7, 0x8000
	v_add_u32_e32 v8, 0x400, v6
	s_waitcnt vmcnt(30)
; #define LAS __attribute__((address_space(3)))
; #define LDS_WAIT() asm volatile("s_waitcnt lgkmcnt(0)" ::: "memory")
; __device__ __forceinline__ unsigned pk2(float lo, float hi) { return pg8::cvt_pk_bf16(lo, hi); }
; __device__ __forceinline__ void conv_item(const float* W, int K, int N, bf16_t* WT, int kb, int n0, int dst_row0, LAS float* scr, int lane) {
;     ...
;     for (int i = 0; i < 32; ++i) { const int kk = 2 * i + (lane >> 5); scr[kk * 33 + (lane & 31)] = __builtin_nontemporal_load(W + (size_t)(k0 + kk) * N + n0 + (lane & 31)); }
;     LDS_WAIT(); asm volatile("" ::: "memory");
;     const int c = lane & 7;
; #pragma unroll
;     for (int j = 0; j < 4; ++j) { const int n = (lane >> 3) + 8 * j; const LAS float* s = scr + (8 * c) * 33 + n;
;         u32x4 o; o.x = pk2(s[0 * 33], s[1 * 33]); o.y = pk2(s[2 * 33], s[3 * 33]); o.z = pk2(s[4 * 33], s[5 * 33]); o.w = pk2(s[6 * 33], s[7 * 33]);
;         *(u32x4*)(WT + (size_t)(dst_row0 + n) * K + k0 + 8 * c) = o; }
;     LDS_WAIT(); asm volatile("" ::: "memory");
	ds_write2_b32 v6, v138, v139 offset1:66
	s_waitcnt vmcnt(28)
	ds_write2_b32 v6, v140, v141 offset0:132 offset1:198
	v_add_u32_e32 v6, 0x840, v6
	s_waitcnt vmcnt(26)
	ds_write2_b32 v8, v142, v143 offset0:8 offset1:74
	s_waitcnt vmcnt(24)
	ds_write2_b32 v8, v144, v145 offset0:140 offset1:206
	v_add_u32_e32 v8, 0x400, v6
	s_waitcnt vmcnt(22)
	ds_write2_b32 v6, v146, v147 offset1:66
	s_waitcnt vmcnt(20)
	ds_write2_b32 v6, v148, v149 offset0:132 offset1:198
	v_add_u32_e32 v6, 0x840, v6
	s_waitcnt vmcnt(18)
	ds_write2_b32 v8, v150, v151 offset0:8 offset1:74
	s_waitcnt vmcnt(16)
	ds_write2_b32 v8, v152, v153 offset0:140 offset1:206
	v_add_u32_e32 v8, 0x400, v6
	s_waitcnt vmcnt(14)
	ds_write2_b32 v6, v154, v155 offset1:66
	s_waitcnt vmcnt(12)
	ds_write2_b32 v6, v156, v157 offset0:132 offset1:198
	v_add_u32_e32 v6, 0x840, v6
	s_waitcnt vmcnt(10)
	ds_write2_b32 v8, v158, v159 offset0:8 offset1:74
	s_waitcnt vmcnt(8)
	ds_write2_b32 v8, v160, v161 offset0:140 offset1:206
	v_add_u32_e32 v8, 0x400, v6
	s_waitcnt vmcnt(6)
	ds_write2_b32 v6, v162, v163 offset1:66
	s_waitcnt vmcnt(4)
	ds_write2_b32 v6, v164, v165 offset0:132 offset1:198
	v_add_u32_e32 v6, 0x840, v6
	s_waitcnt vmcnt(2)
	ds_write2_b32 v8, v166, v167 offset0:8 offset1:74
	s_waitcnt vmcnt(0)
	ds_write2_b32 v8, v168, v169 offset0:140 offset1:206
	s_waitcnt lgkmcnt(0)
	ds_read2_b32 v[170:171], v46 offset1:33
	ds_read2_b32 v[172:173], v46 offset0:66 offset1:99
	ds_read2_b32 v[174:175], v46 offset0:132 offset1:165
	ds_read2_b32 v[176:177], v46 offset0:198 offset1:231
	ds_read2_b32 v[178:179], v46 offset0:8 offset1:41
	ds_read2_b32 v[180:181], v46 offset0:74 offset1:107
	ds_read2_b32 v[182:183], v46 offset0:140 offset1:173
	ds_read2_b32 v[192:193], v46 offset0:206 offset1:239
	ds_read2_b32 v[194:195], v46 offset0:16 offset1:49
	ds_read2_b32 v[196:197], v46 offset0:82 offset1:115
	ds_read2_b32 v[198:199], v46 offset0:148 offset1:181
	ds_read2_b32 v[200:201], v46 offset0:214 offset1:247
	ds_read2_b32 v[202:203], v46 offset0:24 offset1:57
	ds_read2_b32 v[204:205], v46 offset0:90 offset1:123
	ds_read2_b32 v[206:207], v46 offset0:156 offset1:189
	ds_read2_b32 v[208:209], v46 offset0:222 offset1:255
	s_and_b32 s7, s10, 0xffc0
	v_or_b32_e32 v2, s6, v1
	s_waitcnt lgkmcnt(15)
	v_cvt_pk_bf16_f32 v4, v170, v171
	s_add_i32 s44, s7, 0xffff9200
	v_mul_u32_u24_e32 v2, 0x1600, v2
	s_waitcnt lgkmcnt(14)
	v_cvt_pk_bf16_f32 v5, v172, v173
	v_lshl_add_u64 v[10:11], s[44:45], 1, v[26:27]
	v_lshlrev_b32_e32 v2, 1, v2
	s_waitcnt lgkmcnt(13)
	v_cvt_pk_bf16_f32 v6, v174, v175
	s_waitcnt lgkmcnt(12)
	v_cvt_pk_bf16_f32 v7, v176, v177
	v_lshl_add_u64 v[12:13], v[10:11], 0, v[2:3]
	v_or_b32_e32 v2, s6, v47
	global_store_dwordx4 v[12:13], v[4:7], off
	v_mul_u32_u24_e32 v2, 0x1600, v2
	v_lshlrev_b32_e32 v2, 1, v2
	s_waitcnt lgkmcnt(11)
	v_cvt_pk_bf16_f32 v4, v178, v179
	s_waitcnt lgkmcnt(10)
	v_cvt_pk_bf16_f32 v5, v180, v181
	s_waitcnt lgkmcnt(9)
	v_cvt_pk_bf16_f32 v6, v182, v183
	s_waitcnt lgkmcnt(8)
	v_cvt_pk_bf16_f32 v7, v192, v193
	v_lshl_add_u64 v[12:13], v[10:11], 0, v[2:3]
	v_or_b32_e32 v2, s6, v48
	global_store_dwordx4 v[12:13], v[4:7], off
	v_mul_u32_u24_e32 v2, 0x1600, v2
	v_lshlrev_b32_e32 v2, 1, v2
	s_waitcnt lgkmcnt(7)
	v_cvt_pk_bf16_f32 v4, v194, v195
	s_waitcnt lgkmcnt(6)
	v_cvt_pk_bf16_f32 v5, v196, v197
	s_waitcnt lgkmcnt(5)
	v_cvt_pk_bf16_f32 v6, v198, v199
	s_waitcnt lgkmcnt(4)
	v_cvt_pk_bf16_f32 v7, v200, v201
	v_lshl_add_u64 v[12:13], v[10:11], 0, v[2:3]
	global_store_dwordx4 v[12:13], v[4:7], off
	v_or_b32_e32 v2, s6, v49
	v_mul_u32_u24_e32 v2, 0x1600, v2
	s_waitcnt lgkmcnt(3)
	v_cvt_pk_bf16_f32 v4, v202, v203
	s_waitcnt lgkmcnt(2)
	v_cvt_pk_bf16_f32 v5, v204, v205
	s_waitcnt lgkmcnt(1)
	v_cvt_pk_bf16_f32 v6, v206, v207
	v_lshlrev_b32_e32 v2, 1, v2
	s_waitcnt lgkmcnt(0)
	v_cvt_pk_bf16_f32 v7, v208, v209
	v_lshl_add_u64 v[8:9], v[10:11], 0, v[2:3]
	global_store_dwordx4 v[8:9], v[4:7], off
	s_waitcnt lgkmcnt(0)

; #define LAS __attribute__((address_space(3)))
; #define LDS_WAIT() asm volatile("s_waitcnt lgkmcnt(0)" ::: "memory")
; __device__ __forceinline__ void conv_item(const float* W, int K, int N, bf16_t* WT, int kb, int n0, int dst_row0, LAS float* scr, int lane) {
;     const int k0 = 64 * kb;
; #pragma unroll 8
;     for (int i = 0; i < 32; ++i) { const int kk = 2 * i + (lane >> 5); scr[kk * 33 + (lane & 31)] = __builtin_nontemporal_load(W + (size_t)(k0 + kk) * N + n0 + (lane & 31)); }
;     LDS_WAIT(); asm volatile("" ::: "memory");
.LBB0_383:
	v_lshl_add_u64 v[18:19], v[12:13], 0, s[8:9]
	v_add_co_u32_e32 v66, vcc, 0xb000, v18
	v_lshl_add_u64 v[16:17], v[14:15], 0, s[8:9]
	v_lshl_add_u64 v[42:43], v[10:11], 0, s[8:9]
	v_lshl_add_u64 v[44:45], v[8:9], 0, s[8:9]
	s_mov_b64 s[6:7], vcc
	v_lshl_add_u64 v[62:63], v[6:7], 0, s[8:9]
	v_lshl_add_u64 v[64:65], v[4:5], 0, s[8:9]
	global_load_dword v138, v[16:17], off nt
	s_nop 0
	global_load_dword v139, v[42:43], off nt
	s_nop 0
	global_load_dword v140, v[44:45], off nt
	s_nop 0
	global_load_dword v141, v[62:63], off nt
	global_load_dword v142, v[64:65], off nt
	v_add_co_u32_e32 v16, vcc, 0x16000, v18
	v_addc_co_u32_e64 v67, s[6:7], 0, v19, s[6:7]
	s_mov_b64 s[6:7], vcc
	v_add_co_u32_e32 v18, vcc, 0x21000, v18
	v_addc_co_u32_e64 v17, s[6:7], 0, v19, s[6:7]
	global_load_dword v143, v[66:67], off nt
	v_addc_co_u32_e32 v19, vcc, 0, v19, vcc
	global_load_dword v144, v[16:17], off nt
	s_nop 0
	global_load_dword v145, v[18:19], off nt
	s_add_u32 s8, s8, 0x58000
	s_addc_u32 s9, s9, 0
	v_lshl_add_u64 v[18:19], v[12:13], 0, s[8:9]
	v_add_co_u32_e32 v66, vcc, 0xb000, v18
	v_lshl_add_u64 v[16:17], v[14:15], 0, s[8:9]
	v_lshl_add_u64 v[42:43], v[10:11], 0, s[8:9]
	v_lshl_add_u64 v[44:45], v[8:9], 0, s[8:9]
	s_mov_b64 s[6:7], vcc
	v_lshl_add_u64 v[62:63], v[6:7], 0, s[8:9]
	v_lshl_add_u64 v[64:65], v[4:5], 0, s[8:9]
	global_load_dword v146, v[16:17], off nt
	s_nop 0
	global_load_dword v147, v[42:43], off nt
	s_nop 0
	global_load_dword v148, v[44:45], off nt
	s_nop 0
	global_load_dword v149, v[62:63], off nt
	global_load_dword v150, v[64:65], off nt
	v_add_co_u32_e32 v16, vcc, 0x16000, v18
	v_addc_co_u32_e64 v67, s[6:7], 0, v19, s[6:7]
	s_mov_b64 s[6:7], vcc
	v_add_co_u32_e32 v18, vcc, 0x21000, v18
	v_addc_co_u32_e64 v17, s[6:7], 0, v19, s[6:7]
	global_load_dword v151, v[66:67], off nt
	v_addc_co_u32_e32 v19, vcc, 0, v19, vcc
	global_load_dword v152, v[16:17], off nt
	s_nop 0
	global_load_dword v153, v[18:19], off nt
	s_add_u32 s8, s8, 0x58000
	s_addc_u32 s9, s9, 0
	v_lshl_add_u64 v[18:19], v[12:13], 0, s[8:9]
	v_add_co_u32_e32 v66, vcc, 0xb000, v18
	v_lshl_add_u64 v[16:17], v[14:15], 0, s[8:9]
	v_lshl_add_u64 v[42:43], v[10:11], 0, s[8:9]
	v_lshl_add_u64 v[44:45], v[8:9], 0, s[8:9]
	s_mov_b64 s[6:7], vcc
	v_lshl_add_u64 v[62:63], v[6:7], 0, s[8:9]
	v_lshl_add_u64 v[64:65], v[4:5], 0, s[8:9]
	global_load_dword v154, v[16:17], off nt
	s_nop 0
	global_load_dword v155, v[42:43], off nt
	s_nop 0
	global_load_dword v156, v[44:45], off nt
	s_nop 0
	global_load_dword v157, v[62:63], off nt
	global_load_dword v158, v[64:65], off nt
	v_add_co_u32_e32 v16, vcc, 0x16000, v18
	v_addc_co_u32_e64 v67, s[6:7], 0, v19, s[6:7]
	s_mov_b64 s[6:7], vcc
	v_add_co_u32_e32 v18, vcc, 0x21000, v18
	v_addc_co_u32_e64 v17, s[6:7], 0, v19, s[6:7]
	global_load_dword v159, v[66:67], off nt
	v_addc_co_u32_e32 v19, vcc, 0, v19, vcc
	global_load_dword v160, v[16:17], off nt
	s_nop 0
	global_load_dword v161, v[18:19], off nt
	s_add_u32 s8, s8, 0x58000
	s_addc_u32 s9, s9, 0
	v_lshl_add_u64 v[18:19], v[12:13], 0, s[8:9]
	v_add_co_u32_e32 v66, vcc, 0xb000, v18
	v_lshl_add_u64 v[16:17], v[14:15], 0, s[8:9]
	v_lshl_add_u64 v[42:43], v[10:11], 0, s[8:9]
	v_lshl_add_u64 v[44:45], v[8:9], 0, s[8:9]
	s_mov_b64 s[6:7], vcc
	v_lshl_add_u64 v[62:63], v[6:7], 0, s[8:9]
	v_lshl_add_u64 v[64:65], v[4:5], 0, s[8:9]
	global_load_dword v162, v[16:17], off nt
	s_nop 0
	global_load_dword v163, v[42:43], off nt
	s_nop 0
	global_load_dword v164, v[44:45], off nt
	s_nop 0
	global_load_dword v165, v[62:63], off nt
	global_load_dword v166, v[64:65], off nt
	v_add_co_u32_e32 v16, vcc, 0x16000, v18
	v_addc_co_u32_e64 v67, s[6:7], 0, v19, s[6:7]
	s_mov_b64 s[6:7], vcc
	v_add_co_u32_e32 v18, vcc, 0x21000, v18
	v_addc_co_u32_e64 v17, s[6:7], 0, v19, s[6:7]
	global_load_dword v167, v[66:67], off nt
	v_addc_co_u32_e32 v19, vcc, 0, v19, vcc
	global_load_dword v168, v[16:17], off nt
	s_nop 0
	global_load_dword v169, v[18:19], off nt
	s_add_u32 s8, s8, 0x58000
	s_addc_u32 s9, s9, 0
	v_add_u32_e32 v18, 0x400, v2
	s_waitcnt vmcnt(29)
; #define LAS __attribute__((address_space(3)))
; #define LDS_WAIT() asm volatile("s_waitcnt lgkmcnt(0)" ::: "memory")
; __device__ __forceinline__ unsigned pk2(float lo, float hi) { return pg8::cvt_pk_bf16(lo, hi); }
; __device__ __forceinline__ void conv_item(const float* W, int K, int N, bf16_t* WT, int kb, int n0, int dst_row0, LAS float* scr, int lane) {
;     ...
;     for (int i = 0; i < 32; ++i) { const int kk = 2 * i + (lane >> 5); scr[kk * 33 + (lane & 31)] = __builtin_nontemporal_load(W + (size_t)(k0 + kk) * N + n0 + (lane & 31)); }
;     LDS_WAIT(); asm volatile("" ::: "memory");
;     const int c = lane & 7;
; #pragma unroll
;     for (int j = 0; j < 4; ++j) { const int n = (lane >> 3) + 8 * j; const LAS float* s = scr + (8 * c) * 33 + n;
;         u32x4 o; o.x = pk2(s[0 * 33], s[1 * 33]); o.y = pk2(s[2 * 33], s[3 * 33]); o.z = pk2(s[4 * 33], s[5 * 33]); o.w = pk2(s[6 * 33], s[7 * 33]);
;         *(u32x4*)(WT + (size_t)(dst_row0 + n) * K + k0 + 8 * c) = o; }
;     LDS_WAIT(); asm volatile("" ::: "memory");
	ds_write2_b32 v18, v139, v140 offset0:8 offset1:74
	s_waitcnt vmcnt(27)
	ds_write2_b32 v18, v141, v142 offset0:140 offset1:206
	s_waitcnt vmcnt(26)
	ds_write2_b32 v2, v138, v143 offset1:66
	s_waitcnt vmcnt(24)
	ds_write2_b32 v2, v144, v145 offset0:132 offset1:198
	v_add_u32_e32 v2, 0x840, v2
	v_add_u32_e32 v18, 0x400, v2
	s_waitcnt vmcnt(21)
	ds_write2_b32 v18, v147, v148 offset0:8 offset1:74
	s_waitcnt vmcnt(19)
	ds_write2_b32 v18, v149, v150 offset0:140 offset1:206
	s_waitcnt vmcnt(18)
	ds_write2_b32 v2, v146, v151 offset1:66
	s_waitcnt vmcnt(16)
	ds_write2_b32 v2, v152, v153 offset0:132 offset1:198
	v_add_u32_e32 v2, 0x840, v2
	v_add_u32_e32 v18, 0x400, v2
	s_waitcnt vmcnt(13)
	ds_write2_b32 v18, v155, v156 offset0:8 offset1:74
	s_waitcnt vmcnt(11)
	ds_write2_b32 v18, v157, v158 offset0:140 offset1:206
	s_waitcnt vmcnt(10)
	ds_write2_b32 v2, v154, v159 offset1:66
	s_waitcnt vmcnt(8)
	ds_write2_b32 v2, v160, v161 offset0:132 offset1:198
	v_add_u32_e32 v2, 0x840, v2
	v_add_u32_e32 v18, 0x400, v2
	s_waitcnt vmcnt(5)
	ds_write2_b32 v18, v163, v164 offset0:8 offset1:74
	s_waitcnt vmcnt(3)
	ds_write2_b32 v18, v165, v166 offset0:140 offset1:206
	s_waitcnt vmcnt(2)
	ds_write2_b32 v2, v162, v167 offset1:66
	s_waitcnt vmcnt(0)
	ds_write2_b32 v2, v168, v169 offset0:132 offset1:198
	v_add_u32_e32 v2, 0x840, v2
	s_lshl_b32 s6, s14, 6
	s_waitcnt lgkmcnt(0)
	ds_read2_b32 v[170:171], v46 offset1:33
	ds_read2_b32 v[172:173], v46 offset0:66 offset1:99
	ds_read2_b32 v[174:175], v46 offset0:132 offset1:165
	ds_read2_b32 v[176:177], v46 offset0:198 offset1:231
	ds_read2_b32 v[178:179], v46 offset0:8 offset1:41
	ds_read2_b32 v[180:181], v46 offset0:74 offset1:107
	ds_read2_b32 v[182:183], v46 offset0:140 offset1:173
	ds_read2_b32 v[192:193], v46 offset0:206 offset1:239
	ds_read2_b32 v[194:195], v46 offset0:16 offset1:49
	ds_read2_b32 v[196:197], v46 offset0:82 offset1:115
	ds_read2_b32 v[198:199], v46 offset0:148 offset1:181
	ds_read2_b32 v[200:201], v46 offset0:214 offset1:247
	ds_read2_b32 v[202:203], v46 offset0:24 offset1:57
	ds_read2_b32 v[204:205], v46 offset0:90 offset1:123
	ds_read2_b32 v[206:207], v46 offset0:156 offset1:189
	ds_read2_b32 v[208:209], v46 offset0:222 offset1:255
	s_and_b32 s7, s15, 0x60
	s_and_b32 s6, s6, 0x3f00
	s_or_b32 s6, s6, s7
	s_and_b32 s8, 0xffff, s16
	s_bitset1_b32 s6, 7
	s_waitcnt lgkmcnt(15)
	v_cvt_pk_bf16_f32 v4, v170, v171
	s_lshl_b32 s44, s8, 1
	v_or_b32_e32 v2, s6, v1
	s_waitcnt lgkmcnt(14)
	v_cvt_pk_bf16_f32 v5, v172, v173
	v_lshl_add_u64 v[10:11], v[28:29], 0, s[44:45]
	v_lshlrev_b32_e32 v2, 12, v2
	s_waitcnt lgkmcnt(13)
	v_cvt_pk_bf16_f32 v6, v174, v175
	s_waitcnt lgkmcnt(12)
	v_cvt_pk_bf16_f32 v7, v176, v177
	v_lshl_add_u64 v[12:13], v[10:11], 0, v[2:3]
	global_store_dwordx4 v[12:13], v[4:7], off
	v_or_b32_e32 v2, s6, v47
	v_lshlrev_b32_e32 v2, 12, v2
	s_waitcnt lgkmcnt(11)
	v_cvt_pk_bf16_f32 v4, v178, v179
	s_waitcnt lgkmcnt(10)
	v_cvt_pk_bf16_f32 v5, v180, v181
	s_waitcnt lgkmcnt(9)
	v_cvt_pk_bf16_f32 v6, v182, v183
	s_waitcnt lgkmcnt(8)
	v_cvt_pk_bf16_f32 v7, v192, v193
	v_lshl_add_u64 v[12:13], v[10:11], 0, v[2:3]
	global_store_dwordx4 v[12:13], v[4:7], off
	v_or_b32_e32 v2, s6, v48
	v_lshlrev_b32_e32 v2, 12, v2
	s_waitcnt lgkmcnt(7)
	v_cvt_pk_bf16_f32 v4, v194, v195
	s_waitcnt lgkmcnt(6)
	v_cvt_pk_bf16_f32 v5, v196, v197
	s_waitcnt lgkmcnt(5)
	v_cvt_pk_bf16_f32 v6, v198, v199
	s_waitcnt lgkmcnt(4)
	v_cvt_pk_bf16_f32 v7, v200, v201
	v_lshl_add_u64 v[12:13], v[10:11], 0, v[2:3]
	global_store_dwordx4 v[12:13], v[4:7], off
	v_or_b32_e32 v2, s6, v49
	v_lshlrev_b32_e32 v2, 12, v2
	s_waitcnt lgkmcnt(3)
	v_cvt_pk_bf16_f32 v4, v202, v203
	s_waitcnt lgkmcnt(2)
	v_cvt_pk_bf16_f32 v5, v204, v205
	s_waitcnt lgkmcnt(1)
	v_cvt_pk_bf16_f32 v6, v206, v207
	s_waitcnt lgkmcnt(0)
	v_cvt_pk_bf16_f32 v7, v208, v209
	v_lshl_add_u64 v[8:9], v[10:11], 0, v[2:3]
	global_store_dwordx4 v[8:9], v[4:7], off
	s_waitcnt lgkmcnt(0)

; #define LAS __attribute__((address_space(3)))
; #define LDS_WAIT() asm volatile("s_waitcnt lgkmcnt(0)" ::: "memory")
; __device__ __forceinline__ void conv_item(const float* W, int K, int N, bf16_t* WT, int kb, int n0, int dst_row0, LAS float* scr, int lane) {
;     const int k0 = 64 * kb;
; #pragma unroll 8
;     for (int i = 0; i < 32; ++i) { const int kk = 2 * i + (lane >> 5); scr[kk * 33 + (lane & 31)] = __builtin_nontemporal_load(W + (size_t)(k0 + kk) * N + n0 + (lane & 31)); }
;     LDS_WAIT(); asm volatile("" ::: "memory");
.LBB0_388:
	v_lshl_add_u64 v[18:19], v[12:13], 0, s[8:9]
	v_add_co_u32_e32 v66, vcc, 0xb000, v18
	v_lshl_add_u64 v[16:17], v[14:15], 0, s[8:9]
	v_lshl_add_u64 v[42:43], v[10:11], 0, s[8:9]
	v_lshl_add_u64 v[44:45], v[8:9], 0, s[8:9]
	s_mov_b64 s[6:7], vcc
	v_lshl_add_u64 v[62:63], v[6:7], 0, s[8:9]
	v_lshl_add_u64 v[64:65], v[4:5], 0, s[8:9]
	global_load_dword v138, v[16:17], off nt
	s_nop 0
	global_load_dword v139, v[42:43], off nt
	s_nop 0
	global_load_dword v140, v[44:45], off nt
	s_nop 0
	global_load_dword v141, v[62:63], off nt
	global_load_dword v142, v[64:65], off nt
	v_add_co_u32_e32 v16, vcc, 0x16000, v18
	v_addc_co_u32_e64 v67, s[6:7], 0, v19, s[6:7]
	s_mov_b64 s[6:7], vcc
	v_add_co_u32_e32 v18, vcc, 0x21000, v18
	v_addc_co_u32_e64 v17, s[6:7], 0, v19, s[6:7]
	global_load_dword v143, v[66:67], off nt
	v_addc_co_u32_e32 v19, vcc, 0, v19, vcc
	global_load_dword v144, v[16:17], off nt
	s_nop 0
	global_load_dword v145, v[18:19], off nt
	s_add_u32 s8, s8, 0x58000
	s_addc_u32 s9, s9, 0
	v_lshl_add_u64 v[18:19], v[12:13], 0, s[8:9]
	v_add_co_u32_e32 v66, vcc, 0xb000, v18
	v_lshl_add_u64 v[16:17], v[14:15], 0, s[8:9]
	v_lshl_add_u64 v[42:43], v[10:11], 0, s[8:9]
	v_lshl_add_u64 v[44:45], v[8:9], 0, s[8:9]
	s_mov_b64 s[6:7], vcc
	v_lshl_add_u64 v[62:63], v[6:7], 0, s[8:9]
	v_lshl_add_u64 v[64:65], v[4:5], 0, s[8:9]
	global_load_dword v146, v[16:17], off nt
	s_nop 0
	global_load_dword v147, v[42:43], off nt
	s_nop 0
	global_load_dword v148, v[44:45], off nt
	s_nop 0
	global_load_dword v149, v[62:63], off nt
	global_load_dword v150, v[64:65], off nt
	v_add_co_u32_e32 v16, vcc, 0x16000, v18
	v_addc_co_u32_e64 v67, s[6:7], 0, v19, s[6:7]
	s_mov_b64 s[6:7], vcc
	v_add_co_u32_e32 v18, vcc, 0x21000, v18
	v_addc_co_u32_e64 v17, s[6:7], 0, v19, s[6:7]
	global_load_dword v151, v[66:67], off nt
	v_addc_co_u32_e32 v19, vcc, 0, v19, vcc
	global_load_dword v152, v[16:17], off nt
	s_nop 0
	global_load_dword v153, v[18:19], off nt
	s_add_u32 s8, s8, 0x58000
	s_addc_u32 s9, s9, 0
	v_lshl_add_u64 v[18:19], v[12:13], 0, s[8:9]
	v_add_co_u32_e32 v66, vcc, 0xb000, v18
	v_lshl_add_u64 v[16:17], v[14:15], 0, s[8:9]
	v_lshl_add_u64 v[42:43], v[10:11], 0, s[8:9]
	v_lshl_add_u64 v[44:45], v[8:9], 0, s[8:9]
	s_mov_b64 s[6:7], vcc
	v_lshl_add_u64 v[62:63], v[6:7], 0, s[8:9]
	v_lshl_add_u64 v[64:65], v[4:5], 0, s[8:9]
	global_load_dword v154, v[16:17], off nt
	s_nop 0
	global_load_dword v155, v[42:43], off nt
	s_nop 0
	global_load_dword v156, v[44:45], off nt
	s_nop 0
	global_load_dword v157, v[62:63], off nt
	global_load_dword v158, v[64:65], off nt
	v_add_co_u32_e32 v16, vcc, 0x16000, v18
	v_addc_co_u32_e64 v67, s[6:7], 0, v19, s[6:7]
	s_mov_b64 s[6:7], vcc
	v_add_co_u32_e32 v18, vcc, 0x21000, v18
	v_addc_co_u32_e64 v17, s[6:7], 0, v19, s[6:7]
	global_load_dword v159, v[66:67], off nt
	v_addc_co_u32_e32 v19, vcc, 0, v19, vcc
	global_load_dword v160, v[16:17], off nt
	s_nop 0
	global_load_dword v161, v[18:19], off nt
	s_add_u32 s8, s8, 0x58000
	s_addc_u32 s9, s9, 0
	v_lshl_add_u64 v[18:19], v[12:13], 0, s[8:9]
	v_add_co_u32_e32 v66, vcc, 0xb000, v18
	v_lshl_add_u64 v[16:17], v[14:15], 0, s[8:9]
	v_lshl_add_u64 v[42:43], v[10:11], 0, s[8:9]
	v_lshl_add_u64 v[44:45], v[8:9], 0, s[8:9]
	s_mov_b64 s[6:7], vcc
	v_lshl_add_u64 v[62:63], v[6:7], 0, s[8:9]
	v_lshl_add_u64 v[64:65], v[4:5], 0, s[8:9]
	global_load_dword v162, v[16:17], off nt
	s_nop 0
	global_load_dword v163, v[42:43], off nt
	s_nop 0
	global_load_dword v164, v[44:45], off nt
	s_nop 0
	global_load_dword v165, v[62:63], off nt
	global_load_dword v166, v[64:65], off nt
	v_add_co_u32_e32 v16, vcc, 0x16000, v18
	v_addc_co_u32_e64 v67, s[6:7], 0, v19, s[6:7]
	s_mov_b64 s[6:7], vcc
	v_add_co_u32_e32 v18, vcc, 0x21000, v18
	v_addc_co_u32_e64 v17, s[6:7], 0, v19, s[6:7]
	global_load_dword v167, v[66:67], off nt
	v_addc_co_u32_e32 v19, vcc, 0, v19, vcc
	global_load_dword v168, v[16:17], off nt
	s_nop 0
	global_load_dword v169, v[18:19], off nt
	s_add_u32 s8, s8, 0x58000
	s_addc_u32 s9, s9, 0
	v_add_u32_e32 v18, 0x400, v2
	s_waitcnt vmcnt(29)
; #define LAS __attribute__((address_space(3)))
; #define LDS_WAIT() asm volatile("s_waitcnt lgkmcnt(0)" ::: "memory")
; __device__ __forceinline__ unsigned pk2(float lo, float hi) { return pg8::cvt_pk_bf16(lo, hi); }
; __device__ __forceinline__ void conv_item(const float* W, int K, int N, bf16_t* WT, int kb, int n0, int dst_row0, LAS float* scr, int lane) {
;     ...
;     for (int i = 0; i < 32; ++i) { const int kk = 2 * i + (lane >> 5); scr[kk * 33 + (lane & 31)] = __builtin_nontemporal_load(W + (size_t)(k0 + kk) * N + n0 + (lane & 31)); }
;     LDS_WAIT(); asm volatile("" ::: "memory");
;     const int c = lane & 7;
; #pragma unroll
;     for (int j = 0; j < 4; ++j) { const int n = (lane >> 3) + 8 * j; const LAS float* s = scr + (8 * c) * 33 + n;
;         u32x4 o; o.x = pk2(s[0 * 33], s[1 * 33]); o.y = pk2(s[2 * 33], s[3 * 33]); o.z = pk2(s[4 * 33], s[5 * 33]); o.w = pk2(s[6 * 33], s[7 * 33]);
;         *(u32x4*)(WT + (size_t)(dst_row0 + n) * K + k0 + 8 * c) = o; }
;     LDS_WAIT(); asm volatile("" ::: "memory");
	ds_write2_b32 v18, v139, v140 offset0:8 offset1:74
	s_waitcnt vmcnt(27)
	ds_write2_b32 v18, v141, v142 offset0:140 offset1:206
	s_waitcnt vmcnt(26)
	ds_write2_b32 v2, v138, v143 offset1:66
	s_waitcnt vmcnt(24)
	ds_write2_b32 v2, v144, v145 offset0:132 offset1:198
	v_add_u32_e32 v2, 0x840, v2
	v_add_u32_e32 v18, 0x400, v2
	s_waitcnt vmcnt(21)
	ds_write2_b32 v18, v147, v148 offset0:8 offset1:74
	s_waitcnt vmcnt(19)
	ds_write2_b32 v18, v149, v150 offset0:140 offset1:206
	s_waitcnt vmcnt(18)
	ds_write2_b32 v2, v146, v151 offset1:66
	s_waitcnt vmcnt(16)
	ds_write2_b32 v2, v152, v153 offset0:132 offset1:198
	v_add_u32_e32 v2, 0x840, v2
	v_add_u32_e32 v18, 0x400, v2
	s_waitcnt vmcnt(13)
	ds_write2_b32 v18, v155, v156 offset0:8 offset1:74
	s_waitcnt vmcnt(11)
	ds_write2_b32 v18, v157, v158 offset0:140 offset1:206
	s_waitcnt vmcnt(10)
	ds_write2_b32 v2, v154, v159 offset1:66
	s_waitcnt vmcnt(8)
	ds_write2_b32 v2, v160, v161 offset0:132 offset1:198
	v_add_u32_e32 v2, 0x840, v2
	v_add_u32_e32 v18, 0x400, v2
	s_waitcnt vmcnt(5)
	ds_write2_b32 v18, v163, v164 offset0:8 offset1:74
	s_waitcnt vmcnt(3)
	ds_write2_b32 v18, v165, v166 offset0:140 offset1:206
	s_waitcnt vmcnt(2)
	ds_write2_b32 v2, v162, v167 offset1:66
	s_waitcnt vmcnt(0)
	ds_write2_b32 v2, v168, v169 offset0:132 offset1:198
	v_add_u32_e32 v2, 0x840, v2
	s_waitcnt lgkmcnt(0)
	ds_read2_b32 v[170:171], v46 offset1:33
	ds_read2_b32 v[172:173], v46 offset0:66 offset1:99
	ds_read2_b32 v[174:175], v46 offset0:132 offset1:165
	ds_read2_b32 v[176:177], v46 offset0:198 offset1:231
	ds_read2_b32 v[178:179], v46 offset0:8 offset1:41
	ds_read2_b32 v[180:181], v46 offset0:74 offset1:107
	ds_read2_b32 v[182:183], v46 offset0:140 offset1:173
	ds_read2_b32 v[192:193], v46 offset0:206 offset1:239
	ds_read2_b32 v[194:195], v46 offset0:16 offset1:49
	ds_read2_b32 v[196:197], v46 offset0:82 offset1:115
	ds_read2_b32 v[198:199], v46 offset0:148 offset1:181
	ds_read2_b32 v[200:201], v46 offset0:214 offset1:247
	ds_read2_b32 v[202:203], v46 offset0:24 offset1:57
	ds_read2_b32 v[204:205], v46 offset0:90 offset1:123
	ds_read2_b32 v[206:207], v46 offset0:156 offset1:189
	ds_read2_b32 v[208:209], v46 offset0:222 offset1:255
	s_lshl_b32 s6, s13, 6
	s_and_b32 s7, s14, 0x60
	s_and_b32 s6, s6, 0x3f00
	s_and_b32 s8, 0xffff, s15
	s_or_b32 s6, s6, s7
	s_waitcnt lgkmcnt(15)
	v_cvt_pk_bf16_f32 v4, v170, v171
	s_lshl_b32 s44, s8, 1
	v_or_b32_e32 v2, s6, v1
	s_waitcnt lgkmcnt(14)
	v_cvt_pk_bf16_f32 v5, v172, v173
	v_lshl_add_u64 v[10:11], v[28:29], 0, s[44:45]
	v_lshlrev_b32_e32 v2, 12, v2
	s_waitcnt lgkmcnt(13)
	v_cvt_pk_bf16_f32 v6, v174, v175
	s_waitcnt lgkmcnt(12)
	v_cvt_pk_bf16_f32 v7, v176, v177
	v_lshl_add_u64 v[12:13], v[10:11], 0, v[2:3]
	global_store_dwordx4 v[12:13], v[4:7], off
	v_or_b32_e32 v2, s6, v47
	v_lshlrev_b32_e32 v2, 12, v2
	s_waitcnt lgkmcnt(11)
	v_cvt_pk_bf16_f32 v4, v178, v179
	s_waitcnt lgkmcnt(10)
	v_cvt_pk_bf16_f32 v5, v180, v181
	s_waitcnt lgkmcnt(9)
	v_cvt_pk_bf16_f32 v6, v182, v183
	s_waitcnt lgkmcnt(8)
	v_cvt_pk_bf16_f32 v7, v192, v193
	v_lshl_add_u64 v[12:13], v[10:11], 0, v[2:3]
	global_store_dwordx4 v[12:13], v[4:7], off
	v_or_b32_e32 v2, s6, v48
	v_lshlrev_b32_e32 v2, 12, v2
	s_waitcnt lgkmcnt(7)
	v_cvt_pk_bf16_f32 v4, v194, v195
	s_waitcnt lgkmcnt(6)
	v_cvt_pk_bf16_f32 v5, v196, v197
	s_waitcnt lgkmcnt(5)
	v_cvt_pk_bf16_f32 v6, v198, v199
	s_waitcnt lgkmcnt(4)
	v_cvt_pk_bf16_f32 v7, v200, v201
	v_lshl_add_u64 v[12:13], v[10:11], 0, v[2:3]
	global_store_dwordx4 v[12:13], v[4:7], off
	v_or_b32_e32 v2, s6, v49
	v_lshlrev_b32_e32 v2, 12, v2
	s_waitcnt lgkmcnt(3)
	v_cvt_pk_bf16_f32 v4, v202, v203
	s_waitcnt lgkmcnt(2)
	v_cvt_pk_bf16_f32 v5, v204, v205
	s_waitcnt lgkmcnt(1)
	v_cvt_pk_bf16_f32 v6, v206, v207
	s_waitcnt lgkmcnt(0)
	v_cvt_pk_bf16_f32 v7, v208, v209
	v_lshl_add_u64 v[8:9], v[10:11], 0, v[2:3]
	global_store_dwordx4 v[8:9], v[4:7], off
	s_waitcnt lgkmcnt(0)

; #define LAS __attribute__((address_space(3)))
; #define LDS_WAIT() asm volatile("s_waitcnt lgkmcnt(0)" ::: "memory")
; __device__ __forceinline__ void conv_item(const float* W, int K, int N, bf16_t* WT, int kb, int n0, int dst_row0, LAS float* scr, int lane) {
;     const int k0 = 64 * kb;
; #pragma unroll 8
;     for (int i = 0; i < 32; ++i) { const int kk = 2 * i + (lane >> 5); scr[kk * 33 + (lane & 31)] = __builtin_nontemporal_load(W + (size_t)(k0 + kk) * N + n0 + (lane & 31)); }
;     LDS_WAIT(); asm volatile("" ::: "memory");
.LBB0_393:
	v_add_u32_e32 v12, s7, v6
	v_add_u32_e32 v2, 0xfea00000, v12
	v_lshl_add_u64 v[8:9], v[2:3], 2, v[4:5]
	v_add_u32_e32 v2, 0xfea01000, v12
	v_lshl_add_u64 v[10:11], v[2:3], 2, v[4:5]
	v_add_u32_e32 v2, 0xfea02000, v12
	global_load_dword v138, v[8:9], off nt
	global_load_dword v139, v[10:11], off nt
	v_lshl_add_u64 v[8:9], v[2:3], 2, v[4:5]
	v_add_u32_e32 v2, 0xfea03000, v12
	v_lshl_add_u64 v[10:11], v[2:3], 2, v[4:5]
	v_add_u32_e32 v2, 0xfea04000, v12
	global_load_dword v140, v[8:9], off nt
	global_load_dword v141, v[10:11], off nt
	v_lshl_add_u64 v[8:9], v[2:3], 2, v[4:5]
	v_add_u32_e32 v2, 0xfea05000, v12
	v_lshl_add_u64 v[10:11], v[2:3], 2, v[4:5]
	v_add_u32_e32 v2, 0xfea06000, v12
	global_load_dword v142, v[8:9], off nt
	global_load_dword v143, v[10:11], off nt
	v_lshl_add_u64 v[8:9], v[2:3], 2, v[4:5]
	v_add_u32_e32 v2, 0xfea07000, v12
	v_lshl_add_u64 v[10:11], v[2:3], 2, v[4:5]
	global_load_dword v144, v[8:9], off nt
	s_nop 0
	global_load_dword v145, v[10:11], off nt
	s_add_i32 s7, s7, 0x8000
	v_add_u32_e32 v12, s7, v6
	v_add_u32_e32 v2, 0xfea00000, v12
	v_lshl_add_u64 v[8:9], v[2:3], 2, v[4:5]
	v_add_u32_e32 v2, 0xfea01000, v12
	v_lshl_add_u64 v[10:11], v[2:3], 2, v[4:5]
	v_add_u32_e32 v2, 0xfea02000, v12
	global_load_dword v146, v[8:9], off nt
	global_load_dword v147, v[10:11], off nt
	v_lshl_add_u64 v[8:9], v[2:3], 2, v[4:5]
	v_add_u32_e32 v2, 0xfea03000, v12
	v_lshl_add_u64 v[10:11], v[2:3], 2, v[4:5]
	v_add_u32_e32 v2, 0xfea04000, v12
	global_load_dword v148, v[8:9], off nt
	global_load_dword v149, v[10:11], off nt
	v_lshl_add_u64 v[8:9], v[2:3], 2, v[4:5]
	v_add_u32_e32 v2, 0xfea05000, v12
	v_lshl_add_u64 v[10:11], v[2:3], 2, v[4:5]
	v_add_u32_e32 v2, 0xfea06000, v12
	global_load_dword v150, v[8:9], off nt
	global_load_dword v151, v[10:11], off nt
	v_lshl_add_u64 v[8:9], v[2:3], 2, v[4:5]
	v_add_u32_e32 v2, 0xfea07000, v12
	v_lshl_add_u64 v[10:11], v[2:3], 2, v[4:5]
	global_load_dword v152, v[8:9], off nt
	s_nop 0
	global_load_dword v153, v[10:11], off nt
	s_add_i32 s7, s7, 0x8000
	v_add_u32_e32 v12, s7, v6
	v_add_u32_e32 v2, 0xfea00000, v12
	v_lshl_add_u64 v[8:9], v[2:3], 2, v[4:5]
	v_add_u32_e32 v2, 0xfea01000, v12
	v_lshl_add_u64 v[10:11], v[2:3], 2, v[4:5]
	v_add_u32_e32 v2, 0xfea02000, v12
	global_load_dword v154, v[8:9], off nt
	global_load_dword v155, v[10:11], off nt
	v_lshl_add_u64 v[8:9], v[2:3], 2, v[4:5]
	v_add_u32_e32 v2, 0xfea03000, v12
	v_lshl_add_u64 v[10:11], v[2:3], 2, v[4:5]
	v_add_u32_e32 v2, 0xfea04000, v12
	global_load_dword v156, v[8:9], off nt
	global_load_dword v157, v[10:11], off nt
	v_lshl_add_u64 v[8:9], v[2:3], 2, v[4:5]
	v_add_u32_e32 v2, 0xfea05000, v12
	v_lshl_add_u64 v[10:11], v[2:3], 2, v[4:5]
	v_add_u32_e32 v2, 0xfea06000, v12
	global_load_dword v158, v[8:9], off nt
	global_load_dword v159, v[10:11], off nt
	v_lshl_add_u64 v[8:9], v[2:3], 2, v[4:5]
	v_add_u32_e32 v2, 0xfea07000, v12
	v_lshl_add_u64 v[10:11], v[2:3], 2, v[4:5]
	global_load_dword v160, v[8:9], off nt
	s_nop 0
	global_load_dword v161, v[10:11], off nt
	s_add_i32 s7, s7, 0x8000
	v_add_u32_e32 v12, s7, v6
	v_add_u32_e32 v2, 0xfea00000, v12
	v_lshl_add_u64 v[8:9], v[2:3], 2, v[4:5]
	v_add_u32_e32 v2, 0xfea01000, v12
	v_lshl_add_u64 v[10:11], v[2:3], 2, v[4:5]
	v_add_u32_e32 v2, 0xfea02000, v12
	global_load_dword v162, v[8:9], off nt
	global_load_dword v163, v[10:11], off nt
	v_lshl_add_u64 v[8:9], v[2:3], 2, v[4:5]
	v_add_u32_e32 v2, 0xfea03000, v12
	v_lshl_add_u64 v[10:11], v[2:3], 2, v[4:5]
	v_add_u32_e32 v2, 0xfea04000, v12
	global_load_dword v164, v[8:9], off nt
	global_load_dword v165, v[10:11], off nt
	v_lshl_add_u64 v[8:9], v[2:3], 2, v[4:5]
	v_add_u32_e32 v2, 0xfea05000, v12
	v_lshl_add_u64 v[10:11], v[2:3], 2, v[4:5]
	v_add_u32_e32 v2, 0xfea06000, v12
	global_load_dword v166, v[8:9], off nt
	global_load_dword v167, v[10:11], off nt
	v_lshl_add_u64 v[8:9], v[2:3], 2, v[4:5]
	v_add_u32_e32 v2, 0xfea07000, v12
	v_lshl_add_u64 v[10:11], v[2:3], 2, v[4:5]
	global_load_dword v168, v[8:9], off nt
	s_nop 0
	global_load_dword v169, v[10:11], off nt
	s_add_i32 s7, s7, 0x8000
	v_add_u32_e32 v9, 0x400, v7
	s_waitcnt vmcnt(30)
; #define LAS __attribute__((address_space(3)))
; #define LDS_WAIT() asm volatile("s_waitcnt lgkmcnt(0)" ::: "memory")
; __device__ __forceinline__ unsigned pk2(float lo, float hi) { return pg8::cvt_pk_bf16(lo, hi); }
; __device__ __forceinline__ void conv_item(const float* W, int K, int N, bf16_t* WT, int kb, int n0, int dst_row0, LAS float* scr, int lane) {
;     ...
;     for (int i = 0; i < 32; ++i) { const int kk = 2 * i + (lane >> 5); scr[kk * 33 + (lane & 31)] = __builtin_nontemporal_load(W + (size_t)(k0 + kk) * N + n0 + (lane & 31)); }
;     LDS_WAIT(); asm volatile("" ::: "memory");
;     const int c = lane & 7;
; #pragma unroll
;     for (int j = 0; j < 4; ++j) { const int n = (lane >> 3) + 8 * j; const LAS float* s = scr + (8 * c) * 33 + n;
;         u32x4 o; o.x = pk2(s[0 * 33], s[1 * 33]); o.y = pk2(s[2 * 33], s[3 * 33]); o.z = pk2(s[4 * 33], s[5 * 33]); o.w = pk2(s[6 * 33], s[7 * 33]);
;         *(u32x4*)(WT + (size_t)(dst_row0 + n) * K + k0 + 8 * c) = o; }
;     LDS_WAIT(); asm volatile("" ::: "memory");
	ds_write2_b32 v7, v138, v139 offset1:66
	s_waitcnt vmcnt(28)
	ds_write2_b32 v7, v140, v141 offset0:132 offset1:198
	v_add_u32_e32 v7, 0x840, v7
	s_waitcnt vmcnt(26)
	ds_write2_b32 v9, v142, v143 offset0:8 offset1:74
	s_waitcnt vmcnt(24)
	ds_write2_b32 v9, v144, v145 offset0:140 offset1:206
	v_add_u32_e32 v9, 0x400, v7
	s_waitcnt vmcnt(22)
	ds_write2_b32 v7, v146, v147 offset1:66
	s_waitcnt vmcnt(20)
	ds_write2_b32 v7, v148, v149 offset0:132 offset1:198
	v_add_u32_e32 v7, 0x840, v7
	s_waitcnt vmcnt(18)
	ds_write2_b32 v9, v150, v151 offset0:8 offset1:74
	s_waitcnt vmcnt(16)
	ds_write2_b32 v9, v152, v153 offset0:140 offset1:206
	v_add_u32_e32 v9, 0x400, v7
	s_waitcnt vmcnt(14)
	ds_write2_b32 v7, v154, v155 offset1:66
	s_waitcnt vmcnt(12)
	ds_write2_b32 v7, v156, v157 offset0:132 offset1:198
	v_add_u32_e32 v7, 0x840, v7
	s_waitcnt vmcnt(10)
	ds_write2_b32 v9, v158, v159 offset0:8 offset1:74
	s_waitcnt vmcnt(8)
	ds_write2_b32 v9, v160, v161 offset0:140 offset1:206
	v_add_u32_e32 v9, 0x400, v7
	s_waitcnt vmcnt(6)
	ds_write2_b32 v7, v162, v163 offset1:66
	s_waitcnt vmcnt(4)
	ds_write2_b32 v7, v164, v165 offset0:132 offset1:198
	v_add_u32_e32 v7, 0x840, v7
	s_waitcnt vmcnt(2)
	ds_write2_b32 v9, v166, v167 offset0:8 offset1:74
	s_waitcnt vmcnt(0)
	ds_write2_b32 v9, v168, v169 offset0:140 offset1:206
	s_waitcnt lgkmcnt(0)
	ds_read2_b32 v[170:171], v46 offset1:33
	ds_read2_b32 v[172:173], v46 offset0:66 offset1:99
	ds_read2_b32 v[174:175], v46 offset0:132 offset1:165
	ds_read2_b32 v[176:177], v46 offset0:198 offset1:231
	ds_read2_b32 v[178:179], v46 offset0:8 offset1:41
	ds_read2_b32 v[180:181], v46 offset0:74 offset1:107
	ds_read2_b32 v[182:183], v46 offset0:140 offset1:173
	ds_read2_b32 v[192:193], v46 offset0:206 offset1:239
	ds_read2_b32 v[194:195], v46 offset0:16 offset1:49
	ds_read2_b32 v[196:197], v46 offset0:82 offset1:115
	ds_read2_b32 v[198:199], v46 offset0:148 offset1:181
	ds_read2_b32 v[200:201], v46 offset0:214 offset1:247
	ds_read2_b32 v[202:203], v46 offset0:24 offset1:57
	ds_read2_b32 v[204:205], v46 offset0:90 offset1:123
	ds_read2_b32 v[206:207], v46 offset0:156 offset1:189
	ds_read2_b32 v[208:209], v46 offset0:222 offset1:255
	s_and_b32 s7, s10, 0x7fc0
	v_or_b32_e32 v2, s6, v1
	s_waitcnt lgkmcnt(15)
	v_cvt_pk_bf16_f32 v4, v170, v171
	s_add_i32 s44, s7, 0xffffd400
	v_mul_u32_u24_e32 v2, 0x1600, v2
	s_waitcnt lgkmcnt(14)
	v_cvt_pk_bf16_f32 v5, v172, v173
	v_lshl_add_u64 v[10:11], s[44:45], 1, v[30:31]
	v_lshlrev_b32_e32 v2, 1, v2
	s_waitcnt lgkmcnt(13)
	v_cvt_pk_bf16_f32 v6, v174, v175
	s_waitcnt lgkmcnt(12)
	v_cvt_pk_bf16_f32 v7, v176, v177
	v_lshl_add_u64 v[12:13], v[10:11], 0, v[2:3]
	v_or_b32_e32 v2, s6, v47
	global_store_dwordx4 v[12:13], v[4:7], off
	v_mul_u32_u24_e32 v2, 0x1600, v2
	v_lshlrev_b32_e32 v2, 1, v2
	s_waitcnt lgkmcnt(11)
	v_cvt_pk_bf16_f32 v4, v178, v179
	s_waitcnt lgkmcnt(10)
	v_cvt_pk_bf16_f32 v5, v180, v181
	s_waitcnt lgkmcnt(9)
	v_cvt_pk_bf16_f32 v6, v182, v183
	s_waitcnt lgkmcnt(8)
	v_cvt_pk_bf16_f32 v7, v192, v193
	v_lshl_add_u64 v[12:13], v[10:11], 0, v[2:3]
	v_or_b32_e32 v2, s6, v48
	global_store_dwordx4 v[12:13], v[4:7], off
	v_mul_u32_u24_e32 v2, 0x1600, v2
	v_lshlrev_b32_e32 v2, 1, v2
	s_waitcnt lgkmcnt(7)
	v_cvt_pk_bf16_f32 v4, v194, v195
	s_waitcnt lgkmcnt(6)
	v_cvt_pk_bf16_f32 v5, v196, v197
	s_waitcnt lgkmcnt(5)
	v_cvt_pk_bf16_f32 v6, v198, v199
	s_waitcnt lgkmcnt(4)
	v_cvt_pk_bf16_f32 v7, v200, v201
	v_lshl_add_u64 v[12:13], v[10:11], 0, v[2:3]
	global_store_dwordx4 v[12:13], v[4:7], off
	v_or_b32_e32 v2, s6, v49
	v_mul_u32_u24_e32 v2, 0x1600, v2
	s_waitcnt lgkmcnt(3)
	v_cvt_pk_bf16_f32 v4, v202, v203
	s_waitcnt lgkmcnt(2)
	v_cvt_pk_bf16_f32 v5, v204, v205
	s_waitcnt lgkmcnt(1)
	v_cvt_pk_bf16_f32 v6, v206, v207
	v_lshlrev_b32_e32 v2, 1, v2
	s_waitcnt lgkmcnt(0)
	v_cvt_pk_bf16_f32 v7, v208, v209
	v_lshl_add_u64 v[8:9], v[10:11], 0, v[2:3]
	global_store_dwordx4 v[8:9], v[4:7], off
	s_waitcnt lgkmcnt(0)

; #define LAS __attribute__((address_space(3)))
; #define LDS_WAIT() asm volatile("s_waitcnt lgkmcnt(0)" ::: "memory")
; __device__ __forceinline__ void conv_item(const float* W, int K, int N, bf16_t* WT, int kb, int n0, int dst_row0, LAS float* scr, int lane) {
;     const int k0 = 64 * kb;
; #pragma unroll 8
;     for (int i = 0; i < 32; ++i) { const int kk = 2 * i + (lane >> 5); scr[kk * 33 + (lane & 31)] = __builtin_nontemporal_load(W + (size_t)(k0 + kk) * N + n0 + (lane & 31)); }
;     LDS_WAIT(); asm volatile("" ::: "memory");
.LBB0_398:
	v_lshl_add_u64 v[18:19], v[12:13], 0, s[8:9]
	v_add_co_u32_e32 v66, vcc, 0xb000, v18
	v_lshl_add_u64 v[16:17], v[14:15], 0, s[8:9]
	v_lshl_add_u64 v[42:43], v[10:11], 0, s[8:9]
	v_lshl_add_u64 v[44:45], v[8:9], 0, s[8:9]
	s_mov_b64 s[6:7], vcc
	v_lshl_add_u64 v[62:63], v[6:7], 0, s[8:9]
	v_lshl_add_u64 v[64:65], v[4:5], 0, s[8:9]
	global_load_dword v138, v[16:17], off nt
	s_nop 0
	global_load_dword v139, v[42:43], off nt
	s_nop 0
	global_load_dword v140, v[44:45], off nt
	s_nop 0
	global_load_dword v141, v[62:63], off nt
	global_load_dword v142, v[64:65], off nt
	v_add_co_u32_e32 v16, vcc, 0x16000, v18
	v_addc_co_u32_e64 v67, s[6:7], 0, v19, s[6:7]
	s_mov_b64 s[6:7], vcc
	v_add_co_u32_e32 v18, vcc, 0x21000, v18
	v_addc_co_u32_e64 v17, s[6:7], 0, v19, s[6:7]
	global_load_dword v143, v[66:67], off nt
	v_addc_co_u32_e32 v19, vcc, 0, v19, vcc
	global_load_dword v144, v[16:17], off nt
	s_nop 0
	global_load_dword v145, v[18:19], off nt
	s_add_u32 s8, s8, 0x58000
	s_addc_u32 s9, s9, 0
	v_lshl_add_u64 v[18:19], v[12:13], 0, s[8:9]
	v_add_co_u32_e32 v66, vcc, 0xb000, v18
	v_lshl_add_u64 v[16:17], v[14:15], 0, s[8:9]
	v_lshl_add_u64 v[42:43], v[10:11], 0, s[8:9]
	v_lshl_add_u64 v[44:45], v[8:9], 0, s[8:9]
	s_mov_b64 s[6:7], vcc
	v_lshl_add_u64 v[62:63], v[6:7], 0, s[8:9]
	v_lshl_add_u64 v[64:65], v[4:5], 0, s[8:9]
	global_load_dword v146, v[16:17], off nt
	s_nop 0
	global_load_dword v147, v[42:43], off nt
	s_nop 0
	global_load_dword v148, v[44:45], off nt
	s_nop 0
	global_load_dword v149, v[62:63], off nt
	global_load_dword v150, v[64:65], off nt
	v_add_co_u32_e32 v16, vcc, 0x16000, v18
	v_addc_co_u32_e64 v67, s[6:7], 0, v19, s[6:7]
	s_mov_b64 s[6:7], vcc
	v_add_co_u32_e32 v18, vcc, 0x21000, v18
	v_addc_co_u32_e64 v17, s[6:7], 0, v19, s[6:7]
	global_load_dword v151, v[66:67], off nt
	v_addc_co_u32_e32 v19, vcc, 0, v19, vcc
	global_load_dword v152, v[16:17], off nt
	s_nop 0
	global_load_dword v153, v[18:19], off nt
	s_add_u32 s8, s8, 0x58000
	s_addc_u32 s9, s9, 0
	v_lshl_add_u64 v[18:19], v[12:13], 0, s[8:9]
	v_add_co_u32_e32 v66, vcc, 0xb000, v18
	v_lshl_add_u64 v[16:17], v[14:15], 0, s[8:9]
	v_lshl_add_u64 v[42:43], v[10:11], 0, s[8:9]
	v_lshl_add_u64 v[44:45], v[8:9], 0, s[8:9]
	s_mov_b64 s[6:7], vcc
	v_lshl_add_u64 v[62:63], v[6:7], 0, s[8:9]
	v_lshl_add_u64 v[64:65], v[4:5], 0, s[8:9]
	global_load_dword v154, v[16:17], off nt
	s_nop 0
	global_load_dword v155, v[42:43], off nt
	s_nop 0
	global_load_dword v156, v[44:45], off nt
	s_nop 0
	global_load_dword v157, v[62:63], off nt
	global_load_dword v158, v[64:65], off nt
	v_add_co_u32_e32 v16, vcc, 0x16000, v18
	v_addc_co_u32_e64 v67, s[6:7], 0, v19, s[6:7]
	s_mov_b64 s[6:7], vcc
	v_add_co_u32_e32 v18, vcc, 0x21000, v18
	v_addc_co_u32_e64 v17, s[6:7], 0, v19, s[6:7]
	global_load_dword v159, v[66:67], off nt
	v_addc_co_u32_e32 v19, vcc, 0, v19, vcc
	global_load_dword v160, v[16:17], off nt
	s_nop 0
	global_load_dword v161, v[18:19], off nt
	s_add_u32 s8, s8, 0x58000
	s_addc_u32 s9, s9, 0
	v_lshl_add_u64 v[18:19], v[12:13], 0, s[8:9]
	v_add_co_u32_e32 v66, vcc, 0xb000, v18
	v_lshl_add_u64 v[16:17], v[14:15], 0, s[8:9]
	v_lshl_add_u64 v[42:43], v[10:11], 0, s[8:9]
	v_lshl_add_u64 v[44:45], v[8:9], 0, s[8:9]
	s_mov_b64 s[6:7], vcc
	v_lshl_add_u64 v[62:63], v[6:7], 0, s[8:9]
	v_lshl_add_u64 v[64:65], v[4:5], 0, s[8:9]
	global_load_dword v162, v[16:17], off nt
	s_nop 0
	global_load_dword v163, v[42:43], off nt
	s_nop 0
	global_load_dword v164, v[44:45], off nt
	s_nop 0
	global_load_dword v165, v[62:63], off nt
	global_load_dword v166, v[64:65], off nt
	v_add_co_u32_e32 v16, vcc, 0x16000, v18
	v_addc_co_u32_e64 v67, s[6:7], 0, v19, s[6:7]
	s_mov_b64 s[6:7], vcc
	v_add_co_u32_e32 v18, vcc, 0x21000, v18
	v_addc_co_u32_e64 v17, s[6:7], 0, v19, s[6:7]
	global_load_dword v167, v[66:67], off nt
	v_addc_co_u32_e32 v19, vcc, 0, v19, vcc
	global_load_dword v168, v[16:17], off nt
	s_nop 0
	global_load_dword v169, v[18:19], off nt
	s_add_u32 s8, s8, 0x58000
	s_addc_u32 s9, s9, 0
	v_add_u32_e32 v18, 0x400, v2
	s_waitcnt vmcnt(29)
; #define LAS __attribute__((address_space(3)))
; #define LDS_WAIT() asm volatile("s_waitcnt lgkmcnt(0)" ::: "memory")
; __device__ __forceinline__ unsigned pk2(float lo, float hi) { return pg8::cvt_pk_bf16(lo, hi); }
; __device__ __forceinline__ void conv_item(const float* W, int K, int N, bf16_t* WT, int kb, int n0, int dst_row0, LAS float* scr, int lane) {
;     ...
;     for (int i = 0; i < 32; ++i) { const int kk = 2 * i + (lane >> 5); scr[kk * 33 + (lane & 31)] = __builtin_nontemporal_load(W + (size_t)(k0 + kk) * N + n0 + (lane & 31)); }
;     LDS_WAIT(); asm volatile("" ::: "memory");
;     const int c = lane & 7;
; #pragma unroll
;     for (int j = 0; j < 4; ++j) { const int n = (lane >> 3) + 8 * j; const LAS float* s = scr + (8 * c) * 33 + n;
;         u32x4 o; o.x = pk2(s[0 * 33], s[1 * 33]); o.y = pk2(s[2 * 33], s[3 * 33]); o.z = pk2(s[4 * 33], s[5 * 33]); o.w = pk2(s[6 * 33], s[7 * 33]);
;         *(u32x4*)(WT + (size_t)(dst_row0 + n) * K + k0 + 8 * c) = o; }
;     LDS_WAIT(); asm volatile("" ::: "memory");
	ds_write2_b32 v18, v139, v140 offset0:8 offset1:74
	s_waitcnt vmcnt(27)
	ds_write2_b32 v18, v141, v142 offset0:140 offset1:206
	s_waitcnt vmcnt(26)
	ds_write2_b32 v2, v138, v143 offset1:66
	s_waitcnt vmcnt(24)
	ds_write2_b32 v2, v144, v145 offset0:132 offset1:198
	v_add_u32_e32 v2, 0x840, v2
	v_add_u32_e32 v18, 0x400, v2
	s_waitcnt vmcnt(21)
	ds_write2_b32 v18, v147, v148 offset0:8 offset1:74
	s_waitcnt vmcnt(19)
	ds_write2_b32 v18, v149, v150 offset0:140 offset1:206
	s_waitcnt vmcnt(18)
	ds_write2_b32 v2, v146, v151 offset1:66
	s_waitcnt vmcnt(16)
	ds_write2_b32 v2, v152, v153 offset0:132 offset1:198
	v_add_u32_e32 v2, 0x840, v2
	v_add_u32_e32 v18, 0x400, v2
	s_waitcnt vmcnt(13)
	ds_write2_b32 v18, v155, v156 offset0:8 offset1:74
	s_waitcnt vmcnt(11)
	ds_write2_b32 v18, v157, v158 offset0:140 offset1:206
	s_waitcnt vmcnt(10)
	ds_write2_b32 v2, v154, v159 offset1:66
	s_waitcnt vmcnt(8)
	ds_write2_b32 v2, v160, v161 offset0:132 offset1:198
	v_add_u32_e32 v2, 0x840, v2
	v_add_u32_e32 v18, 0x400, v2
	s_waitcnt vmcnt(5)
	ds_write2_b32 v18, v163, v164 offset0:8 offset1:74
	s_waitcnt vmcnt(3)
	ds_write2_b32 v18, v165, v166 offset0:140 offset1:206
	s_waitcnt vmcnt(2)
	ds_write2_b32 v2, v162, v167 offset1:66
	s_waitcnt vmcnt(0)
	ds_write2_b32 v2, v168, v169 offset0:132 offset1:198
	v_add_u32_e32 v2, 0x840, v2
	s_lshl_b32 s6, s11, 6
	s_waitcnt lgkmcnt(0)
	ds_read2_b32 v[170:171], v46 offset1:33
	ds_read2_b32 v[172:173], v46 offset0:66 offset1:99
	ds_read2_b32 v[174:175], v46 offset0:132 offset1:165
	ds_read2_b32 v[176:177], v46 offset0:198 offset1:231
	ds_read2_b32 v[178:179], v46 offset0:8 offset1:41
	ds_read2_b32 v[180:181], v46 offset0:74 offset1:107
	ds_read2_b32 v[182:183], v46 offset0:140 offset1:173
	ds_read2_b32 v[192:193], v46 offset0:206 offset1:239
	ds_read2_b32 v[194:195], v46 offset0:16 offset1:49
	ds_read2_b32 v[196:197], v46 offset0:82 offset1:115
	ds_read2_b32 v[198:199], v46 offset0:148 offset1:181
	ds_read2_b32 v[200:201], v46 offset0:214 offset1:247
	ds_read2_b32 v[202:203], v46 offset0:24 offset1:57
	ds_read2_b32 v[204:205], v46 offset0:90 offset1:123
	ds_read2_b32 v[206:207], v46 offset0:156 offset1:189
	ds_read2_b32 v[208:209], v46 offset0:222 offset1:255
	s_and_b32 s7, s13, 0x60
	s_and_b32 s6, s6, 0x3f00
	s_or_b32 s6, s6, s7
	s_and_b32 s8, 0xffff, s14
	s_bitset1_b32 s6, 7
	s_waitcnt lgkmcnt(15)
	v_cvt_pk_bf16_f32 v4, v170, v171
	s_lshl_b32 s44, s8, 1
	v_or_b32_e32 v2, s6, v1
	s_waitcnt lgkmcnt(14)
	v_cvt_pk_bf16_f32 v5, v172, v173
	v_lshl_add_u64 v[10:11], v[32:33], 0, s[44:45]
	v_lshlrev_b32_e32 v2, 12, v2
	s_waitcnt lgkmcnt(13)
	v_cvt_pk_bf16_f32 v6, v174, v175
	s_waitcnt lgkmcnt(12)
	v_cvt_pk_bf16_f32 v7, v176, v177
	v_lshl_add_u64 v[12:13], v[10:11], 0, v[2:3]
	global_store_dwordx4 v[12:13], v[4:7], off
	v_or_b32_e32 v2, s6, v47
	v_lshlrev_b32_e32 v2, 12, v2
	s_waitcnt lgkmcnt(11)
	v_cvt_pk_bf16_f32 v4, v178, v179
	s_waitcnt lgkmcnt(10)
	v_cvt_pk_bf16_f32 v5, v180, v181
	s_waitcnt lgkmcnt(9)
	v_cvt_pk_bf16_f32 v6, v182, v183
	s_waitcnt lgkmcnt(8)
	v_cvt_pk_bf16_f32 v7, v192, v193
	v_lshl_add_u64 v[12:13], v[10:11], 0, v[2:3]
	global_store_dwordx4 v[12:13], v[4:7], off
	v_or_b32_e32 v2, s6, v48
	v_lshlrev_b32_e32 v2, 12, v2
	s_waitcnt lgkmcnt(7)
	v_cvt_pk_bf16_f32 v4, v194, v195
	s_waitcnt lgkmcnt(6)
	v_cvt_pk_bf16_f32 v5, v196, v197
	s_waitcnt lgkmcnt(5)
	v_cvt_pk_bf16_f32 v6, v198, v199
	s_waitcnt lgkmcnt(4)
	v_cvt_pk_bf16_f32 v7, v200, v201
	v_lshl_add_u64 v[12:13], v[10:11], 0, v[2:3]
	global_store_dwordx4 v[12:13], v[4:7], off
	v_or_b32_e32 v2, s6, v49
	v_lshlrev_b32_e32 v2, 12, v2
	s_waitcnt lgkmcnt(3)
	v_cvt_pk_bf16_f32 v4, v202, v203
	s_waitcnt lgkmcnt(2)
	v_cvt_pk_bf16_f32 v5, v204, v205
	s_waitcnt lgkmcnt(1)
	v_cvt_pk_bf16_f32 v6, v206, v207
	s_waitcnt lgkmcnt(0)
	v_cvt_pk_bf16_f32 v7, v208, v209
	v_lshl_add_u64 v[8:9], v[10:11], 0, v[2:3]
	global_store_dwordx4 v[8:9], v[4:7], off
	s_waitcnt lgkmcnt(0)

; __device__ __forceinline__ void conv_item(const float* W, int K, int N, bf16_t* WT, int kb, int n0, int dst_row0, LAS float* scr, int lane) {
;     ...
; #pragma unroll 8
;     for (int i = 0; i < 32; ++i) { const int kk = 2 * i + (lane >> 5); scr[kk * 33 + (lane & 31)] = __builtin_nontemporal_load(W + (size_t)(k0 + kk) * N + n0 + (lane & 31)); }
.LBB0_403:
	v_lshl_add_u64 v[18:19], v[12:13], 0, s[8:9]
	v_add_co_u32_e32 v66, vcc, 0xb000, v18
	v_lshl_add_u64 v[16:17], v[14:15], 0, s[8:9]
	v_lshl_add_u64 v[42:43], v[10:11], 0, s[8:9]
	v_lshl_add_u64 v[44:45], v[8:9], 0, s[8:9]
	s_mov_b64 s[6:7], vcc
	v_lshl_add_u64 v[62:63], v[6:7], 0, s[8:9]
	v_lshl_add_u64 v[64:65], v[4:5], 0, s[8:9]
	global_load_dword v138, v[16:17], off nt
	s_nop 0
	global_load_dword v139, v[42:43], off nt
	s_nop 0
	global_load_dword v140, v[44:45], off nt
	s_nop 0
	global_load_dword v141, v[62:63], off nt
	global_load_dword v142, v[64:65], off nt
	v_add_co_u32_e32 v16, vcc, 0x16000, v18
	v_addc_co_u32_e64 v67, s[6:7], 0, v19, s[6:7]
	s_mov_b64 s[6:7], vcc
	v_add_co_u32_e32 v18, vcc, 0x21000, v18
	v_addc_co_u32_e64 v17, s[6:7], 0, v19, s[6:7]
	global_load_dword v143, v[66:67], off nt
	v_addc_co_u32_e32 v19, vcc, 0, v19, vcc
	global_load_dword v144, v[16:17], off nt
	s_nop 0
	global_load_dword v145, v[18:19], off nt
	s_add_u32 s8, s8, 0x58000
	s_addc_u32 s9, s9, 0
	v_lshl_add_u64 v[18:19], v[12:13], 0, s[8:9]
	v_add_co_u32_e32 v66, vcc, 0xb000, v18
	v_lshl_add_u64 v[16:17], v[14:15], 0, s[8:9]
	v_lshl_add_u64 v[42:43], v[10:11], 0, s[8:9]
	v_lshl_add_u64 v[44:45], v[8:9], 0, s[8:9]
	s_mov_b64 s[6:7], vcc
	v_lshl_add_u64 v[62:63], v[6:7], 0, s[8:9]
	v_lshl_add_u64 v[64:65], v[4:5], 0, s[8:9]
	global_load_dword v146, v[16:17], off nt
	s_nop 0
	global_load_dword v147, v[42:43], off nt
	s_nop 0
	global_load_dword v148, v[44:45], off nt
	s_nop 0
	global_load_dword v149, v[62:63], off nt
	global_load_dword v150, v[64:65], off nt
	v_add_co_u32_e32 v16, vcc, 0x16000, v18
	v_addc_co_u32_e64 v67, s[6:7], 0, v19, s[6:7]
	s_mov_b64 s[6:7], vcc
	v_add_co_u32_e32 v18, vcc, 0x21000, v18
	v_addc_co_u32_e64 v17, s[6:7], 0, v19, s[6:7]
	global_load_dword v151, v[66:67], off nt
	v_addc_co_u32_e32 v19, vcc, 0, v19, vcc
	global_load_dword v152, v[16:17], off nt
	s_nop 0
	global_load_dword v153, v[18:19], off nt
	s_add_u32 s8, s8, 0x58000
	s_addc_u32 s9, s9, 0
	v_lshl_add_u64 v[18:19], v[12:13], 0, s[8:9]
	v_add_co_u32_e32 v66, vcc, 0xb000, v18
	v_lshl_add_u64 v[16:17], v[14:15], 0, s[8:9]
	v_lshl_add_u64 v[42:43], v[10:11], 0, s[8:9]
	v_lshl_add_u64 v[44:45], v[8:9], 0, s[8:9]
	s_mov_b64 s[6:7], vcc
	v_lshl_add_u64 v[62:63], v[6:7], 0, s[8:9]
	v_lshl_add_u64 v[64:65], v[4:5], 0, s[8:9]
	global_load_dword v154, v[16:17], off nt
	s_nop 0
	global_load_dword v155, v[42:43], off nt
	s_nop 0
	global_load_dword v156, v[44:45], off nt
	s_nop 0
	global_load_dword v157, v[62:63], off nt
	global_load_dword v158, v[64:65], off nt
	v_add_co_u32_e32 v16, vcc, 0x16000, v18
	v_addc_co_u32_e64 v67, s[6:7], 0, v19, s[6:7]
	s_mov_b64 s[6:7], vcc
	v_add_co_u32_e32 v18, vcc, 0x21000, v18
	v_addc_co_u32_e64 v17, s[6:7], 0, v19, s[6:7]
	global_load_dword v159, v[66:67], off nt
	v_addc_co_u32_e32 v19, vcc, 0, v19, vcc
	global_load_dword v160, v[16:17], off nt
	s_nop 0
	global_load_dword v161, v[18:19], off nt
	s_add_u32 s8, s8, 0x58000
	s_addc_u32 s9, s9, 0
	v_lshl_add_u64 v[18:19], v[12:13], 0, s[8:9]
	v_add_co_u32_e32 v66, vcc, 0xb000, v18
	v_lshl_add_u64 v[16:17], v[14:15], 0, s[8:9]
	v_lshl_add_u64 v[42:43], v[10:11], 0, s[8:9]
	v_lshl_add_u64 v[44:45], v[8:9], 0, s[8:9]
	s_mov_b64 s[6:7], vcc
	v_lshl_add_u64 v[62:63], v[6:7], 0, s[8:9]
	v_lshl_add_u64 v[64:65], v[4:5], 0, s[8:9]
	global_load_dword v162, v[16:17], off nt
	s_nop 0
	global_load_dword v163, v[42:43], off nt
	s_nop 0
	global_load_dword v164, v[44:45], off nt
	s_nop 0
	global_load_dword v165, v[62:63], off nt
	global_load_dword v166, v[64:65], off nt
	v_add_co_u32_e32 v16, vcc, 0x16000, v18
	v_addc_co_u32_e64 v67, s[6:7], 0, v19, s[6:7]
	s_mov_b64 s[6:7], vcc
	v_add_co_u32_e32 v18, vcc, 0x21000, v18
	v_addc_co_u32_e64 v17, s[6:7], 0, v19, s[6:7]
	global_load_dword v167, v[66:67], off nt
	v_addc_co_u32_e32 v19, vcc, 0, v19, vcc
	global_load_dword v168, v[16:17], off nt
	s_nop 0
	global_load_dword v169, v[18:19], off nt
	s_add_u32 s8, s8, 0x58000
	s_addc_u32 s9, s9, 0
	v_add_u32_e32 v18, 0x400, v2
	s_waitcnt vmcnt(29)
; #define LAS __attribute__((address_space(3)))
; #define LDS_WAIT() asm volatile("s_waitcnt lgkmcnt(0)" ::: "memory")
; __device__ __forceinline__ unsigned pk2(float lo, float hi) { return pg8::cvt_pk_bf16(lo, hi); }
; __device__ __forceinline__ void conv_item(const float* W, int K, int N, bf16_t* WT, int kb, int n0, int dst_row0, LAS float* scr, int lane) {
;     ...
;     for (int i = 0; i < 32; ++i) { const int kk = 2 * i + (lane >> 5); scr[kk * 33 + (lane & 31)] = __builtin_nontemporal_load(W + (size_t)(k0 + kk) * N + n0 + (lane & 31)); }
;     LDS_WAIT(); asm volatile("" ::: "memory");
;     const int c = lane & 7;
; #pragma unroll
;     for (int j = 0; j < 4; ++j) { const int n = (lane >> 3) + 8 * j; const LAS float* s = scr + (8 * c) * 33 + n;
;         u32x4 o; o.x = pk2(s[0 * 33], s[1 * 33]); o.y = pk2(s[2 * 33], s[3 * 33]); o.z = pk2(s[4 * 33], s[5 * 33]); o.w = pk2(s[6 * 33], s[7 * 33]);
;         *(u32x4*)(WT + (size_t)(dst_row0 + n) * K + k0 + 8 * c) = o; }
;     LDS_WAIT(); asm volatile("" ::: "memory");
	ds_write2_b32 v18, v139, v140 offset0:8 offset1:74
	s_waitcnt vmcnt(27)
	ds_write2_b32 v18, v141, v142 offset0:140 offset1:206
	s_waitcnt vmcnt(26)
	ds_write2_b32 v2, v138, v143 offset1:66
	s_waitcnt vmcnt(24)
	ds_write2_b32 v2, v144, v145 offset0:132 offset1:198
	v_add_u32_e32 v2, 0x840, v2
	v_add_u32_e32 v18, 0x400, v2
	s_waitcnt vmcnt(21)
	ds_write2_b32 v18, v147, v148 offset0:8 offset1:74
	s_waitcnt vmcnt(19)
	ds_write2_b32 v18, v149, v150 offset0:140 offset1:206
	s_waitcnt vmcnt(18)
	ds_write2_b32 v2, v146, v151 offset1:66
	s_waitcnt vmcnt(16)
	ds_write2_b32 v2, v152, v153 offset0:132 offset1:198
	v_add_u32_e32 v2, 0x840, v2
	v_add_u32_e32 v18, 0x400, v2
	s_waitcnt vmcnt(13)
	ds_write2_b32 v18, v155, v156 offset0:8 offset1:74
	s_waitcnt vmcnt(11)
	ds_write2_b32 v18, v157, v158 offset0:140 offset1:206
	s_waitcnt vmcnt(10)
	ds_write2_b32 v2, v154, v159 offset1:66
	s_waitcnt vmcnt(8)
	ds_write2_b32 v2, v160, v161 offset0:132 offset1:198
	v_add_u32_e32 v2, 0x840, v2
	v_add_u32_e32 v18, 0x400, v2
	s_waitcnt vmcnt(5)
	ds_write2_b32 v18, v163, v164 offset0:8 offset1:74
	s_waitcnt vmcnt(3)
	ds_write2_b32 v18, v165, v166 offset0:140 offset1:206
	s_waitcnt vmcnt(2)
	ds_write2_b32 v2, v162, v167 offset1:66
	s_waitcnt vmcnt(0)
	ds_write2_b32 v2, v168, v169 offset0:132 offset1:198
	v_add_u32_e32 v2, 0x840, v2
	s_waitcnt lgkmcnt(0)
	ds_read2_b32 v[170:171], v46 offset1:33
	ds_read2_b32 v[172:173], v46 offset0:66 offset1:99
	ds_read2_b32 v[174:175], v46 offset0:132 offset1:165
	ds_read2_b32 v[176:177], v46 offset0:198 offset1:231
	ds_read2_b32 v[178:179], v46 offset0:8 offset1:41
	ds_read2_b32 v[180:181], v46 offset0:74 offset1:107
	ds_read2_b32 v[182:183], v46 offset0:140 offset1:173
	ds_read2_b32 v[192:193], v46 offset0:206 offset1:239
	ds_read2_b32 v[194:195], v46 offset0:16 offset1:49
	ds_read2_b32 v[196:197], v46 offset0:82 offset1:115
	ds_read2_b32 v[198:199], v46 offset0:148 offset1:181
	ds_read2_b32 v[200:201], v46 offset0:214 offset1:247
	ds_read2_b32 v[202:203], v46 offset0:24 offset1:57
	ds_read2_b32 v[204:205], v46 offset0:90 offset1:123
	ds_read2_b32 v[206:207], v46 offset0:156 offset1:189
	ds_read2_b32 v[208:209], v46 offset0:222 offset1:255
	s_lshl_b32 s6, s10, 6
	s_and_b32 s7, s11, 0x60
	s_and_b32 s6, s6, 0x3f00
	s_and_b32 s8, 0xffff, s13
	s_or_b32 s6, s6, s7
	s_waitcnt lgkmcnt(15)
	v_cvt_pk_bf16_f32 v4, v170, v171
	s_lshl_b32 s44, s8, 1
	v_or_b32_e32 v2, s6, v1
	s_waitcnt lgkmcnt(14)
	v_cvt_pk_bf16_f32 v5, v172, v173
	v_lshl_add_u64 v[10:11], v[32:33], 0, s[44:45]
	v_lshlrev_b32_e32 v2, 12, v2
	s_waitcnt lgkmcnt(13)
	v_cvt_pk_bf16_f32 v6, v174, v175
	s_waitcnt lgkmcnt(12)
	v_cvt_pk_bf16_f32 v7, v176, v177
	v_lshl_add_u64 v[12:13], v[10:11], 0, v[2:3]
	global_store_dwordx4 v[12:13], v[4:7], off
	v_or_b32_e32 v2, s6, v47
	v_lshlrev_b32_e32 v2, 12, v2
	s_waitcnt lgkmcnt(11)
	v_cvt_pk_bf16_f32 v4, v178, v179
	s_waitcnt lgkmcnt(10)
	v_cvt_pk_bf16_f32 v5, v180, v181
	s_waitcnt lgkmcnt(9)
	v_cvt_pk_bf16_f32 v6, v182, v183
	s_waitcnt lgkmcnt(8)
	v_cvt_pk_bf16_f32 v7, v192, v193
	v_lshl_add_u64 v[12:13], v[10:11], 0, v[2:3]
	global_store_dwordx4 v[12:13], v[4:7], off
	v_or_b32_e32 v2, s6, v48
	v_lshlrev_b32_e32 v2, 12, v2
	s_waitcnt lgkmcnt(7)
	v_cvt_pk_bf16_f32 v4, v194, v195
	s_waitcnt lgkmcnt(6)
	v_cvt_pk_bf16_f32 v5, v196, v197
	s_waitcnt lgkmcnt(5)
	v_cvt_pk_bf16_f32 v6, v198, v199
	s_waitcnt lgkmcnt(4)
	v_cvt_pk_bf16_f32 v7, v200, v201
	v_lshl_add_u64 v[12:13], v[10:11], 0, v[2:3]
	global_store_dwordx4 v[12:13], v[4:7], off
	v_or_b32_e32 v2, s6, v49
	v_lshlrev_b32_e32 v2, 12, v2
	s_waitcnt lgkmcnt(3)
	v_cvt_pk_bf16_f32 v4, v202, v203
	s_waitcnt lgkmcnt(2)
	v_cvt_pk_bf16_f32 v5, v204, v205
	s_waitcnt lgkmcnt(1)
	v_cvt_pk_bf16_f32 v6, v206, v207
	s_waitcnt lgkmcnt(0)
	v_cvt_pk_bf16_f32 v7, v208, v209
	v_lshl_add_u64 v[8:9], v[10:11], 0, v[2:3]
	global_store_dwordx4 v[8:9], v[4:7], off
	s_waitcnt lgkmcnt(0)
